# LDS-DMA staging loads in all GEMM loops use the saddr + 32-bit voffset form (removes one 64-bit VALU add per load from the load segments)
# speedup vs baseline: 1.0757x; 1.0757x over previous
.LBB0_112:
	s_add_u32 s10, s6, 0x3100000
	s_addc_u32 s11, s7, 0
	s_add_u32 s22, s6, 0x7100000
	s_addc_u32 s23, s7, 0
	v_and_b32_e32 v9, 48, v8
	v_lshlrev_b32_e32 v10, 6, v8
	s_movk_i32 s7, 0x3c0
	v_lshlrev_b32_e32 v8, 2, v8
	s_and_b32 s78, s19, 3
	s_lshl_b32 s6, s18, 13
	v_and_or_b32 v9, v10, s7, v9
	v_and_b32_e32 v8, 32, v8
	s_add_i32 m0, s67, 0x18000
	v_lshl_add_u64 v[6:7], v[6:7], 0, s[26:27]
	s_lshl_b32 s79, s18, 6
	v_bitop3_b32 v10, v9, s6, v8 bitop3:0xde
	s_lshl_b32 s80, s78, 5
	s_lshl_b32 s6, s78, 12
	s_waitcnt vmcnt(2)
	s_barrier
	global_load_lds_dwordx4 v[6:7], off
	v_lshl_add_u64 v[4:5], v[4:5], 0, s[26:27]
	s_add_i32 m0, s67, 0x1a000
	s_add_i32 s81, s67, 0x8000
	s_add_i32 s82, s67, 0xa000
	v_bitop3_b32 v142, v9, s6, v8 bitop3:0xde
	global_load_lds_dwordx4 v[4:5], off
	v_lshl_add_u64 v[0:1], v[0:1], 0, s[26:27]
	s_mov_b32 m0, s81
	s_add_u32 s6, s38, 0x40080
	global_load_lds_dwordx4 v[0:1], off
	v_lshl_add_u64 v[0:1], v[2:3], 0, s[26:27]
	s_mov_b32 m0, s82
	s_addc_u32 s7, s39, 0
	global_load_lds_dwordx4 v[0:1], off
	s_add_i32 m0, s67, 0x1c000
	s_nop 0
	global_load_lds_dwordx4 v96, s[6:7]
	s_add_i32 m0, s67, 0x1e000
	s_cmpk_lt_u32 s16, 0x100
	global_load_lds_dwordx4 v134, s[6:7]
	s_waitcnt vmcnt(6)
	s_cselect_b64 s[28:29], -1, 0
	s_ashr_i32 s83, s33, 31
	s_ashr_i32 s84, s2, 31
	s_mov_b32 s85, 0
	v_add_u32_e32 v143, 0, v10
	s_barrier
	s_branch .LBB0_115

.LBB0_122:
	s_cmp_eq_u32 s89, 12
	s_cselect_b32 s42, s20, s65
	s_cselect_b32 s43, s16, s86
	s_cselect_b32 s45, s31, s88
	s_cselect_b32 s44, s59, s87
	s_add_u32 s38, s42, 0x80
	s_addc_u32 s39, s43, 0
	s_add_u32 s74, s44, 0x80
	s_addc_u32 s75, s45, 0
	s_add_i32 s35, 0, 0x10000
	s_mov_b64 s[18:19], s[68:69]
	v_add_u32_e32 v140, s35, v142
	s_add_i32 s49, 0, 0x14000
	ds_read_b128 v[136:139], v140
	ds_read_b128 v[144:147], v140 offset:1024
	ds_read_b128 v[148:151], v140 offset:2048
	ds_read_b128 v[152:155], v140 offset:3072
	v_add_u32_e32 v140, s49, v142
	ds_read_b128 v[156:159], v140
	ds_read_b128 v[160:163], v140 offset:1024
	ds_read_b128 v[164:167], v140 offset:2048
	ds_read_b128 v[168:171], v140 offset:3072
	s_add_u32 s18, s18, 0x40000
	s_addc_u32 s19, s19, 0
	s_add_i32 m0, s67, 0xc000
	ds_read_b128 v[172:175], v143
	ds_read_b128 v[176:179], v143 offset:1024
	ds_read_b128 v[180:183], v143 offset:2048
	ds_read_b128 v[184:187], v143 offset:3072
	ds_read_b128 v[188:191], v143 offset:4096
	ds_read_b128 v[192:195], v143 offset:5120
	ds_read_b128 v[196:199], v143 offset:6144
	ds_read_b128 v[200:203], v143 offset:7168
	global_load_lds_dwordx4 v130, s[18:19]
	s_add_i32 m0, s67, 0xe000
	s_nop 0
	global_load_lds_dwordx4 v132, s[18:19]
	s_waitcnt vmcnt(8)
	s_waitcnt lgkmcnt(0)
	s_barrier
	s_setprio 1
	s_waitcnt lgkmcnt(0)
	v_mfma_f32_16x16x32_bf16 v[126:129], v[136:139], v[172:175], v[126:129]
	v_mfma_f32_16x16x32_bf16 v[122:125], v[148:151], v[172:175], v[122:125]
	v_mfma_f32_16x16x32_bf16 v[110:113], v[136:139], v[180:183], v[110:113]
	v_mfma_f32_16x16x32_bf16 v[106:109], v[148:151], v[180:183], v[106:109]
	v_mfma_f32_16x16x32_bf16 v[92:95], v[136:139], v[188:191], v[92:95]
	v_mfma_f32_16x16x32_bf16 v[88:91], v[148:151], v[188:191], v[88:91]
	v_mfma_f32_16x16x32_bf16 v[76:79], v[136:139], v[196:199], v[76:79]
	v_mfma_f32_16x16x32_bf16 v[72:75], v[148:151], v[196:199], v[72:75]
	v_mfma_f32_16x16x32_bf16 v[126:129], v[144:147], v[176:179], v[126:129]
	v_mfma_f32_16x16x32_bf16 v[122:125], v[152:155], v[176:179], v[122:125]
	v_mfma_f32_16x16x32_bf16 v[110:113], v[144:147], v[184:187], v[110:113]
	v_mfma_f32_16x16x32_bf16 v[106:109], v[152:155], v[184:187], v[106:109]
	v_mfma_f32_16x16x32_bf16 v[92:95], v[144:147], v[192:195], v[92:95]
	v_mfma_f32_16x16x32_bf16 v[88:91], v[152:155], v[192:195], v[88:91]
	v_mfma_f32_16x16x32_bf16 v[76:79], v[144:147], v[200:203], v[76:79]
	v_mfma_f32_16x16x32_bf16 v[72:75], v[152:155], v[200:203], v[72:75]
	v_mfma_f32_16x16x32_bf16 v[118:121], v[156:159], v[172:175], v[118:121]
	v_mfma_f32_16x16x32_bf16 v[114:117], v[164:167], v[172:175], v[114:117]
	v_mfma_f32_16x16x32_bf16 v[102:105], v[156:159], v[180:183], v[102:105]
	v_mfma_f32_16x16x32_bf16 v[98:101], v[164:167], v[180:183], v[98:101]
	v_mfma_f32_16x16x32_bf16 v[84:87], v[156:159], v[188:191], v[84:87]
	v_mfma_f32_16x16x32_bf16 v[80:83], v[164:167], v[188:191], v[80:83]
	v_mfma_f32_16x16x32_bf16 v[68:71], v[156:159], v[196:199], v[68:71]
	v_mfma_f32_16x16x32_bf16 v[64:67], v[164:167], v[196:199], v[64:67]
	v_mfma_f32_16x16x32_bf16 v[118:121], v[160:163], v[176:179], v[118:121]
	v_mfma_f32_16x16x32_bf16 v[114:117], v[168:171], v[176:179], v[114:117]
	v_mfma_f32_16x16x32_bf16 v[102:105], v[160:163], v[184:187], v[102:105]
	v_mfma_f32_16x16x32_bf16 v[98:101], v[168:171], v[184:187], v[98:101]
	v_mfma_f32_16x16x32_bf16 v[84:87], v[160:163], v[192:195], v[84:87]
	v_mfma_f32_16x16x32_bf16 v[80:83], v[168:171], v[192:195], v[80:83]
	v_mfma_f32_16x16x32_bf16 v[68:71], v[160:163], v[200:203], v[68:71]
	v_mfma_f32_16x16x32_bf16 v[64:67], v[168:171], v[200:203], v[64:67]
	s_setprio 0
	s_barrier
	s_add_i32 s18, s35, s14
	s_mov_b32 m0, s18
	ds_read_b128 v[172:175], v143 offset:16384
	ds_read_b128 v[176:179], v143 offset:17408
	ds_read_b128 v[180:183], v143 offset:18432
	ds_read_b128 v[184:187], v143 offset:19456
	ds_read_b128 v[188:191], v143 offset:20480
	ds_read_b128 v[192:195], v143 offset:21504
	ds_read_b128 v[196:199], v143 offset:22528
	ds_read_b128 v[200:203], v143 offset:23552
	global_load_lds_dwordx4 v96, s[44:45]
	s_add_i32 m0, s18, 0x2000
	s_add_u32 s18, s44, 0x40000
	s_addc_u32 s19, s45, 0
	s_add_i32 s35, s49, s14
	global_load_lds_dwordx4 v134, s[44:45]
	s_mov_b32 m0, s35
	s_nop 0
	global_load_lds_dwordx4 v96, s[18:19]
	s_add_i32 m0, s35, 0x2000
	s_nop 0
	global_load_lds_dwordx4 v134, s[18:19]
	s_mov_b32 m0, s67
	s_nop 0
	global_load_lds_dwordx4 v130, s[42:43]
	s_mov_b32 m0, s73
	s_nop 0
	global_load_lds_dwordx4 v132, s[42:43]
	s_waitcnt vmcnt(8)
	s_waitcnt lgkmcnt(0)
	s_barrier
	s_setprio 1
	s_waitcnt lgkmcnt(0)
	v_mfma_f32_16x16x32_bf16 v[60:63], v[136:139], v[172:175], v[60:63]
	v_mfma_f32_16x16x32_bf16 v[56:59], v[148:151], v[172:175], v[56:59]
	v_mfma_f32_16x16x32_bf16 v[44:47], v[136:139], v[180:183], v[44:47]
	v_mfma_f32_16x16x32_bf16 v[40:43], v[148:151], v[180:183], v[40:43]
	v_mfma_f32_16x16x32_bf16 v[28:31], v[136:139], v[188:191], v[28:31]
	v_mfma_f32_16x16x32_bf16 v[24:27], v[148:151], v[188:191], v[24:27]
	v_mfma_f32_16x16x32_bf16 v[12:15], v[136:139], v[196:199], v[12:15]
	v_mfma_f32_16x16x32_bf16 v[8:11], v[148:151], v[196:199], v[8:11]
	v_mfma_f32_16x16x32_bf16 v[60:63], v[144:147], v[176:179], v[60:63]
	v_mfma_f32_16x16x32_bf16 v[56:59], v[152:155], v[176:179], v[56:59]
	v_mfma_f32_16x16x32_bf16 v[44:47], v[144:147], v[184:187], v[44:47]
	v_mfma_f32_16x16x32_bf16 v[40:43], v[152:155], v[184:187], v[40:43]
	v_mfma_f32_16x16x32_bf16 v[28:31], v[144:147], v[192:195], v[28:31]
	v_mfma_f32_16x16x32_bf16 v[24:27], v[152:155], v[192:195], v[24:27]
	v_mfma_f32_16x16x32_bf16 v[12:15], v[144:147], v[200:203], v[12:15]
	v_mfma_f32_16x16x32_bf16 v[8:11], v[152:155], v[200:203], v[8:11]
	v_mfma_f32_16x16x32_bf16 v[52:55], v[156:159], v[172:175], v[52:55]
	v_mfma_f32_16x16x32_bf16 v[48:51], v[164:167], v[172:175], v[48:51]
	v_mfma_f32_16x16x32_bf16 v[36:39], v[156:159], v[180:183], v[36:39]
	v_mfma_f32_16x16x32_bf16 v[32:35], v[164:167], v[180:183], v[32:35]
	v_mfma_f32_16x16x32_bf16 v[20:23], v[156:159], v[188:191], v[20:23]
	v_mfma_f32_16x16x32_bf16 v[16:19], v[164:167], v[188:191], v[16:19]
	v_mfma_f32_16x16x32_bf16 v[4:7], v[156:159], v[196:199], v[4:7]
	v_mfma_f32_16x16x32_bf16 v[0:3], v[164:167], v[196:199], v[0:3]
	v_mfma_f32_16x16x32_bf16 v[52:55], v[160:163], v[176:179], v[52:55]
	v_mfma_f32_16x16x32_bf16 v[48:51], v[168:171], v[176:179], v[48:51]
	v_mfma_f32_16x16x32_bf16 v[36:39], v[160:163], v[184:187], v[36:39]
	v_mfma_f32_16x16x32_bf16 v[32:35], v[168:171], v[184:187], v[32:35]
	v_mfma_f32_16x16x32_bf16 v[20:23], v[160:163], v[192:195], v[20:23]
	v_mfma_f32_16x16x32_bf16 v[16:19], v[168:171], v[192:195], v[16:19]
	v_mfma_f32_16x16x32_bf16 v[4:7], v[160:163], v[200:203], v[4:7]
	v_mfma_f32_16x16x32_bf16 v[0:3], v[168:171], v[200:203], v[0:3]
	s_setprio 0
	s_barrier
	s_add_i32 s35, 0, 0x18000
	v_add_u32_e32 v140, s35, v142
	s_add_i32 s44, 0, 0x1c000
	ds_read_b128 v[136:139], v140
	ds_read_b128 v[144:147], v140 offset:1024
	ds_read_b128 v[148:151], v140 offset:2048
	ds_read_b128 v[152:155], v140 offset:3072
	v_add_u32_e32 v140, s44, v142
	ds_read_b128 v[156:159], v140
	ds_read_b128 v[160:163], v140 offset:1024
	ds_read_b128 v[164:167], v140 offset:2048
	ds_read_b128 v[168:171], v140 offset:3072
	s_add_u32 s18, s42, 0x40000
	s_addc_u32 s19, s43, 0
	s_mov_b32 m0, s76
	ds_read_b128 v[172:175], v143 offset:32768
	ds_read_b128 v[176:179], v143 offset:33792
	ds_read_b128 v[180:183], v143 offset:34816
	ds_read_b128 v[184:187], v143 offset:35840
	ds_read_b128 v[188:191], v143 offset:36864
	ds_read_b128 v[192:195], v143 offset:37888
	ds_read_b128 v[196:199], v143 offset:38912
	ds_read_b128 v[200:203], v143 offset:39936
	global_load_lds_dwordx4 v130, s[18:19]
	s_mov_b32 m0, s77
	s_nop 0
	global_load_lds_dwordx4 v132, s[18:19]
	s_waitcnt vmcnt(8)
	s_waitcnt lgkmcnt(0)
	s_barrier
	s_setprio 1
	s_waitcnt lgkmcnt(0)
	v_mfma_f32_16x16x32_bf16 v[126:129], v[136:139], v[172:175], v[126:129]
	v_mfma_f32_16x16x32_bf16 v[122:125], v[148:151], v[172:175], v[122:125]
	v_mfma_f32_16x16x32_bf16 v[110:113], v[136:139], v[180:183], v[110:113]
	v_mfma_f32_16x16x32_bf16 v[106:109], v[148:151], v[180:183], v[106:109]
	v_mfma_f32_16x16x32_bf16 v[92:95], v[136:139], v[188:191], v[92:95]
	v_mfma_f32_16x16x32_bf16 v[88:91], v[148:151], v[188:191], v[88:91]
	v_mfma_f32_16x16x32_bf16 v[76:79], v[136:139], v[196:199], v[76:79]
	v_mfma_f32_16x16x32_bf16 v[72:75], v[148:151], v[196:199], v[72:75]
	v_mfma_f32_16x16x32_bf16 v[126:129], v[144:147], v[176:179], v[126:129]
	v_mfma_f32_16x16x32_bf16 v[122:125], v[152:155], v[176:179], v[122:125]
	v_mfma_f32_16x16x32_bf16 v[110:113], v[144:147], v[184:187], v[110:113]
	v_mfma_f32_16x16x32_bf16 v[106:109], v[152:155], v[184:187], v[106:109]
	v_mfma_f32_16x16x32_bf16 v[92:95], v[144:147], v[192:195], v[92:95]
	v_mfma_f32_16x16x32_bf16 v[88:91], v[152:155], v[192:195], v[88:91]
	v_mfma_f32_16x16x32_bf16 v[76:79], v[144:147], v[200:203], v[76:79]
	v_mfma_f32_16x16x32_bf16 v[72:75], v[152:155], v[200:203], v[72:75]
	v_mfma_f32_16x16x32_bf16 v[118:121], v[156:159], v[172:175], v[118:121]
	v_mfma_f32_16x16x32_bf16 v[114:117], v[164:167], v[172:175], v[114:117]
	v_mfma_f32_16x16x32_bf16 v[102:105], v[156:159], v[180:183], v[102:105]
	v_mfma_f32_16x16x32_bf16 v[98:101], v[164:167], v[180:183], v[98:101]
	v_mfma_f32_16x16x32_bf16 v[84:87], v[156:159], v[188:191], v[84:87]
	v_mfma_f32_16x16x32_bf16 v[80:83], v[164:167], v[188:191], v[80:83]
	v_mfma_f32_16x16x32_bf16 v[68:71], v[156:159], v[196:199], v[68:71]
	v_mfma_f32_16x16x32_bf16 v[64:67], v[164:167], v[196:199], v[64:67]
	v_mfma_f32_16x16x32_bf16 v[118:121], v[160:163], v[176:179], v[118:121]
	v_mfma_f32_16x16x32_bf16 v[114:117], v[168:171], v[176:179], v[114:117]
	v_mfma_f32_16x16x32_bf16 v[102:105], v[160:163], v[184:187], v[102:105]
	v_mfma_f32_16x16x32_bf16 v[98:101], v[168:171], v[184:187], v[98:101]
	v_mfma_f32_16x16x32_bf16 v[84:87], v[160:163], v[192:195], v[84:87]
	v_mfma_f32_16x16x32_bf16 v[80:83], v[168:171], v[192:195], v[80:83]
	v_mfma_f32_16x16x32_bf16 v[68:71], v[160:163], v[200:203], v[68:71]
	v_mfma_f32_16x16x32_bf16 v[64:67], v[168:171], v[200:203], v[64:67]
	s_setprio 0
	s_barrier
	s_add_i32 s18, s35, s14
	s_mov_b32 m0, s18
	ds_read_b128 v[172:175], v143 offset:49152
	ds_read_b128 v[176:179], v143 offset:50176
	ds_read_b128 v[180:183], v143 offset:51200
	ds_read_b128 v[184:187], v143 offset:52224
	ds_read_b128 v[188:191], v143 offset:53248
	ds_read_b128 v[192:195], v143 offset:54272
	ds_read_b128 v[196:199], v143 offset:55296
	ds_read_b128 v[200:203], v143 offset:56320
	global_load_lds_dwordx4 v96, s[74:75]
	s_add_i32 m0, s18, 0x2000
	s_add_u32 s18, s74, 0x40000
	s_addc_u32 s19, s75, 0
	s_add_i32 s35, s44, s14
	global_load_lds_dwordx4 v134, s[74:75]
	s_mov_b32 m0, s35
	s_nop 0
	global_load_lds_dwordx4 v96, s[18:19]
	s_add_i32 m0, s35, 0x2000
	s_nop 0
	global_load_lds_dwordx4 v134, s[18:19]
	s_mov_b32 m0, s81
	s_nop 0
	global_load_lds_dwordx4 v130, s[38:39]
	s_mov_b32 m0, s82
	s_nop 0
	global_load_lds_dwordx4 v132, s[38:39]
	s_waitcnt vmcnt(8)
	s_waitcnt lgkmcnt(0)
	s_barrier
	s_setprio 1
	s_waitcnt lgkmcnt(0)
	v_mfma_f32_16x16x32_bf16 v[60:63], v[136:139], v[172:175], v[60:63]
	v_mfma_f32_16x16x32_bf16 v[56:59], v[148:151], v[172:175], v[56:59]
	v_mfma_f32_16x16x32_bf16 v[44:47], v[136:139], v[180:183], v[44:47]
	v_mfma_f32_16x16x32_bf16 v[40:43], v[148:151], v[180:183], v[40:43]
	v_mfma_f32_16x16x32_bf16 v[28:31], v[136:139], v[188:191], v[28:31]
	v_mfma_f32_16x16x32_bf16 v[24:27], v[148:151], v[188:191], v[24:27]
	v_mfma_f32_16x16x32_bf16 v[12:15], v[136:139], v[196:199], v[12:15]
	v_mfma_f32_16x16x32_bf16 v[8:11], v[148:151], v[196:199], v[8:11]
	v_mfma_f32_16x16x32_bf16 v[60:63], v[144:147], v[176:179], v[60:63]
	v_mfma_f32_16x16x32_bf16 v[56:59], v[152:155], v[176:179], v[56:59]
	v_mfma_f32_16x16x32_bf16 v[44:47], v[144:147], v[184:187], v[44:47]
	v_mfma_f32_16x16x32_bf16 v[40:43], v[152:155], v[184:187], v[40:43]
	v_mfma_f32_16x16x32_bf16 v[28:31], v[144:147], v[192:195], v[28:31]
	v_mfma_f32_16x16x32_bf16 v[24:27], v[152:155], v[192:195], v[24:27]
	v_mfma_f32_16x16x32_bf16 v[12:15], v[144:147], v[200:203], v[12:15]
	v_mfma_f32_16x16x32_bf16 v[8:11], v[152:155], v[200:203], v[8:11]
	v_mfma_f32_16x16x32_bf16 v[52:55], v[156:159], v[172:175], v[52:55]
	v_mfma_f32_16x16x32_bf16 v[48:51], v[164:167], v[172:175], v[48:51]
	v_mfma_f32_16x16x32_bf16 v[36:39], v[156:159], v[180:183], v[36:39]
	v_mfma_f32_16x16x32_bf16 v[32:35], v[164:167], v[180:183], v[32:35]
	v_mfma_f32_16x16x32_bf16 v[20:23], v[156:159], v[188:191], v[20:23]
	v_mfma_f32_16x16x32_bf16 v[16:19], v[164:167], v[188:191], v[16:19]
	v_mfma_f32_16x16x32_bf16 v[4:7], v[156:159], v[196:199], v[4:7]
	v_mfma_f32_16x16x32_bf16 v[0:3], v[164:167], v[196:199], v[0:3]
	v_mfma_f32_16x16x32_bf16 v[52:55], v[160:163], v[176:179], v[52:55]
	v_mfma_f32_16x16x32_bf16 v[48:51], v[168:171], v[176:179], v[48:51]
	v_mfma_f32_16x16x32_bf16 v[36:39], v[160:163], v[184:187], v[36:39]
	v_mfma_f32_16x16x32_bf16 v[32:35], v[168:171], v[184:187], v[32:35]
	v_mfma_f32_16x16x32_bf16 v[20:23], v[160:163], v[192:195], v[20:23]
	v_mfma_f32_16x16x32_bf16 v[16:19], v[168:171], v[192:195], v[16:19]
	v_mfma_f32_16x16x32_bf16 v[4:7], v[160:163], v[200:203], v[4:7]
	v_mfma_f32_16x16x32_bf16 v[0:3], v[168:171], v[200:203], v[0:3]
	s_setprio 0
	s_barrier
	s_add_i32 s89, s89, 2
	s_add_u32 s65, s65, 0x100
	s_addc_u32 s86, s86, 0
	s_add_u32 s87, s87, 0x100
	s_addc_u32 s88, s88, 0
	s_add_u32 s68, s68, 0x100
	s_addc_u32 s69, s69, 0
	s_cmp_gt_u32 s89, 13
	s_cbranch_scc0 .LBB0_122
	s_and_b64 vcc, exec, s[28:29]
	s_cbranch_vccz .LBB0_125
	s_barrier

.LBB0_163:
	v_readlane_b32 s22, v255, 12
	v_readlane_b32 s23, v255, 13
	s_ashr_i32 s23, s22, 31
	s_mov_b32 s20, s22
	s_lshl_b64 s[22:23], s[22:23], 13
	s_add_u32 s10, s10, s22
	s_addc_u32 s11, s11, s23
	v_writelane_b32 v255, s20, 12
	s_add_u32 s22, s6, 0x1780000
	s_addc_u32 s23, s7, 0
	v_writelane_b32 v255, s21, 13
	v_writelane_b32 v255, s22, 20
	v_lshlrev_b32_e32 v168, 1, v11
	v_lshlrev_b32_e32 v169, 1, v12
	v_writelane_b32 v255, s23, 21
	s_add_u32 s22, s6, 0x1aa0000
	s_addc_u32 s23, s7, 0
	v_writelane_b32 v255, s22, 32
	v_and_b32_e32 v11, 48, v10
	v_lshlrev_b32_e32 v12, 6, v10
	v_writelane_b32 v255, s23, 33
	s_add_u32 s22, s10, 0x1000
	v_writelane_b32 v255, s10, 28
	s_addc_u32 s23, s11, 0
	v_lshlrev_b32_e32 v10, 2, v10
	v_writelane_b32 v255, s11, 29
	s_movk_i32 s11, 0x3c0
	s_lshl_b32 s10, s16, 13
	v_and_or_b32 v11, v12, s11, v11
	v_and_b32_e32 v10, 32, v10
	v_bitop3_b32 v12, v11, s10, v10 bitop3:0xde
	s_lshl_b32 s10, s18, 5
	s_and_b32 s91, s10, 0x60
	s_lshl_b32 s71, s16, 6
	s_lshl_b32 s10, s91, 7
	s_cmp_gt_i32 s85, 0
	s_cselect_b32 s28, 0, 4
	s_add_u32 s86, s8, 0x7100000
	s_addc_u32 s87, s9, 0
	s_add_u32 s88, s8, 0x7d00000
	s_addc_u32 s89, s9, 0
	v_writelane_b32 v255, s22, 18
	v_bitop3_b32 v170, s10, v11, v10 bitop3:0xf6
	s_add_u32 s10, s8, 0x16100000
	v_writelane_b32 v255, s23, 19
	s_addc_u32 s11, s9, 0
	v_writelane_b32 v255, s10, 36
	v_lshl_add_u64 v[6:7], v[6:7], 0, s[26:27]
	s_waitcnt vmcnt(2)
	s_barrier
	v_writelane_b32 v255, s11, 37
	s_add_u32 s10, s8, 0x18100000
	s_addc_u32 s11, s9, 0
	s_add_u32 s94, s8, 0xbd00000
	s_addc_u32 s95, s9, 0
	s_add_i32 m0, s63, 0x18000
	v_lshl_add_u64 v[4:5], v[4:5], 0, s[26:27]
	global_load_lds_dwordx4 v[6:7], off
	s_add_i32 m0, s63, 0x1a000
	s_add_i32 s82, s63, 0x8000
	s_add_i32 s83, s63, 0xa000
	global_load_lds_dwordx4 v[4:5], off
	v_lshl_add_u64 v[2:3], v[2:3], 0, s[26:27]
	s_mov_b32 m0, s82
	s_add_u32 s8, s68, 0x40080
	global_load_lds_dwordx4 v[2:3], off
	v_lshl_add_u64 v[2:3], v[8:9], 0, s[26:27]
	s_mov_b32 m0, s83
	s_addc_u32 s9, s69, 0
	global_load_lds_dwordx4 v[2:3], off
	s_add_i32 m0, s63, 0x1c000
	s_nop 0
	global_load_lds_dwordx4 v96, s[8:9]
	v_lshl_add_u64 v[0:1], s[8:9], 0, v[0:1]
	s_add_i32 m0, s63, 0x1e000
	s_cmpk_lt_u32 s14, 0x100
	global_load_lds_dwordx4 v[0:1], off
	s_cselect_b64 s[96:97], -1, 0
	s_ashr_i32 s92, s2, 31
	v_writelane_b32 v255, s10, 34
	s_add_u32 s6, s6, 0x1500000
	s_addc_u32 s7, s7, 0
	v_writelane_b32 v255, s11, 35
	v_writelane_b32 v255, s6, 22
	s_waitcnt vmcnt(6)
	s_mov_b32 s33, 0
	s_sub_i32 s93, 0, s85
	v_writelane_b32 v255, s7, 23
	s_mov_b64 s[66:67], 0x40000
	v_readlane_b32 s10, v255, 24
	v_readlane_b32 s8, v255, 30
	s_movk_i32 s14, 0x400
	v_add_u32_e32 v171, 0, v12
	v_readlane_b32 s11, v255, 25
	v_readlane_b32 s9, v255, 31
	s_barrier
	s_branch .LBB0_166

.LBB0_195:
	s_cmp_eq_u32 s72, s76
	s_cselect_b64 s[18:19], -1, 0
	s_add_i32 s76, s76, 2
	s_and_b64 s[42:43], s[18:19], exec
	s_cselect_b32 s44, s38, s73
	s_cselect_b32 s45, s39, s75
	s_cselect_b32 s47, s61, vcc_hi
	s_cselect_b32 s46, s60, vcc_lo
	s_add_u32 s58, s44, 0x80
	s_addc_u32 s59, s45, 0
	s_add_u32 s42, s46, 0x80
	s_addc_u32 s43, s47, 0
	s_add_i32 s35, 0, 0x10000
	s_and_b64 s[30:31], s[18:19], exec
	s_mov_b64 s[68:69], s[78:79]
	v_add_u32_e32 v144, s35, v170
	s_cselect_b32 s49, s29, s14
	s_add_i32 s70, 0, 0x14000
	ds_read_b128 v[132:135], v144
	ds_read_b128 v[136:139], v144 offset:1024
	ds_read_b128 v[140:143], v144 offset:2048
	ds_read_b128 v[150:153], v144 offset:3072
	v_add_u32_e32 v144, s70, v170
	ds_read_b128 v[154:157], v144
	ds_read_b128 v[158:161], v144 offset:1024
	ds_read_b128 v[162:165], v144 offset:2048
	ds_read_b128 v[172:175], v144 offset:3072
	s_and_b64 s[18:19], s[18:19], exec
	s_cselect_b32 s18, 0, s67
	s_cselect_b32 s19, s20, s66
	s_add_u32 s30, s68, s66
	s_addc_u32 s31, s69, s67
	s_add_i32 m0, s63, 0xc000
	ds_read_b128 v[176:179], v171
	ds_read_b128 v[180:183], v171 offset:1024
	ds_read_b128 v[184:187], v171 offset:2048
	ds_read_b128 v[188:191], v171 offset:3072
	ds_read_b128 v[192:195], v171 offset:4096
	ds_read_b128 v[196:199], v171 offset:5120
	ds_read_b128 v[200:203], v171 offset:6144
	ds_read_b128 v[204:207], v171 offset:7168
	global_load_lds_dwordx4 v96, s[30:31]
	s_add_i32 m0, s63, 0xe000
	s_nop 0
	global_load_lds_dwordx4 v130, s[30:31]
	s_waitcnt vmcnt(8)
	s_waitcnt lgkmcnt(0)
	s_barrier
	s_setprio 1
	s_waitcnt lgkmcnt(0)
	v_mfma_f32_16x16x32_bf16 v[126:129], v[132:135], v[176:179], v[126:129]
	v_mfma_f32_16x16x32_bf16 v[122:125], v[140:143], v[176:179], v[122:125]
	v_mfma_f32_16x16x32_bf16 v[110:113], v[132:135], v[184:187], v[110:113]
	v_mfma_f32_16x16x32_bf16 v[106:109], v[140:143], v[184:187], v[106:109]
	v_mfma_f32_16x16x32_bf16 v[92:95], v[132:135], v[192:195], v[92:95]
	v_mfma_f32_16x16x32_bf16 v[88:91], v[140:143], v[192:195], v[88:91]
	v_mfma_f32_16x16x32_bf16 v[76:79], v[132:135], v[200:203], v[76:79]
	v_mfma_f32_16x16x32_bf16 v[72:75], v[140:143], v[200:203], v[72:75]
	v_mfma_f32_16x16x32_bf16 v[126:129], v[136:139], v[180:183], v[126:129]
	v_mfma_f32_16x16x32_bf16 v[122:125], v[150:153], v[180:183], v[122:125]
	v_mfma_f32_16x16x32_bf16 v[110:113], v[136:139], v[188:191], v[110:113]
	v_mfma_f32_16x16x32_bf16 v[106:109], v[150:153], v[188:191], v[106:109]
	v_mfma_f32_16x16x32_bf16 v[92:95], v[136:139], v[196:199], v[92:95]
	v_mfma_f32_16x16x32_bf16 v[88:91], v[150:153], v[196:199], v[88:91]
	v_mfma_f32_16x16x32_bf16 v[76:79], v[136:139], v[204:207], v[76:79]
	v_mfma_f32_16x16x32_bf16 v[72:75], v[150:153], v[204:207], v[72:75]
	v_mfma_f32_16x16x32_bf16 v[118:121], v[154:157], v[176:179], v[118:121]
	v_mfma_f32_16x16x32_bf16 v[114:117], v[162:165], v[176:179], v[114:117]
	v_mfma_f32_16x16x32_bf16 v[102:105], v[154:157], v[184:187], v[102:105]
	v_mfma_f32_16x16x32_bf16 v[98:101], v[162:165], v[184:187], v[98:101]
	v_mfma_f32_16x16x32_bf16 v[84:87], v[154:157], v[192:195], v[84:87]
	v_mfma_f32_16x16x32_bf16 v[80:83], v[162:165], v[192:195], v[80:83]
	v_mfma_f32_16x16x32_bf16 v[68:71], v[154:157], v[200:203], v[68:71]
	v_mfma_f32_16x16x32_bf16 v[64:67], v[162:165], v[200:203], v[64:67]
	v_mfma_f32_16x16x32_bf16 v[118:121], v[158:161], v[180:183], v[118:121]
	v_mfma_f32_16x16x32_bf16 v[114:117], v[172:175], v[180:183], v[114:117]
	v_mfma_f32_16x16x32_bf16 v[102:105], v[158:161], v[188:191], v[102:105]
	v_mfma_f32_16x16x32_bf16 v[98:101], v[172:175], v[188:191], v[98:101]
	v_mfma_f32_16x16x32_bf16 v[84:87], v[158:161], v[196:199], v[84:87]
	v_mfma_f32_16x16x32_bf16 v[80:83], v[172:175], v[196:199], v[80:83]
	v_mfma_f32_16x16x32_bf16 v[68:71], v[158:161], v[204:207], v[68:71]
	v_mfma_f32_16x16x32_bf16 v[64:67], v[172:175], v[204:207], v[64:67]
	s_setprio 0
	s_barrier
	s_add_i32 s35, s35, s80
	v_mad_u64_u32 v[144:145], s[30:31], v168, s49, v[146:147]
	s_mov_b32 m0, s35
	ds_read_b128 v[176:179], v171 offset:16384
	ds_read_b128 v[180:183], v171 offset:17408
	ds_read_b128 v[184:187], v171 offset:18432
	ds_read_b128 v[188:191], v171 offset:19456
	ds_read_b128 v[192:195], v171 offset:20480
	ds_read_b128 v[196:199], v171 offset:21504
	ds_read_b128 v[200:203], v171 offset:22528
	ds_read_b128 v[204:207], v171 offset:23552
	global_load_lds_dwordx4 v144, s[46:47]
	v_mad_u64_u32 v[166:167], s[30:31], v169, s49, v[148:149]
	s_add_i32 m0, s35, 0x2000
	s_add_u32 s30, s46, s19
	s_addc_u32 s31, s47, s18
	s_add_i32 s35, s70, s80
	global_load_lds_dwordx4 v166, s[46:47]
	s_mov_b32 m0, s35
	s_nop 0
	global_load_lds_dwordx4 v144, s[30:31]
	s_add_i32 m0, s35, 0x2000
	s_nop 0
	global_load_lds_dwordx4 v166, s[30:31]
	v_mad_u64_u32 v[208:209], s[30:31], s49, v147, v[146:147]
	s_mov_b32 m0, s63
	v_mad_u64_u32 v[210:211], s[30:31], s49, v149, v[148:149]
	global_load_lds_dwordx4 v208, s[44:45]
	s_mov_b32 m0, s65
	s_nop 0
	global_load_lds_dwordx4 v210, s[44:45]
	s_waitcnt vmcnt(8)
	s_waitcnt lgkmcnt(0)
	s_barrier
	s_setprio 1
	s_waitcnt lgkmcnt(0)
	v_mfma_f32_16x16x32_bf16 v[60:63], v[132:135], v[176:179], v[60:63]
	v_mfma_f32_16x16x32_bf16 v[56:59], v[140:143], v[176:179], v[56:59]
	v_mfma_f32_16x16x32_bf16 v[44:47], v[132:135], v[184:187], v[44:47]
	v_mfma_f32_16x16x32_bf16 v[40:43], v[140:143], v[184:187], v[40:43]
	v_mfma_f32_16x16x32_bf16 v[28:31], v[132:135], v[192:195], v[28:31]
	v_mfma_f32_16x16x32_bf16 v[24:27], v[140:143], v[192:195], v[24:27]
	v_mfma_f32_16x16x32_bf16 v[12:15], v[132:135], v[200:203], v[12:15]
	v_mfma_f32_16x16x32_bf16 v[8:11], v[140:143], v[200:203], v[8:11]
	v_mfma_f32_16x16x32_bf16 v[60:63], v[136:139], v[180:183], v[60:63]
	v_mfma_f32_16x16x32_bf16 v[56:59], v[150:153], v[180:183], v[56:59]
	v_mfma_f32_16x16x32_bf16 v[44:47], v[136:139], v[188:191], v[44:47]
	v_mfma_f32_16x16x32_bf16 v[40:43], v[150:153], v[188:191], v[40:43]
	v_mfma_f32_16x16x32_bf16 v[28:31], v[136:139], v[196:199], v[28:31]
	v_mfma_f32_16x16x32_bf16 v[24:27], v[150:153], v[196:199], v[24:27]
	v_mfma_f32_16x16x32_bf16 v[12:15], v[136:139], v[204:207], v[12:15]
	v_mfma_f32_16x16x32_bf16 v[8:11], v[150:153], v[204:207], v[8:11]
	v_mfma_f32_16x16x32_bf16 v[52:55], v[154:157], v[176:179], v[52:55]
	v_mfma_f32_16x16x32_bf16 v[48:51], v[162:165], v[176:179], v[48:51]
	v_mfma_f32_16x16x32_bf16 v[36:39], v[154:157], v[184:187], v[36:39]
	v_mfma_f32_16x16x32_bf16 v[32:35], v[162:165], v[184:187], v[32:35]
	v_mfma_f32_16x16x32_bf16 v[20:23], v[154:157], v[192:195], v[20:23]
	v_mfma_f32_16x16x32_bf16 v[16:19], v[162:165], v[192:195], v[16:19]
	v_mfma_f32_16x16x32_bf16 v[4:7], v[154:157], v[200:203], v[4:7]
	v_mfma_f32_16x16x32_bf16 v[0:3], v[162:165], v[200:203], v[0:3]
	v_mfma_f32_16x16x32_bf16 v[52:55], v[158:161], v[180:183], v[52:55]
	v_mfma_f32_16x16x32_bf16 v[48:51], v[172:175], v[180:183], v[48:51]
	v_mfma_f32_16x16x32_bf16 v[36:39], v[158:161], v[188:191], v[36:39]
	v_mfma_f32_16x16x32_bf16 v[32:35], v[172:175], v[188:191], v[32:35]
	v_mfma_f32_16x16x32_bf16 v[20:23], v[158:161], v[196:199], v[20:23]
	v_mfma_f32_16x16x32_bf16 v[16:19], v[172:175], v[196:199], v[16:19]
	v_mfma_f32_16x16x32_bf16 v[4:7], v[158:161], v[204:207], v[4:7]
	v_mfma_f32_16x16x32_bf16 v[0:3], v[172:175], v[204:207], v[0:3]
	s_setprio 0
	s_barrier
	s_add_i32 s35, 0, 0x18000
	v_add_u32_e32 v145, s35, v170
	s_add_i32 s46, 0, 0x1c000
	ds_read_b128 v[132:135], v145
	ds_read_b128 v[136:139], v145 offset:1024
	ds_read_b128 v[140:143], v145 offset:2048
	ds_read_b128 v[150:153], v145 offset:3072
	v_add_u32_e32 v145, s46, v170
	ds_read_b128 v[154:157], v145
	ds_read_b128 v[158:161], v145 offset:1024
	ds_read_b128 v[162:165], v145 offset:2048
	ds_read_b128 v[172:175], v145 offset:3072
	s_add_u32 s30, s44, s19
	s_addc_u32 s31, s45, s18
	s_mov_b32 m0, s81
	ds_read_b128 v[176:179], v171 offset:32768
	ds_read_b128 v[180:183], v171 offset:33792
	ds_read_b128 v[184:187], v171 offset:34816
	ds_read_b128 v[188:191], v171 offset:35840
	ds_read_b128 v[192:195], v171 offset:36864
	ds_read_b128 v[196:199], v171 offset:37888
	ds_read_b128 v[200:203], v171 offset:38912
	ds_read_b128 v[204:207], v171 offset:39936
	global_load_lds_dwordx4 v208, s[30:31]
	s_mov_b32 m0, s90
	s_nop 0
	global_load_lds_dwordx4 v210, s[30:31]
	s_waitcnt vmcnt(8)
	s_waitcnt lgkmcnt(0)
	s_barrier
	s_setprio 1
	s_waitcnt lgkmcnt(0)
	v_mfma_f32_16x16x32_bf16 v[126:129], v[132:135], v[176:179], v[126:129]
	v_mfma_f32_16x16x32_bf16 v[122:125], v[140:143], v[176:179], v[122:125]
	v_mfma_f32_16x16x32_bf16 v[110:113], v[132:135], v[184:187], v[110:113]
	v_mfma_f32_16x16x32_bf16 v[106:109], v[140:143], v[184:187], v[106:109]
	v_mfma_f32_16x16x32_bf16 v[92:95], v[132:135], v[192:195], v[92:95]
	v_mfma_f32_16x16x32_bf16 v[88:91], v[140:143], v[192:195], v[88:91]
	v_mfma_f32_16x16x32_bf16 v[76:79], v[132:135], v[200:203], v[76:79]
	v_mfma_f32_16x16x32_bf16 v[72:75], v[140:143], v[200:203], v[72:75]
	v_mfma_f32_16x16x32_bf16 v[126:129], v[136:139], v[180:183], v[126:129]
	v_mfma_f32_16x16x32_bf16 v[122:125], v[150:153], v[180:183], v[122:125]
	v_mfma_f32_16x16x32_bf16 v[110:113], v[136:139], v[188:191], v[110:113]
	v_mfma_f32_16x16x32_bf16 v[106:109], v[150:153], v[188:191], v[106:109]
	v_mfma_f32_16x16x32_bf16 v[92:95], v[136:139], v[196:199], v[92:95]
	v_mfma_f32_16x16x32_bf16 v[88:91], v[150:153], v[196:199], v[88:91]
	v_mfma_f32_16x16x32_bf16 v[76:79], v[136:139], v[204:207], v[76:79]
	v_mfma_f32_16x16x32_bf16 v[72:75], v[150:153], v[204:207], v[72:75]
	v_mfma_f32_16x16x32_bf16 v[118:121], v[154:157], v[176:179], v[118:121]
	v_mfma_f32_16x16x32_bf16 v[114:117], v[162:165], v[176:179], v[114:117]
	v_mfma_f32_16x16x32_bf16 v[102:105], v[154:157], v[184:187], v[102:105]
	v_mfma_f32_16x16x32_bf16 v[98:101], v[162:165], v[184:187], v[98:101]
	v_mfma_f32_16x16x32_bf16 v[84:87], v[154:157], v[192:195], v[84:87]
	v_mfma_f32_16x16x32_bf16 v[80:83], v[162:165], v[192:195], v[80:83]
	v_mfma_f32_16x16x32_bf16 v[68:71], v[154:157], v[200:203], v[68:71]
	v_mfma_f32_16x16x32_bf16 v[64:67], v[162:165], v[200:203], v[64:67]
	v_mfma_f32_16x16x32_bf16 v[118:121], v[158:161], v[180:183], v[118:121]
	v_mfma_f32_16x16x32_bf16 v[114:117], v[172:175], v[180:183], v[114:117]
	v_mfma_f32_16x16x32_bf16 v[102:105], v[158:161], v[188:191], v[102:105]
	v_mfma_f32_16x16x32_bf16 v[98:101], v[172:175], v[188:191], v[98:101]
	v_mfma_f32_16x16x32_bf16 v[84:87], v[158:161], v[196:199], v[84:87]
	v_mfma_f32_16x16x32_bf16 v[80:83], v[172:175], v[196:199], v[80:83]
	v_mfma_f32_16x16x32_bf16 v[68:71], v[158:161], v[204:207], v[68:71]
	v_mfma_f32_16x16x32_bf16 v[64:67], v[172:175], v[204:207], v[64:67]
	s_setprio 0
	s_barrier
	s_add_i32 s30, s35, s80
	s_mov_b32 m0, s30
	ds_read_b128 v[176:179], v171 offset:49152
	ds_read_b128 v[180:183], v171 offset:50176
	ds_read_b128 v[184:187], v171 offset:51200
	ds_read_b128 v[188:191], v171 offset:52224
	ds_read_b128 v[192:195], v171 offset:53248
	ds_read_b128 v[196:199], v171 offset:54272
	ds_read_b128 v[200:203], v171 offset:55296
	ds_read_b128 v[204:207], v171 offset:56320
	global_load_lds_dwordx4 v144, s[42:43]
	s_add_i32 m0, s30, 0x2000
	s_add_u32 s30, s42, s19
	s_addc_u32 s31, s43, s18
	s_add_i32 s18, s46, s80
	global_load_lds_dwordx4 v166, s[42:43]
	s_mov_b32 m0, s18
	s_nop 0
	global_load_lds_dwordx4 v144, s[30:31]
	s_add_i32 m0, s18, 0x2000
	s_nop 0
	global_load_lds_dwordx4 v166, s[30:31]
	s_mov_b32 m0, s82
	s_nop 0
	global_load_lds_dwordx4 v208, s[58:59]
	s_mov_b32 m0, s83
	s_nop 0
	global_load_lds_dwordx4 v210, s[58:59]
	s_waitcnt vmcnt(8)
	s_waitcnt lgkmcnt(0)
	s_barrier
	s_setprio 1
	s_waitcnt lgkmcnt(0)
	v_mfma_f32_16x16x32_bf16 v[60:63], v[132:135], v[176:179], v[60:63]
	v_mfma_f32_16x16x32_bf16 v[56:59], v[140:143], v[176:179], v[56:59]
	v_mfma_f32_16x16x32_bf16 v[44:47], v[132:135], v[184:187], v[44:47]
	v_mfma_f32_16x16x32_bf16 v[40:43], v[140:143], v[184:187], v[40:43]
	v_mfma_f32_16x16x32_bf16 v[28:31], v[132:135], v[192:195], v[28:31]
	v_mfma_f32_16x16x32_bf16 v[24:27], v[140:143], v[192:195], v[24:27]
	v_mfma_f32_16x16x32_bf16 v[12:15], v[132:135], v[200:203], v[12:15]
	v_mfma_f32_16x16x32_bf16 v[8:11], v[140:143], v[200:203], v[8:11]
	v_mfma_f32_16x16x32_bf16 v[60:63], v[136:139], v[180:183], v[60:63]
	v_mfma_f32_16x16x32_bf16 v[56:59], v[150:153], v[180:183], v[56:59]
	v_mfma_f32_16x16x32_bf16 v[44:47], v[136:139], v[188:191], v[44:47]
	v_mfma_f32_16x16x32_bf16 v[40:43], v[150:153], v[188:191], v[40:43]
	v_mfma_f32_16x16x32_bf16 v[28:31], v[136:139], v[196:199], v[28:31]
	v_mfma_f32_16x16x32_bf16 v[24:27], v[150:153], v[196:199], v[24:27]
	v_mfma_f32_16x16x32_bf16 v[12:15], v[136:139], v[204:207], v[12:15]
	v_mfma_f32_16x16x32_bf16 v[8:11], v[150:153], v[204:207], v[8:11]
	v_mfma_f32_16x16x32_bf16 v[52:55], v[154:157], v[176:179], v[52:55]
	v_mfma_f32_16x16x32_bf16 v[48:51], v[162:165], v[176:179], v[48:51]
	v_mfma_f32_16x16x32_bf16 v[36:39], v[154:157], v[184:187], v[36:39]
	v_mfma_f32_16x16x32_bf16 v[32:35], v[162:165], v[184:187], v[32:35]
	v_mfma_f32_16x16x32_bf16 v[20:23], v[154:157], v[192:195], v[20:23]
	v_mfma_f32_16x16x32_bf16 v[16:19], v[162:165], v[192:195], v[16:19]
	v_mfma_f32_16x16x32_bf16 v[4:7], v[154:157], v[200:203], v[4:7]
	v_mfma_f32_16x16x32_bf16 v[0:3], v[162:165], v[200:203], v[0:3]
	v_mfma_f32_16x16x32_bf16 v[52:55], v[158:161], v[180:183], v[52:55]
	v_mfma_f32_16x16x32_bf16 v[48:51], v[172:175], v[180:183], v[48:51]
	v_mfma_f32_16x16x32_bf16 v[36:39], v[158:161], v[188:191], v[36:39]
	v_mfma_f32_16x16x32_bf16 v[32:35], v[172:175], v[188:191], v[32:35]
	v_mfma_f32_16x16x32_bf16 v[20:23], v[158:161], v[196:199], v[20:23]
	v_mfma_f32_16x16x32_bf16 v[16:19], v[172:175], v[196:199], v[16:19]
	v_mfma_f32_16x16x32_bf16 v[4:7], v[158:161], v[204:207], v[4:7]
	v_mfma_f32_16x16x32_bf16 v[0:3], v[172:175], v[204:207], v[0:3]
	s_setprio 0
	s_barrier
	s_add_u32 s73, s73, 0x100
	s_addc_u32 s75, s75, 0
	s_add_u32 vcc_lo, vcc_lo, 0x100
	s_addc_u32 vcc_hi, vcc_hi, 0
	s_add_u32 s78, s78, 0x100
	s_addc_u32 s79, s79, 0
	s_cmp_ge_u32 s76, s16
	s_cbranch_scc0 .LBB0_195
	s_and_b64 vcc, exec, s[96:97]
	s_cbranch_vccz .LBB0_198
	s_barrier

.LBB0_374:
	v_and_b32_e32 v9, 48, v8
	v_lshlrev_b32_e32 v10, 6, v8
	s_movk_i32 s18, 0x3c0
	v_lshlrev_b32_e32 v8, 2, v8
	s_sext_i32_i8 s72, s14
	s_and_b32 s14, s7, 3
	s_lshl_b32 s92, s9, 6
	s_lshl_b32 s9, s9, 13
	v_and_or_b32 v9, v10, s18, v9
	v_and_b32_e32 v8, 32, v8
	v_bitop3_b32 v10, v9, s9, v8 bitop3:0xde
	s_lshl_b32 s9, s14, 5
	s_lshl_b32 s14, s14, 12
	s_add_u32 s30, s10, 0x7300000
	s_addc_u32 s31, s11, 0
	s_add_u32 s58, s10, 0x7500000
	s_addc_u32 s59, s11, 0
	s_add_u32 s60, s10, 0x7d00000
	s_addc_u32 s61, s11, 0
	s_add_i32 m0, s49, 0x18000
	v_lshl_add_u64 v[6:7], v[6:7], 0, s[26:27]
	s_waitcnt vmcnt(2)
	s_barrier
	global_load_lds_dwordx4 v[6:7], off
	v_lshl_add_u64 v[4:5], v[4:5], 0, s[26:27]
	s_add_i32 m0, s49, 0x1a000
	s_add_i32 s93, s49, 0x8000
	s_add_i32 s94, s49, 0xa000
	global_load_lds_dwordx4 v[4:5], off
	v_lshl_add_u64 v[0:1], v[0:1], 0, s[26:27]
	s_mov_b32 m0, s93
	s_add_u32 s18, s76, 0x18080
	global_load_lds_dwordx4 v[0:1], off
	v_lshl_add_u64 v[0:1], v[2:3], 0, s[26:27]
	s_mov_b32 m0, s94
	s_addc_u32 s19, s77, 0
	global_load_lds_dwordx4 v[0:1], off
	s_add_i32 m0, s49, 0x1c000
	s_nop 0
	global_load_lds_dwordx4 v134, s[18:19]
	s_add_i32 m0, s49, 0x1e000
	s_cmpk_lt_u32 s6, 0x100
	global_load_lds_dwordx4 v130, s[18:19]
	s_cselect_b64 s[62:63], -1, 0
	s_lshl_b32 s6, s7, 4
	s_and_b32 s95, s6, 16
	s_bfe_u32 s6, s7, 0x10001
	s_waitcnt vmcnt(6)
	s_or_b32 s96, s6, -16
	s_ashr_i32 s97, s2, 31
	s_add_u32 s64, s2, s33
	v_bitop3_b32 v155, v9, s14, v8 bitop3:0xde
	v_add_u32_e32 v157, 0, v10
	s_addc_u32 s65, s97, s8
	s_lshl_b32 s20, s9, 1
	s_barrier
	s_branch .LBB0_377

.LBB0_383:
	s_add_u32 s18, s78, 0x80
	s_addc_u32 s19, s79, 0
	s_add_u32 s42, s78, 0x100
	s_addc_u32 s43, s79, 0
	s_add_u32 s44, s76, 0x100
	s_addc_u32 s45, s77, 0
	s_add_u32 s80, s78, 0x180
	s_addc_u32 s81, s79, 0
	s_add_u32 s84, s76, 0x180
	s_addc_u32 s85, s77, 0
	s_add_i32 vcc_hi, 0, 0x10000
	s_add_i32 s22, 0, 0x14000
	s_mov_b64 s[82:83], s[80:81]
	v_add_u32_e32 v0, vcc_hi, v155
	v_add_u32_e32 v1, s22, v155
	ds_read_b128 v[2:5], v0
	ds_read_b128 v[6:9], v0 offset:1024
	ds_read_b128 v[10:13], v0 offset:2048
	ds_read_b128 v[14:17], v0 offset:3072
	ds_read_b128 v[18:21], v1
	ds_read_b128 v[22:25], v1 offset:1024
	ds_read_b128 v[26:29], v1 offset:2048
	ds_read_b128 v[30:33], v1 offset:3072
	s_add_u32 s18, s18, 0x18000
	s_addc_u32 s19, s19, 0
	s_add_i32 s88, s49, 0xc000
	s_mov_b32 m0, s88
	s_add_i32 vcc_lo, s49, 0xe000
	ds_read_b128 v[34:37], v157
	ds_read_b128 v[38:41], v157 offset:1024
	ds_read_b128 v[42:45], v157 offset:2048
	ds_read_b128 v[46:49], v157 offset:3072
	ds_read_b128 v[50:53], v157 offset:4096
	ds_read_b128 v[54:57], v157 offset:5120
	ds_read_b128 v[58:61], v157 offset:6144
	ds_read_b128 v[62:65], v157 offset:7168
	global_load_lds_dwordx4 v136, s[18:19]
	s_mov_b32 m0, vcc_lo
	s_nop 0
	global_load_lds_dwordx4 v132, s[18:19]
	s_waitcnt vmcnt(8)
	s_waitcnt lgkmcnt(0)
	s_barrier
	s_setprio 1
	s_waitcnt lgkmcnt(0)
	v_mfma_f32_16x16x32_bf16 v[66:69], v[2:5], v[34:37], 0
	v_mfma_f32_16x16x32_bf16 v[70:73], v[10:13], v[34:37], 0
	v_mfma_f32_16x16x32_bf16 v[74:77], v[2:5], v[42:45], 0
	v_mfma_f32_16x16x32_bf16 v[78:81], v[10:13], v[42:45], 0
	v_mfma_f32_16x16x32_bf16 v[82:85], v[2:5], v[50:53], 0
	v_mfma_f32_16x16x32_bf16 v[86:89], v[10:13], v[50:53], 0
	v_mfma_f32_16x16x32_bf16 v[90:93], v[2:5], v[58:61], 0
	v_mfma_f32_16x16x32_bf16 v[98:101], v[10:13], v[58:61], 0
	v_mfma_f32_16x16x32_bf16 v[66:69], v[6:9], v[38:41], v[66:69]
	v_mfma_f32_16x16x32_bf16 v[70:73], v[14:17], v[38:41], v[70:73]
	v_mfma_f32_16x16x32_bf16 v[74:77], v[6:9], v[46:49], v[74:77]
	v_mfma_f32_16x16x32_bf16 v[78:81], v[14:17], v[46:49], v[78:81]
	v_mfma_f32_16x16x32_bf16 v[82:85], v[6:9], v[54:57], v[82:85]
	v_mfma_f32_16x16x32_bf16 v[86:89], v[14:17], v[54:57], v[86:89]
	v_mfma_f32_16x16x32_bf16 v[90:93], v[6:9], v[62:65], v[90:93]
	v_mfma_f32_16x16x32_bf16 v[98:101], v[14:17], v[62:65], v[98:101]
	v_mfma_f32_16x16x32_bf16 v[102:105], v[18:21], v[34:37], 0
	v_mfma_f32_16x16x32_bf16 v[34:37], v[26:29], v[34:37], 0
	v_mfma_f32_16x16x32_bf16 v[102:105], v[22:25], v[38:41], v[102:105]
	v_mfma_f32_16x16x32_bf16 v[34:37], v[30:33], v[38:41], v[34:37]
	v_mfma_f32_16x16x32_bf16 v[38:41], v[18:21], v[42:45], 0
	v_mfma_f32_16x16x32_bf16 v[42:45], v[26:29], v[42:45], 0
	v_mfma_f32_16x16x32_bf16 v[38:41], v[22:25], v[46:49], v[38:41]
	v_mfma_f32_16x16x32_bf16 v[42:45], v[30:33], v[46:49], v[42:45]
	v_mfma_f32_16x16x32_bf16 v[46:49], v[18:21], v[50:53], 0
	v_mfma_f32_16x16x32_bf16 v[50:53], v[26:29], v[50:53], 0
	v_mfma_f32_16x16x32_bf16 v[46:49], v[22:25], v[54:57], v[46:49]
	v_mfma_f32_16x16x32_bf16 v[50:53], v[30:33], v[54:57], v[50:53]
	v_mfma_f32_16x16x32_bf16 v[54:57], v[18:21], v[58:61], 0
	v_mfma_f32_16x16x32_bf16 v[58:61], v[26:29], v[58:61], 0
	v_mfma_f32_16x16x32_bf16 v[54:57], v[22:25], v[62:65], v[54:57]
	v_mfma_f32_16x16x32_bf16 v[58:61], v[30:33], v[62:65], v[58:61]
	s_setprio 0
	s_barrier
	s_add_i32 vcc_hi, vcc_hi, s75
	s_add_i32 s70, vcc_hi, 0x2000
	s_mov_b32 m0, vcc_hi
	s_add_u32 s18, s44, 0x18000
	ds_read_b128 v[62:65], v157 offset:16384
	ds_read_b128 v[106:109], v157 offset:17408
	ds_read_b128 v[110:113], v157 offset:18432
	ds_read_b128 v[114:117], v157 offset:19456
	ds_read_b128 v[118:121], v157 offset:20480
	ds_read_b128 v[122:125], v157 offset:21504
	ds_read_b128 v[126:129], v157 offset:22528
	ds_read_b128 v[138:141], v157 offset:23552
	global_load_lds_dwordx4 v134, s[44:45]
	s_mov_b32 m0, s70
	s_addc_u32 s19, s45, 0
	s_add_i32 s22, s22, s75
	global_load_lds_dwordx4 v130, s[44:45]
	s_mov_b32 m0, s22
	s_add_i32 s23, s22, 0x2000
	global_load_lds_dwordx4 v134, s[18:19]
	s_mov_b32 m0, s23
	s_nop 0
	global_load_lds_dwordx4 v130, s[18:19]
	s_mov_b32 m0, s49
	s_nop 0
	global_load_lds_dwordx4 v136, s[42:43]
	s_mov_b32 m0, s89
	s_nop 0
	global_load_lds_dwordx4 v132, s[42:43]
	s_waitcnt vmcnt(8)
	s_waitcnt lgkmcnt(0)
	s_barrier
	s_setprio 1
	s_waitcnt lgkmcnt(0)
	v_mfma_f32_16x16x32_bf16 v[142:145], v[2:5], v[62:65], 0
	v_mfma_f32_16x16x32_bf16 v[150:153], v[2:5], v[110:113], 0
	v_mfma_f32_16x16x32_bf16 v[162:165], v[2:5], v[118:121], 0
	v_mfma_f32_16x16x32_bf16 v[2:5], v[2:5], v[126:129], 0
	v_mfma_f32_16x16x32_bf16 v[142:145], v[6:9], v[106:109], v[142:145]
	v_mfma_f32_16x16x32_bf16 v[146:149], v[10:13], v[62:65], 0
	v_mfma_f32_16x16x32_bf16 v[150:153], v[6:9], v[114:117], v[150:153]
	v_mfma_f32_16x16x32_bf16 v[158:161], v[10:13], v[110:113], 0
	v_mfma_f32_16x16x32_bf16 v[162:165], v[6:9], v[122:125], v[162:165]
	v_mfma_f32_16x16x32_bf16 v[166:169], v[10:13], v[118:121], 0
	v_mfma_f32_16x16x32_bf16 v[4:7], v[6:9], v[138:141], v[2:5]
	v_mfma_f32_16x16x32_bf16 v[8:11], v[10:13], v[126:129], 0
	v_mfma_f32_16x16x32_bf16 v[8:11], v[14:17], v[138:141], v[8:11]
	v_mfma_f32_16x16x32_bf16 v[146:149], v[14:17], v[106:109], v[146:149]
	v_mfma_f32_16x16x32_bf16 v[158:161], v[14:17], v[114:117], v[158:161]
	v_mfma_f32_16x16x32_bf16 v[166:169], v[14:17], v[122:125], v[166:169]
	v_mfma_f32_16x16x32_bf16 v[12:15], v[18:21], v[62:65], 0
	v_mfma_f32_16x16x32_bf16 v[62:65], v[26:29], v[62:65], 0
	v_mfma_f32_16x16x32_bf16 v[12:15], v[22:25], v[106:109], v[12:15]
	v_mfma_f32_16x16x32_bf16 v[62:65], v[30:33], v[106:109], v[62:65]
	v_mfma_f32_16x16x32_bf16 v[106:109], v[18:21], v[110:113], 0
	v_mfma_f32_16x16x32_bf16 v[110:113], v[26:29], v[110:113], 0
	v_mfma_f32_16x16x32_bf16 v[106:109], v[22:25], v[114:117], v[106:109]
	v_mfma_f32_16x16x32_bf16 v[110:113], v[30:33], v[114:117], v[110:113]
	v_mfma_f32_16x16x32_bf16 v[114:117], v[18:21], v[118:121], 0
	v_mfma_f32_16x16x32_bf16 v[16:19], v[18:21], v[126:129], 0
	v_mfma_f32_16x16x32_bf16 v[114:117], v[22:25], v[122:125], v[114:117]
	v_mfma_f32_16x16x32_bf16 v[118:121], v[26:29], v[118:121], 0
	v_mfma_f32_16x16x32_bf16 v[16:19], v[22:25], v[138:141], v[16:19]
	v_mfma_f32_16x16x32_bf16 v[20:23], v[26:29], v[126:129], 0
	v_mfma_f32_16x16x32_bf16 v[118:121], v[30:33], v[122:125], v[118:121]
	v_mfma_f32_16x16x32_bf16 v[20:23], v[30:33], v[138:141], v[20:23]
	s_setprio 0
	s_barrier
	s_add_i32 s35, 0, 0x18000
	s_add_i32 s44, 0, 0x1c000
	v_add_u32_e32 v2, s35, v155
	v_add_u32_e32 v3, s44, v155
	ds_read_b128 v[24:27], v2
	ds_read_b128 v[28:31], v2 offset:1024
	ds_read_b128 v[122:125], v2 offset:2048
	ds_read_b128 v[126:129], v2 offset:3072
	ds_read_b128 v[138:141], v3
	ds_read_b128 v[170:173], v3 offset:1024
	ds_read_b128 v[174:177], v3 offset:2048
	ds_read_b128 v[178:181], v3 offset:3072
	s_add_u32 s18, s42, 0x18000
	s_addc_u32 s19, s43, 0
	s_mov_b32 m0, s90
	ds_read_b128 v[182:185], v157 offset:32768
	ds_read_b128 v[190:193], v157 offset:33792
	ds_read_b128 v[194:197], v157 offset:34816
	ds_read_b128 v[198:201], v157 offset:35840
	ds_read_b128 v[202:205], v157 offset:36864
	ds_read_b128 v[206:209], v157 offset:37888
	ds_read_b128 v[210:213], v157 offset:38912
	ds_read_b128 v[220:223], v157 offset:39936
	global_load_lds_dwordx4 v136, s[18:19]
	s_mov_b32 m0, s91
	s_nop 0
	global_load_lds_dwordx4 v132, s[18:19]
	s_waitcnt vmcnt(8)
	s_waitcnt lgkmcnt(0)
	s_barrier
	s_setprio 1
	s_waitcnt lgkmcnt(0)
	v_mfma_f32_16x16x32_bf16 v[66:69], v[24:27], v[182:185], v[66:69]
	v_mfma_f32_16x16x32_bf16 v[70:73], v[122:125], v[182:185], v[70:73]
	v_mfma_f32_16x16x32_bf16 v[74:77], v[24:27], v[194:197], v[74:77]
	v_mfma_f32_16x16x32_bf16 v[78:81], v[122:125], v[194:197], v[78:81]
	v_mfma_f32_16x16x32_bf16 v[82:85], v[24:27], v[202:205], v[82:85]
	v_mfma_f32_16x16x32_bf16 v[86:89], v[122:125], v[202:205], v[86:89]
	v_mfma_f32_16x16x32_bf16 v[90:93], v[24:27], v[210:213], v[90:93]
	v_mfma_f32_16x16x32_bf16 v[98:101], v[122:125], v[210:213], v[98:101]
	v_mfma_f32_16x16x32_bf16 v[66:69], v[28:31], v[190:193], v[66:69]
	v_mfma_f32_16x16x32_bf16 v[70:73], v[126:129], v[190:193], v[70:73]
	v_mfma_f32_16x16x32_bf16 v[74:77], v[28:31], v[198:201], v[74:77]
	v_mfma_f32_16x16x32_bf16 v[78:81], v[126:129], v[198:201], v[78:81]
	v_mfma_f32_16x16x32_bf16 v[82:85], v[28:31], v[206:209], v[82:85]
	v_mfma_f32_16x16x32_bf16 v[86:89], v[126:129], v[206:209], v[86:89]
	v_mfma_f32_16x16x32_bf16 v[90:93], v[28:31], v[220:223], v[90:93]
	v_mfma_f32_16x16x32_bf16 v[98:101], v[126:129], v[220:223], v[98:101]
	v_mfma_f32_16x16x32_bf16 v[102:105], v[138:141], v[182:185], v[102:105]
	v_mfma_f32_16x16x32_bf16 v[32:35], v[174:177], v[182:185], v[34:37]
	v_mfma_f32_16x16x32_bf16 v[36:39], v[138:141], v[194:197], v[38:41]
	v_mfma_f32_16x16x32_bf16 v[40:43], v[174:177], v[194:197], v[42:45]
	v_mfma_f32_16x16x32_bf16 v[44:47], v[138:141], v[202:205], v[46:49]
	v_mfma_f32_16x16x32_bf16 v[48:51], v[174:177], v[202:205], v[50:53]
	v_mfma_f32_16x16x32_bf16 v[52:55], v[138:141], v[210:213], v[54:57]
	v_mfma_f32_16x16x32_bf16 v[56:59], v[174:177], v[210:213], v[58:61]
	v_mfma_f32_16x16x32_bf16 v[102:105], v[170:173], v[190:193], v[102:105]
	v_mfma_f32_16x16x32_bf16 v[32:35], v[178:181], v[190:193], v[32:35]
	v_mfma_f32_16x16x32_bf16 v[36:39], v[170:173], v[198:201], v[36:39]
	v_mfma_f32_16x16x32_bf16 v[40:43], v[178:181], v[198:201], v[40:43]
	v_mfma_f32_16x16x32_bf16 v[44:47], v[170:173], v[206:209], v[44:47]
	v_mfma_f32_16x16x32_bf16 v[52:55], v[170:173], v[220:223], v[52:55]
	v_mfma_f32_16x16x32_bf16 v[56:59], v[178:181], v[220:223], v[56:59]
	v_mfma_f32_16x16x32_bf16 v[48:51], v[178:181], v[206:209], v[48:51]
	s_setprio 0
	s_barrier
	s_add_i32 s18, s35, s75
	s_add_i32 s35, s18, 0x2000
	s_mov_b32 m0, s18
	s_add_u32 s42, s84, 0x18000
	ds_read_b128 v[182:185], v157 offset:49152
	ds_read_b128 v[190:193], v157 offset:50176
	ds_read_b128 v[194:197], v157 offset:51200
	ds_read_b128 v[198:201], v157 offset:52224
	ds_read_b128 v[202:205], v157 offset:53248
	ds_read_b128 v[206:209], v157 offset:54272
	ds_read_b128 v[210:213], v157 offset:55296
	ds_read_b128 v[220:223], v157 offset:56320
	global_load_lds_dwordx4 v134, s[84:85]
	s_mov_b32 m0, s35
	s_addc_u32 s43, s85, 0
	s_add_i32 s19, s44, s75
	global_load_lds_dwordx4 v130, s[84:85]
	s_mov_b32 m0, s19
	s_add_i32 s84, s19, 0x2000
	global_load_lds_dwordx4 v134, s[42:43]
	s_mov_b32 m0, s84
	s_nop 0
	global_load_lds_dwordx4 v130, s[42:43]
	s_mov_b32 m0, s93
	s_nop 0
	global_load_lds_dwordx4 v136, s[82:83]
	s_mov_b32 m0, s94
	s_nop 0
	global_load_lds_dwordx4 v132, s[82:83]
	s_waitcnt vmcnt(8)
	s_waitcnt lgkmcnt(0)
	s_barrier
	s_setprio 1
	s_waitcnt lgkmcnt(0)
	v_mfma_f32_16x16x32_bf16 v[4:7], v[24:27], v[210:213], v[4:7]
	v_mfma_f32_16x16x32_bf16 v[8:11], v[122:125], v[210:213], v[8:11]
	v_mfma_f32_16x16x32_bf16 v[142:145], v[24:27], v[182:185], v[142:145]
	v_mfma_f32_16x16x32_bf16 v[146:149], v[122:125], v[182:185], v[146:149]
	v_mfma_f32_16x16x32_bf16 v[150:153], v[24:27], v[194:197], v[150:153]
	v_mfma_f32_16x16x32_bf16 v[158:161], v[122:125], v[194:197], v[158:161]
	v_mfma_f32_16x16x32_bf16 v[162:165], v[24:27], v[202:205], v[162:165]
	v_mfma_f32_16x16x32_bf16 v[166:169], v[122:125], v[202:205], v[166:169]
	v_mfma_f32_16x16x32_bf16 v[4:7], v[28:31], v[220:223], v[4:7]
	v_mfma_f32_16x16x32_bf16 v[8:11], v[126:129], v[220:223], v[8:11]
	v_mfma_f32_16x16x32_bf16 v[142:145], v[28:31], v[190:193], v[142:145]
	v_mfma_f32_16x16x32_bf16 v[146:149], v[126:129], v[190:193], v[146:149]
	v_mfma_f32_16x16x32_bf16 v[150:153], v[28:31], v[198:201], v[150:153]
	v_mfma_f32_16x16x32_bf16 v[158:161], v[126:129], v[198:201], v[158:161]
	v_mfma_f32_16x16x32_bf16 v[162:165], v[28:31], v[206:209], v[162:165]
	v_mfma_f32_16x16x32_bf16 v[166:169], v[126:129], v[206:209], v[166:169]
	v_mfma_f32_16x16x32_bf16 v[12:15], v[138:141], v[182:185], v[12:15]
	v_mfma_f32_16x16x32_bf16 v[24:27], v[174:177], v[182:185], v[62:65]
	v_mfma_f32_16x16x32_bf16 v[28:31], v[138:141], v[194:197], v[106:109]
	v_mfma_f32_16x16x32_bf16 v[60:63], v[174:177], v[194:197], v[110:113]
	v_mfma_f32_16x16x32_bf16 v[106:109], v[138:141], v[202:205], v[114:117]
	v_mfma_f32_16x16x32_bf16 v[110:113], v[174:177], v[202:205], v[118:121]
	v_mfma_f32_16x16x32_bf16 v[16:19], v[138:141], v[210:213], v[16:19]
	v_mfma_f32_16x16x32_bf16 v[20:23], v[174:177], v[210:213], v[20:23]
	v_mfma_f32_16x16x32_bf16 v[12:15], v[170:173], v[190:193], v[12:15]
	v_mfma_f32_16x16x32_bf16 v[24:27], v[178:181], v[190:193], v[24:27]
	v_mfma_f32_16x16x32_bf16 v[28:31], v[170:173], v[198:201], v[28:31]
	v_mfma_f32_16x16x32_bf16 v[60:63], v[178:181], v[198:201], v[60:63]
	v_mfma_f32_16x16x32_bf16 v[106:109], v[170:173], v[206:209], v[106:109]
	v_mfma_f32_16x16x32_bf16 v[110:113], v[178:181], v[206:209], v[110:113]
	v_mfma_f32_16x16x32_bf16 v[16:19], v[170:173], v[220:223], v[16:19]
	v_mfma_f32_16x16x32_bf16 v[20:23], v[178:181], v[220:223], v[20:23]
	s_setprio 0
	s_barrier
	s_add_u32 s44, s78, 0x200
	s_addc_u32 s45, s79, 0
	s_add_u32 s46, s76, 0x200
	s_addc_u32 s47, s77, 0
	s_add_u32 s78, s78, 0x280
	s_addc_u32 s79, s79, 0
	s_add_u32 s76, s76, 0x280
	s_addc_u32 s77, s77, 0
	s_mov_b64 s[42:43], s[78:79]
	ds_read_b128 v[114:117], v0
	ds_read_b128 v[118:121], v0 offset:1024
	ds_read_b128 v[122:125], v0 offset:2048
	ds_read_b128 v[126:129], v0 offset:3072
	ds_read_b128 v[138:141], v1
	ds_read_b128 v[170:173], v1 offset:1024
	ds_read_b128 v[174:177], v1 offset:2048
	ds_read_b128 v[178:181], v1 offset:3072
	s_add_u32 s80, s80, 0x18000
	s_addc_u32 s81, s81, 0
	s_mov_b32 m0, s88
	ds_read_b128 v[182:185], v157
	ds_read_b128 v[190:193], v157 offset:1024
	ds_read_b128 v[194:197], v157 offset:2048
	ds_read_b128 v[198:201], v157 offset:3072
	ds_read_b128 v[202:205], v157 offset:4096
	ds_read_b128 v[206:209], v157 offset:5120
	ds_read_b128 v[210:213], v157 offset:6144
	ds_read_b128 v[220:223], v157 offset:7168
	global_load_lds_dwordx4 v136, s[80:81]
	s_mov_b32 m0, vcc_lo
	s_nop 0
	global_load_lds_dwordx4 v132, s[80:81]
	s_waitcnt vmcnt(8)
	s_waitcnt lgkmcnt(0)
	s_barrier
	s_setprio 1
	s_waitcnt lgkmcnt(0)
	v_mfma_f32_16x16x32_bf16 v[64:67], v[114:117], v[182:185], v[66:69]
	v_mfma_f32_16x16x32_bf16 v[68:71], v[122:125], v[182:185], v[70:73]
	v_mfma_f32_16x16x32_bf16 v[72:75], v[114:117], v[194:197], v[74:77]
	v_mfma_f32_16x16x32_bf16 v[76:79], v[122:125], v[194:197], v[78:81]
	v_mfma_f32_16x16x32_bf16 v[80:83], v[114:117], v[202:205], v[82:85]
	v_mfma_f32_16x16x32_bf16 v[84:87], v[122:125], v[202:205], v[86:89]
	v_mfma_f32_16x16x32_bf16 v[88:91], v[114:117], v[210:213], v[90:93]
	v_mfma_f32_16x16x32_bf16 v[92:95], v[122:125], v[210:213], v[98:101]
	v_mfma_f32_16x16x32_bf16 v[64:67], v[118:121], v[190:193], v[64:67]
	v_mfma_f32_16x16x32_bf16 v[68:71], v[126:129], v[190:193], v[68:71]
	v_mfma_f32_16x16x32_bf16 v[72:75], v[118:121], v[198:201], v[72:75]
	v_mfma_f32_16x16x32_bf16 v[76:79], v[126:129], v[198:201], v[76:79]
	v_mfma_f32_16x16x32_bf16 v[80:83], v[118:121], v[206:209], v[80:83]
	v_mfma_f32_16x16x32_bf16 v[84:87], v[126:129], v[206:209], v[84:87]
	v_mfma_f32_16x16x32_bf16 v[88:91], v[118:121], v[220:223], v[88:91]
	v_mfma_f32_16x16x32_bf16 v[92:95], v[126:129], v[220:223], v[92:95]
	v_mfma_f32_16x16x32_bf16 v[98:101], v[138:141], v[182:185], v[102:105]
	v_mfma_f32_16x16x32_bf16 v[32:35], v[174:177], v[182:185], v[32:35]
	v_mfma_f32_16x16x32_bf16 v[36:39], v[138:141], v[194:197], v[36:39]
	v_mfma_f32_16x16x32_bf16 v[40:43], v[174:177], v[194:197], v[40:43]
	v_mfma_f32_16x16x32_bf16 v[44:47], v[138:141], v[202:205], v[44:47]
	v_mfma_f32_16x16x32_bf16 v[52:55], v[138:141], v[210:213], v[52:55]
	v_mfma_f32_16x16x32_bf16 v[56:59], v[174:177], v[210:213], v[56:59]
	v_mfma_f32_16x16x32_bf16 v[98:101], v[170:173], v[190:193], v[98:101]
	v_mfma_f32_16x16x32_bf16 v[32:35], v[178:181], v[190:193], v[32:35]
	v_mfma_f32_16x16x32_bf16 v[36:39], v[170:173], v[198:201], v[36:39]
	v_mfma_f32_16x16x32_bf16 v[40:43], v[178:181], v[198:201], v[40:43]
	v_mfma_f32_16x16x32_bf16 v[44:47], v[170:173], v[206:209], v[44:47]
	v_mfma_f32_16x16x32_bf16 v[48:51], v[174:177], v[202:205], v[48:51]
	v_mfma_f32_16x16x32_bf16 v[52:55], v[170:173], v[220:223], v[52:55]
	v_mfma_f32_16x16x32_bf16 v[56:59], v[178:181], v[220:223], v[56:59]
	v_mfma_f32_16x16x32_bf16 v[48:51], v[178:181], v[206:209], v[48:51]
	s_setprio 0
	s_barrier
	s_mov_b32 m0, vcc_hi
	ds_read_b128 v[102:105], v157 offset:16384
	ds_read_b128 v[182:185], v157 offset:17408
	ds_read_b128 v[190:193], v157 offset:18432
	ds_read_b128 v[194:197], v157 offset:19456
	ds_read_b128 v[198:201], v157 offset:20480
	ds_read_b128 v[202:205], v157 offset:21504
	ds_read_b128 v[206:209], v157 offset:22528
	ds_read_b128 v[210:213], v157 offset:23552
	global_load_lds_dwordx4 v134, s[46:47]
	v_lshl_add_u64 v[186:187], s[46:47], 0, v[130:131]
	s_add_u32 s46, s46, 0x18000
	s_mov_b32 m0, s70
	s_addc_u32 s47, s47, 0
	global_load_lds_dwordx4 v[186:187], off
	s_mov_b32 m0, s22
	s_nop 0
	global_load_lds_dwordx4 v134, s[46:47]
	s_mov_b32 m0, s23
	s_nop 0
	global_load_lds_dwordx4 v130, s[46:47]
	s_mov_b32 m0, s49
	s_nop 0
	global_load_lds_dwordx4 v136, s[44:45]
	s_mov_b32 m0, s89
	s_nop 0
	global_load_lds_dwordx4 v132, s[44:45]
	s_waitcnt vmcnt(8)
	s_waitcnt lgkmcnt(0)
	s_barrier
	s_setprio 1
	s_waitcnt lgkmcnt(0)
	v_mfma_f32_16x16x32_bf16 v[4:7], v[114:117], v[206:209], v[4:7]
	v_mfma_f32_16x16x32_bf16 v[8:11], v[122:125], v[206:209], v[8:11]
	v_mfma_f32_16x16x32_bf16 v[142:145], v[114:117], v[102:105], v[142:145]
	v_mfma_f32_16x16x32_bf16 v[146:149], v[122:125], v[102:105], v[146:149]
	v_mfma_f32_16x16x32_bf16 v[150:153], v[114:117], v[190:193], v[150:153]
	v_mfma_f32_16x16x32_bf16 v[158:161], v[122:125], v[190:193], v[158:161]
	v_mfma_f32_16x16x32_bf16 v[162:165], v[114:117], v[198:201], v[162:165]
	v_mfma_f32_16x16x32_bf16 v[166:169], v[122:125], v[198:201], v[166:169]
	v_mfma_f32_16x16x32_bf16 v[4:7], v[118:121], v[210:213], v[4:7]
	v_mfma_f32_16x16x32_bf16 v[8:11], v[126:129], v[210:213], v[8:11]
	v_mfma_f32_16x16x32_bf16 v[142:145], v[118:121], v[182:185], v[142:145]
	v_mfma_f32_16x16x32_bf16 v[146:149], v[126:129], v[182:185], v[146:149]
	v_mfma_f32_16x16x32_bf16 v[150:153], v[118:121], v[194:197], v[150:153]
	v_mfma_f32_16x16x32_bf16 v[158:161], v[126:129], v[194:197], v[158:161]
	v_mfma_f32_16x16x32_bf16 v[162:165], v[118:121], v[202:205], v[162:165]
	v_mfma_f32_16x16x32_bf16 v[166:169], v[126:129], v[202:205], v[166:169]
	v_mfma_f32_16x16x32_bf16 v[12:15], v[138:141], v[102:105], v[12:15]
	v_mfma_f32_16x16x32_bf16 v[24:27], v[174:177], v[102:105], v[24:27]
	v_mfma_f32_16x16x32_bf16 v[28:31], v[138:141], v[190:193], v[28:31]
	v_mfma_f32_16x16x32_bf16 v[60:63], v[174:177], v[190:193], v[60:63]
	v_mfma_f32_16x16x32_bf16 v[102:105], v[138:141], v[198:201], v[106:109]
	v_mfma_f32_16x16x32_bf16 v[106:109], v[174:177], v[198:201], v[110:113]
	v_mfma_f32_16x16x32_bf16 v[16:19], v[138:141], v[206:209], v[16:19]
	v_mfma_f32_16x16x32_bf16 v[20:23], v[174:177], v[206:209], v[20:23]
	v_mfma_f32_16x16x32_bf16 v[12:15], v[170:173], v[182:185], v[12:15]
	v_mfma_f32_16x16x32_bf16 v[24:27], v[178:181], v[182:185], v[24:27]
	v_mfma_f32_16x16x32_bf16 v[28:31], v[170:173], v[194:197], v[28:31]
	v_mfma_f32_16x16x32_bf16 v[60:63], v[178:181], v[194:197], v[60:63]
	v_mfma_f32_16x16x32_bf16 v[102:105], v[170:173], v[202:205], v[102:105]
	v_mfma_f32_16x16x32_bf16 v[106:109], v[178:181], v[202:205], v[106:109]
	v_mfma_f32_16x16x32_bf16 v[16:19], v[170:173], v[210:213], v[16:19]
	v_mfma_f32_16x16x32_bf16 v[20:23], v[178:181], v[210:213], v[20:23]
	s_setprio 0
	s_barrier
	ds_read_b128 v[110:113], v2
	ds_read_b128 v[114:117], v2 offset:1024
	ds_read_b128 v[118:121], v2 offset:2048
	ds_read_b128 v[122:125], v2 offset:3072
	ds_read_b128 v[126:129], v3
	ds_read_b128 v[138:141], v3 offset:1024
	ds_read_b128 v[170:173], v3 offset:2048
	ds_read_b128 v[174:177], v3 offset:3072
	s_add_u32 s44, s44, 0x18000
	s_addc_u32 s45, s45, 0
	s_mov_b32 m0, s90
	ds_read_b128 v[178:181], v157 offset:32768
	ds_read_b128 v[182:185], v157 offset:33792
	ds_read_b128 v[190:193], v157 offset:34816
	ds_read_b128 v[194:197], v157 offset:35840
	ds_read_b128 v[198:201], v157 offset:36864
	ds_read_b128 v[202:205], v157 offset:37888
	ds_read_b128 v[206:209], v157 offset:38912
	ds_read_b128 v[210:213], v157 offset:39936
	global_load_lds_dwordx4 v136, s[44:45]
	s_mov_b32 m0, s91
	s_nop 0
	global_load_lds_dwordx4 v132, s[44:45]
	s_waitcnt vmcnt(8)
	s_waitcnt lgkmcnt(0)
	s_barrier
	s_setprio 1
	s_waitcnt lgkmcnt(0)
	v_mfma_f32_16x16x32_bf16 v[64:67], v[110:113], v[178:181], v[64:67]
	v_mfma_f32_16x16x32_bf16 v[68:71], v[118:121], v[178:181], v[68:71]
	v_mfma_f32_16x16x32_bf16 v[72:75], v[110:113], v[190:193], v[72:75]
	v_mfma_f32_16x16x32_bf16 v[76:79], v[118:121], v[190:193], v[76:79]
	v_mfma_f32_16x16x32_bf16 v[80:83], v[110:113], v[198:201], v[80:83]
	v_mfma_f32_16x16x32_bf16 v[84:87], v[118:121], v[198:201], v[84:87]
	v_mfma_f32_16x16x32_bf16 v[88:91], v[110:113], v[206:209], v[88:91]
	v_mfma_f32_16x16x32_bf16 v[92:95], v[118:121], v[206:209], v[92:95]
	v_mfma_f32_16x16x32_bf16 v[64:67], v[114:117], v[182:185], v[64:67]
	v_mfma_f32_16x16x32_bf16 v[68:71], v[122:125], v[182:185], v[68:71]
	v_mfma_f32_16x16x32_bf16 v[72:75], v[114:117], v[194:197], v[72:75]
	v_mfma_f32_16x16x32_bf16 v[76:79], v[122:125], v[194:197], v[76:79]
	v_mfma_f32_16x16x32_bf16 v[80:83], v[114:117], v[202:205], v[80:83]
	v_mfma_f32_16x16x32_bf16 v[84:87], v[122:125], v[202:205], v[84:87]
	v_mfma_f32_16x16x32_bf16 v[88:91], v[114:117], v[210:213], v[88:91]
	v_mfma_f32_16x16x32_bf16 v[92:95], v[122:125], v[210:213], v[92:95]
	v_mfma_f32_16x16x32_bf16 v[98:101], v[126:129], v[178:181], v[98:101]
	v_mfma_f32_16x16x32_bf16 v[32:35], v[170:173], v[178:181], v[32:35]
	v_mfma_f32_16x16x32_bf16 v[36:39], v[126:129], v[190:193], v[36:39]
	v_mfma_f32_16x16x32_bf16 v[40:43], v[170:173], v[190:193], v[40:43]
	v_mfma_f32_16x16x32_bf16 v[44:47], v[126:129], v[198:201], v[44:47]
	v_mfma_f32_16x16x32_bf16 v[52:55], v[126:129], v[206:209], v[52:55]
	v_mfma_f32_16x16x32_bf16 v[56:59], v[170:173], v[206:209], v[56:59]
	v_mfma_f32_16x16x32_bf16 v[98:101], v[138:141], v[182:185], v[98:101]
	v_mfma_f32_16x16x32_bf16 v[32:35], v[174:177], v[182:185], v[32:35]
	v_mfma_f32_16x16x32_bf16 v[36:39], v[138:141], v[194:197], v[36:39]
	v_mfma_f32_16x16x32_bf16 v[40:43], v[174:177], v[194:197], v[40:43]
	v_mfma_f32_16x16x32_bf16 v[44:47], v[138:141], v[202:205], v[44:47]
	v_mfma_f32_16x16x32_bf16 v[48:51], v[170:173], v[198:201], v[48:51]
	v_mfma_f32_16x16x32_bf16 v[52:55], v[138:141], v[210:213], v[52:55]
	v_mfma_f32_16x16x32_bf16 v[56:59], v[174:177], v[210:213], v[56:59]
	v_mfma_f32_16x16x32_bf16 v[48:51], v[174:177], v[202:205], v[48:51]
	s_setprio 0
	s_barrier
	s_mov_b32 m0, s18
	s_add_u32 s44, s76, 0x18000
	ds_read_b128 v[178:181], v157 offset:49152
	ds_read_b128 v[182:185], v157 offset:50176
	ds_read_b128 v[190:193], v157 offset:51200
	ds_read_b128 v[194:197], v157 offset:52224
	ds_read_b128 v[198:201], v157 offset:53248
	ds_read_b128 v[202:205], v157 offset:54272
	ds_read_b128 v[206:209], v157 offset:55296
	ds_read_b128 v[210:213], v157 offset:56320
	global_load_lds_dwordx4 v134, s[76:77]
	s_mov_b32 m0, s35
	s_addc_u32 s45, s77, 0
	global_load_lds_dwordx4 v130, s[76:77]
	s_mov_b32 m0, s19
	s_nop 0
	global_load_lds_dwordx4 v134, s[44:45]
	s_mov_b32 m0, s84
	s_nop 0
	global_load_lds_dwordx4 v130, s[44:45]
	s_mov_b32 m0, s93
	s_nop 0
	global_load_lds_dwordx4 v136, s[42:43]
	s_mov_b32 m0, s94
	s_nop 0
	global_load_lds_dwordx4 v132, s[42:43]
	s_waitcnt vmcnt(8)
	s_waitcnt lgkmcnt(0)
	s_barrier
	s_setprio 1
	s_waitcnt lgkmcnt(0)
	v_mfma_f32_16x16x32_bf16 v[4:7], v[110:113], v[206:209], v[4:7]
	v_mfma_f32_16x16x32_bf16 v[8:11], v[118:121], v[206:209], v[8:11]
	v_mfma_f32_16x16x32_bf16 v[142:145], v[110:113], v[178:181], v[142:145]
	v_mfma_f32_16x16x32_bf16 v[146:149], v[118:121], v[178:181], v[146:149]
	v_mfma_f32_16x16x32_bf16 v[150:153], v[110:113], v[190:193], v[150:153]
	v_mfma_f32_16x16x32_bf16 v[158:161], v[118:121], v[190:193], v[158:161]
	v_mfma_f32_16x16x32_bf16 v[162:165], v[110:113], v[198:201], v[162:165]
	v_mfma_f32_16x16x32_bf16 v[166:169], v[118:121], v[198:201], v[166:169]
	v_mfma_f32_16x16x32_bf16 v[4:7], v[114:117], v[210:213], v[4:7]
	v_mfma_f32_16x16x32_bf16 v[8:11], v[122:125], v[210:213], v[8:11]
	v_mfma_f32_16x16x32_bf16 v[142:145], v[114:117], v[182:185], v[142:145]
	v_mfma_f32_16x16x32_bf16 v[146:149], v[122:125], v[182:185], v[146:149]
	v_mfma_f32_16x16x32_bf16 v[150:153], v[114:117], v[194:197], v[150:153]
	v_mfma_f32_16x16x32_bf16 v[158:161], v[122:125], v[194:197], v[158:161]
	v_mfma_f32_16x16x32_bf16 v[162:165], v[114:117], v[202:205], v[162:165]
	v_mfma_f32_16x16x32_bf16 v[166:169], v[122:125], v[202:205], v[166:169]
	v_mfma_f32_16x16x32_bf16 v[12:15], v[126:129], v[178:181], v[12:15]
	v_mfma_f32_16x16x32_bf16 v[24:27], v[170:173], v[178:181], v[24:27]
	v_mfma_f32_16x16x32_bf16 v[28:31], v[126:129], v[190:193], v[28:31]
	v_mfma_f32_16x16x32_bf16 v[60:63], v[170:173], v[190:193], v[60:63]
	v_mfma_f32_16x16x32_bf16 v[102:105], v[126:129], v[198:201], v[102:105]
	v_mfma_f32_16x16x32_bf16 v[106:109], v[170:173], v[198:201], v[106:109]
	v_mfma_f32_16x16x32_bf16 v[16:19], v[126:129], v[206:209], v[16:19]
	v_mfma_f32_16x16x32_bf16 v[20:23], v[170:173], v[206:209], v[20:23]
	v_mfma_f32_16x16x32_bf16 v[12:15], v[138:141], v[182:185], v[12:15]
	v_mfma_f32_16x16x32_bf16 v[24:27], v[174:177], v[182:185], v[24:27]
	v_mfma_f32_16x16x32_bf16 v[28:31], v[138:141], v[194:197], v[28:31]
	v_mfma_f32_16x16x32_bf16 v[60:63], v[174:177], v[194:197], v[60:63]
	v_mfma_f32_16x16x32_bf16 v[102:105], v[138:141], v[202:205], v[102:105]
	v_mfma_f32_16x16x32_bf16 v[106:109], v[174:177], v[202:205], v[106:109]
	v_mfma_f32_16x16x32_bf16 v[16:19], v[138:141], v[210:213], v[16:19]
	v_mfma_f32_16x16x32_bf16 v[20:23], v[174:177], v[210:213], v[20:23]
	s_setprio 0
	s_barrier
	s_add_u32 s76, s38, 0x80
	s_addc_u32 s77, s39, 0
	s_add_u32 s42, s68, 0x80
	s_addc_u32 s43, s69, 0
	ds_read_b128 v[110:113], v0
	ds_read_b128 v[114:117], v0 offset:1024
	ds_read_b128 v[118:121], v0 offset:2048
	ds_read_b128 v[122:125], v0 offset:3072
	ds_read_b128 v[126:129], v1
	ds_read_b128 v[138:141], v1 offset:1024
	ds_read_b128 v[170:173], v1 offset:2048
	ds_read_b128 v[174:177], v1 offset:3072
	s_add_u32 s44, s78, 0x18000
	s_addc_u32 s45, s79, 0
	s_mov_b32 m0, s88
	ds_read_b128 v[178:181], v157
	ds_read_b128 v[182:185], v157 offset:1024
	ds_read_b128 v[190:193], v157 offset:2048
	ds_read_b128 v[194:197], v157 offset:3072
	ds_read_b128 v[198:201], v157 offset:4096
	ds_read_b128 v[202:205], v157 offset:5120
	ds_read_b128 v[206:209], v157 offset:6144
	ds_read_b128 v[210:213], v157 offset:7168
	global_load_lds_dwordx4 v136, s[44:45]
	s_mov_b32 m0, vcc_lo
	s_nop 0
	global_load_lds_dwordx4 v132, s[44:45]
	s_waitcnt vmcnt(8)
	s_waitcnt lgkmcnt(0)
	s_barrier
	s_setprio 1
	s_waitcnt lgkmcnt(0)
	v_mfma_f32_16x16x32_bf16 v[88:91], v[110:113], v[206:209], v[88:91]
	v_mfma_f32_16x16x32_bf16 v[64:67], v[110:113], v[178:181], v[64:67]
	v_mfma_f32_16x16x32_bf16 v[68:71], v[118:121], v[178:181], v[68:71]
	v_mfma_f32_16x16x32_bf16 v[72:75], v[110:113], v[190:193], v[72:75]
	v_mfma_f32_16x16x32_bf16 v[76:79], v[118:121], v[190:193], v[76:79]
	v_mfma_f32_16x16x32_bf16 v[80:83], v[110:113], v[198:201], v[80:83]
	v_mfma_f32_16x16x32_bf16 v[84:87], v[118:121], v[198:201], v[84:87]
	v_mfma_f32_16x16x32_bf16 v[220:223], v[114:117], v[210:213], v[88:91]
	v_mfma_f32_16x16x32_bf16 v[88:91], v[118:121], v[206:209], v[92:95]
	v_mfma_f32_16x16x32_bf16 v[64:67], v[114:117], v[182:185], v[64:67]
	v_mfma_f32_16x16x32_bf16 v[68:71], v[122:125], v[182:185], v[68:71]
	v_mfma_f32_16x16x32_bf16 v[72:75], v[114:117], v[194:197], v[72:75]
	v_mfma_f32_16x16x32_bf16 v[76:79], v[122:125], v[194:197], v[76:79]
	v_mfma_f32_16x16x32_bf16 v[80:83], v[114:117], v[202:205], v[80:83]
	v_mfma_f32_16x16x32_bf16 v[84:87], v[122:125], v[202:205], v[84:87]
	v_mfma_f32_16x16x32_bf16 v[92:95], v[122:125], v[210:213], v[88:91]
	v_mfma_f32_16x16x32_bf16 v[48:51], v[170:173], v[198:201], v[48:51]
	v_mfma_f32_16x16x32_bf16 v[88:91], v[126:129], v[178:181], v[98:101]
	v_mfma_f32_16x16x32_bf16 v[32:35], v[170:173], v[178:181], v[32:35]
	v_mfma_f32_16x16x32_bf16 v[36:39], v[126:129], v[190:193], v[36:39]
	v_mfma_f32_16x16x32_bf16 v[40:43], v[170:173], v[190:193], v[40:43]
	v_mfma_f32_16x16x32_bf16 v[44:47], v[126:129], v[198:201], v[44:47]
	v_mfma_f32_16x16x32_bf16 v[178:181], v[174:177], v[202:205], v[48:51]
	v_mfma_f32_16x16x32_bf16 v[48:51], v[126:129], v[206:209], v[52:55]
	v_mfma_f32_16x16x32_bf16 v[32:35], v[174:177], v[182:185], v[32:35]
	v_mfma_f32_16x16x32_bf16 v[36:39], v[138:141], v[194:197], v[36:39]
	v_mfma_f32_16x16x32_bf16 v[40:43], v[174:177], v[194:197], v[40:43]
	v_mfma_f32_16x16x32_bf16 v[44:47], v[138:141], v[202:205], v[44:47]
	v_mfma_f32_16x16x32_bf16 v[52:55], v[138:141], v[210:213], v[48:51]
	v_mfma_f32_16x16x32_bf16 v[48:51], v[170:173], v[206:209], v[56:59]
	v_mfma_f32_16x16x32_bf16 v[224:227], v[138:141], v[182:185], v[88:91]
	v_mfma_f32_16x16x32_bf16 v[182:185], v[174:177], v[210:213], v[48:51]
	s_setprio 0
	s_barrier
	s_mov_b32 m0, vcc_hi
	s_add_u32 s44, s68, 0x18000
	s_nop 0
	ds_read_b128 v[48:51], v157 offset:16384
	ds_read_b128 v[56:59], v157 offset:17408
	ds_read_b128 v[88:91], v157 offset:18432
	ds_read_b128 v[98:101], v157 offset:19456
	ds_read_b128 v[190:193], v157 offset:20480
	ds_read_b128 v[194:197], v157 offset:21504
	ds_read_b128 v[198:201], v157 offset:22528
	ds_read_b128 v[202:205], v157 offset:23552
	global_load_lds_dwordx4 v134, s[68:69]
	s_mov_b32 m0, s70
	s_addc_u32 s45, s69, 0
	global_load_lds_dwordx4 v130, s[68:69]
	s_mov_b32 m0, s22
	s_nop 0
	global_load_lds_dwordx4 v134, s[44:45]
	s_mov_b32 m0, s23
	s_nop 0
	global_load_lds_dwordx4 v130, s[44:45]
	s_mov_b32 m0, s49
	s_nop 0
	global_load_lds_dwordx4 v136, s[38:39]
	s_mov_b32 m0, s89
	s_nop 0
	global_load_lds_dwordx4 v132, s[38:39]
	s_waitcnt vmcnt(8)
	s_waitcnt lgkmcnt(0)
	s_barrier
	s_setprio 1
	s_waitcnt lgkmcnt(0)
	v_mfma_f32_16x16x32_bf16 v[4:7], v[110:113], v[198:201], v[4:7]
	v_mfma_f32_16x16x32_bf16 v[142:145], v[110:113], v[48:51], v[142:145]
	v_mfma_f32_16x16x32_bf16 v[146:149], v[118:121], v[48:51], v[146:149]
	v_mfma_f32_16x16x32_bf16 v[150:153], v[110:113], v[88:91], v[150:153]
	v_mfma_f32_16x16x32_bf16 v[158:161], v[118:121], v[88:91], v[158:161]
	v_mfma_f32_16x16x32_bf16 v[162:165], v[110:113], v[190:193], v[162:165]
	v_mfma_f32_16x16x32_bf16 v[166:169], v[118:121], v[190:193], v[166:169]
	v_mfma_f32_16x16x32_bf16 v[4:7], v[114:117], v[202:205], v[4:7]
	v_mfma_f32_16x16x32_bf16 v[8:11], v[118:121], v[198:201], v[8:11]
	v_mfma_f32_16x16x32_bf16 v[142:145], v[114:117], v[56:59], v[142:145]
	v_mfma_f32_16x16x32_bf16 v[146:149], v[122:125], v[56:59], v[146:149]
	v_mfma_f32_16x16x32_bf16 v[150:153], v[114:117], v[98:101], v[150:153]
	v_mfma_f32_16x16x32_bf16 v[158:161], v[122:125], v[98:101], v[158:161]
	v_mfma_f32_16x16x32_bf16 v[162:165], v[114:117], v[194:197], v[162:165]
	v_mfma_f32_16x16x32_bf16 v[166:169], v[122:125], v[194:197], v[166:169]
	v_mfma_f32_16x16x32_bf16 v[206:209], v[122:125], v[202:205], v[8:11]
	v_mfma_f32_16x16x32_bf16 v[8:11], v[126:129], v[48:51], v[12:15]
	v_mfma_f32_16x16x32_bf16 v[12:15], v[138:141], v[56:59], v[8:11]
	v_mfma_f32_16x16x32_bf16 v[8:11], v[170:173], v[48:51], v[24:27]
	v_mfma_f32_16x16x32_bf16 v[210:213], v[174:177], v[56:59], v[8:11]
	v_mfma_f32_16x16x32_bf16 v[8:11], v[126:129], v[88:91], v[28:31]
	v_mfma_f32_16x16x32_bf16 v[28:31], v[138:141], v[98:101], v[8:11]
	v_mfma_f32_16x16x32_bf16 v[8:11], v[170:173], v[88:91], v[60:63]
	v_mfma_f32_16x16x32_bf16 v[228:231], v[174:177], v[98:101], v[8:11]
	v_mfma_f32_16x16x32_bf16 v[8:11], v[126:129], v[190:193], v[102:105]
	v_mfma_f32_16x16x32_bf16 v[232:235], v[138:141], v[194:197], v[8:11]
	v_mfma_f32_16x16x32_bf16 v[8:11], v[170:173], v[190:193], v[106:109]
	v_mfma_f32_16x16x32_bf16 v[190:193], v[174:177], v[194:197], v[8:11]
	v_mfma_f32_16x16x32_bf16 v[8:11], v[126:129], v[198:201], v[16:19]
	v_mfma_f32_16x16x32_bf16 v[138:141], v[138:141], v[202:205], v[8:11]
	v_mfma_f32_16x16x32_bf16 v[8:11], v[170:173], v[198:201], v[20:23]
	v_mfma_f32_16x16x32_bf16 v[170:173], v[174:177], v[202:205], v[8:11]
	s_setprio 0
	s_barrier
	s_nop 4
	ds_read_b128 v[8:11], v2
	ds_read_b128 v[20:23], v2 offset:1024
	ds_read_b128 v[174:177], v2 offset:2048
	ds_read_b128 v[194:197], v2 offset:3072
	ds_read_b128 v[198:201], v3
	ds_read_b128 v[202:205], v3 offset:1024
	ds_read_b128 v[236:239], v3 offset:2048
	ds_read_b128 v[240:243], v3 offset:3072
	s_add_u32 s22, s38, 0x18000
	s_addc_u32 s23, s39, 0
	s_mov_b32 m0, s90
	ds_read_b128 v[0:3], v157 offset:32768
	ds_read_b128 v[16:19], v157 offset:33792
	ds_read_b128 v[24:27], v157 offset:34816
	ds_read_b128 v[60:63], v157 offset:35840
	ds_read_b128 v[244:247], v157 offset:36864
	ds_read_b128 v[248:251], v157 offset:37888
	ds_read_b128 v[186:189], v157 offset:38912
	ds_read_b128 v[48:51], v157 offset:39936
	global_load_lds_dwordx4 v136, s[22:23]
	s_mov_b32 m0, s91
	s_nop 0
	global_load_lds_dwordx4 v132, s[22:23]
	s_waitcnt vmcnt(8)
	s_waitcnt lgkmcnt(0)
	s_barrier
	s_setprio 1
	s_waitcnt lgkmcnt(0)
	v_mfma_f32_16x16x32_bf16 v[56:59], v[8:11], v[0:3], v[64:67]
	v_mfma_f32_16x16x32_bf16 v[122:125], v[20:23], v[16:19], v[56:59]
	v_mfma_f32_16x16x32_bf16 v[56:59], v[174:177], v[0:3], v[68:71]
	v_mfma_f32_16x16x32_bf16 v[114:117], v[194:197], v[16:19], v[56:59]
	v_mfma_f32_16x16x32_bf16 v[56:59], v[8:11], v[24:27], v[72:75]
	v_mfma_f32_16x16x32_bf16 v[106:109], v[20:23], v[60:63], v[56:59]
	v_mfma_f32_16x16x32_bf16 v[56:59], v[174:177], v[24:27], v[76:79]
	v_mfma_f32_16x16x32_bf16 v[98:101], v[194:197], v[60:63], v[56:59]
	v_mfma_f32_16x16x32_bf16 v[56:59], v[8:11], v[244:247], v[80:83]
	v_mfma_f32_16x16x32_bf16 v[88:91], v[20:23], v[248:251], v[56:59]
	v_mfma_f32_16x16x32_bf16 v[56:59], v[174:177], v[244:247], v[84:87]
	v_mfma_f32_16x16x32_bf16 v[80:83], v[194:197], v[248:251], v[56:59]
	v_mfma_f32_16x16x32_bf16 v[56:59], v[8:11], v[186:189], v[220:223]
	v_mfma_f32_16x16x32_bf16 v[64:67], v[174:177], v[186:189], v[92:95]
	v_mfma_f32_16x16x32_bf16 v[56:59], v[20:23], v[48:51], v[56:59]
	v_mfma_f32_16x16x32_bf16 v[220:223], v[194:197], v[48:51], v[64:67]
	v_mfma_f32_16x16x32_bf16 v[64:67], v[198:201], v[0:3], v[224:227]
	v_mfma_f32_16x16x32_bf16 v[0:3], v[236:239], v[0:3], v[32:35]
	v_mfma_f32_16x16x32_bf16 v[118:121], v[240:243], v[16:19], v[0:3]
	v_mfma_f32_16x16x32_bf16 v[0:3], v[198:201], v[24:27], v[36:39]
	v_mfma_f32_16x16x32_bf16 v[110:113], v[202:205], v[60:63], v[0:3]
	v_mfma_f32_16x16x32_bf16 v[0:3], v[236:239], v[24:27], v[40:43]
	v_mfma_f32_16x16x32_bf16 v[102:105], v[240:243], v[60:63], v[0:3]
	v_mfma_f32_16x16x32_bf16 v[0:3], v[198:201], v[244:247], v[44:47]
	v_mfma_f32_16x16x32_bf16 v[92:95], v[202:205], v[248:251], v[0:3]
	v_mfma_f32_16x16x32_bf16 v[0:3], v[236:239], v[244:247], v[178:181]
	v_mfma_f32_16x16x32_bf16 v[84:87], v[240:243], v[248:251], v[0:3]
	v_mfma_f32_16x16x32_bf16 v[0:3], v[198:201], v[186:189], v[52:55]
	v_mfma_f32_16x16x32_bf16 v[60:63], v[202:205], v[48:51], v[0:3]
	v_mfma_f32_16x16x32_bf16 v[0:3], v[236:239], v[186:189], v[182:185]
	v_mfma_f32_16x16x32_bf16 v[126:129], v[202:205], v[16:19], v[64:67]
	v_mfma_f32_16x16x32_bf16 v[52:55], v[240:243], v[48:51], v[0:3]
	s_setprio 0
	s_barrier
	s_mov_b32 m0, s18
	s_nop 2
	s_add_u32 s22, s42, 0x18000
	ds_read_b128 v[36:39], v157 offset:49152
	ds_read_b128 v[44:47], v157 offset:50176
	ds_read_b128 v[48:51], v157 offset:51200
	ds_read_b128 v[178:181], v157 offset:52224
	ds_read_b128 v[182:185], v157 offset:53248
	ds_read_b128 v[186:189], v157 offset:54272
	ds_read_b128 v[224:227], v157 offset:55296
	ds_read_b128 v[244:247], v157 offset:56320
	global_load_lds_dwordx4 v134, s[42:43]
	s_mov_b32 m0, s35
	s_addc_u32 s23, s43, 0
	global_load_lds_dwordx4 v130, s[42:43]
	s_mov_b32 m0, s19
	s_nop 0
	global_load_lds_dwordx4 v134, s[22:23]
	s_mov_b32 m0, s84
	s_nop 0
	global_load_lds_dwordx4 v130, s[22:23]
	s_mov_b32 m0, s93
	s_nop 0
	global_load_lds_dwordx4 v136, s[76:77]
	s_mov_b32 m0, s94
	s_nop 0
	global_load_lds_dwordx4 v132, s[76:77]
	s_waitcnt vmcnt(8)
	s_waitcnt lgkmcnt(0)
	s_barrier
	s_setprio 1
	s_waitcnt lgkmcnt(0)
	v_mfma_f32_16x16x32_bf16 v[0:3], v[8:11], v[36:39], v[142:145]
	v_mfma_f32_16x16x32_bf16 v[72:75], v[20:23], v[44:47], v[0:3]
	v_mfma_f32_16x16x32_bf16 v[0:3], v[174:177], v[36:39], v[146:149]
	v_mfma_f32_16x16x32_bf16 v[64:67], v[194:197], v[44:47], v[0:3]
	v_mfma_f32_16x16x32_bf16 v[0:3], v[8:11], v[48:51], v[150:153]
	v_mfma_f32_16x16x32_bf16 v[40:43], v[20:23], v[178:181], v[0:3]
	v_mfma_f32_16x16x32_bf16 v[0:3], v[174:177], v[48:51], v[158:161]
	v_mfma_f32_16x16x32_bf16 v[32:35], v[194:197], v[178:181], v[0:3]
	v_mfma_f32_16x16x32_bf16 v[0:3], v[8:11], v[182:185], v[162:165]
	v_mfma_f32_16x16x32_bf16 v[24:27], v[20:23], v[186:189], v[0:3]
	v_mfma_f32_16x16x32_bf16 v[0:3], v[174:177], v[182:185], v[166:169]
	v_mfma_f32_16x16x32_bf16 v[16:19], v[194:197], v[186:189], v[0:3]
	v_mfma_f32_16x16x32_bf16 v[0:3], v[8:11], v[224:227], v[4:7]
	v_mfma_f32_16x16x32_bf16 v[8:11], v[20:23], v[244:247], v[0:3]
	v_mfma_f32_16x16x32_bf16 v[0:3], v[174:177], v[224:227], v[206:209]
	v_mfma_f32_16x16x32_bf16 v[0:3], v[194:197], v[244:247], v[0:3]
	v_mfma_f32_16x16x32_bf16 v[4:7], v[198:201], v[36:39], v[12:15]
	v_mfma_f32_16x16x32_bf16 v[76:79], v[202:205], v[44:47], v[4:7]
	v_mfma_f32_16x16x32_bf16 v[4:7], v[236:239], v[36:39], v[210:213]
	v_mfma_f32_16x16x32_bf16 v[68:71], v[240:243], v[44:47], v[4:7]
	v_mfma_f32_16x16x32_bf16 v[4:7], v[198:201], v[48:51], v[28:31]
	v_mfma_f32_16x16x32_bf16 v[44:47], v[202:205], v[178:181], v[4:7]
	v_mfma_f32_16x16x32_bf16 v[4:7], v[236:239], v[48:51], v[228:231]
	v_mfma_f32_16x16x32_bf16 v[36:39], v[240:243], v[178:181], v[4:7]
	v_mfma_f32_16x16x32_bf16 v[4:7], v[198:201], v[182:185], v[232:235]
	v_mfma_f32_16x16x32_bf16 v[28:31], v[202:205], v[186:189], v[4:7]
	v_mfma_f32_16x16x32_bf16 v[4:7], v[236:239], v[182:185], v[190:193]
	v_mfma_f32_16x16x32_bf16 v[20:23], v[240:243], v[186:189], v[4:7]
	v_mfma_f32_16x16x32_bf16 v[4:7], v[198:201], v[224:227], v[138:141]
	v_mfma_f32_16x16x32_bf16 v[12:15], v[202:205], v[244:247], v[4:7]
	v_mfma_f32_16x16x32_bf16 v[4:7], v[236:239], v[224:227], v[170:173]
	v_mfma_f32_16x16x32_bf16 v[4:7], v[240:243], v[244:247], v[4:7]
	s_setprio 0
	s_barrier
	s_andn2_b64 vcc, exec, s[62:63]
	s_cbranch_vccnz .LBB0_385
	s_barrier

.LBB0_400:
	v_and_b32_e32 v9, 48, v8
	v_lshlrev_b32_e32 v10, 6, v8
	s_movk_i32 s22, 0x3c0
	v_lshlrev_b32_e32 v8, 2, v8
	s_sext_i32_i8 s89, s6
	s_and_b32 s6, s20, 3
	s_lshl_b32 s20, s7, 13
	v_and_or_b32 v9, v10, s22, v9
	v_and_b32_e32 v8, 32, v8
	s_lshl_b32 s75, s7, 6
	v_bitop3_b32 v10, v9, s20, v8 bitop3:0xde
	s_lshl_b32 s82, s6, 5
	s_lshl_b32 s20, s6, 12
	s_add_u32 s22, s10, 0x7400000
	s_addc_u32 s23, s11, 0
	s_add_u32 s28, s10, 0xdd00000
	s_addc_u32 s29, s11, 0
	s_add_u32 s83, s10, 0x11d00000
	s_addc_u32 s84, s11, 0
	s_add_i32 m0, s67, 0x18000
	v_lshl_add_u64 v[6:7], v[6:7], 0, s[26:27]
	s_waitcnt vmcnt(2)
	s_barrier
	global_load_lds_dwordx4 v[6:7], off
	v_lshl_add_u64 v[4:5], v[4:5], 0, s[26:27]
	s_add_i32 m0, s67, 0x1a000
	s_add_i32 s85, s67, 0x8000
	s_add_i32 s86, s67, 0xa000
	global_load_lds_dwordx4 v[4:5], off
	v_lshl_add_u64 v[0:1], v[0:1], 0, s[26:27]
	s_mov_b32 m0, s85
	s_add_u32 s10, s76, 0x10080
	global_load_lds_dwordx4 v[0:1], off
	v_lshl_add_u64 v[0:1], v[2:3], 0, s[26:27]
	s_mov_b32 m0, s86
	s_addc_u32 s11, s77, 0
	global_load_lds_dwordx4 v[0:1], off
	s_add_i32 m0, s67, 0x1c000
	s_nop 0
	global_load_lds_dwordx4 v132, s[10:11]
	s_add_i32 m0, s67, 0x1e000
	s_cmpk_lt_u32 s19, 0x100
	global_load_lds_dwordx4 v136, s[10:11]
	s_cselect_b64 s[10:11], -1, 0
	s_lshl_b32 s7, s7, 2
	s_or_b32 s6, s7, s6
	s_mulk_i32 s6, 0xb00
	s_add_i32 s88, s6, 0
	s_waitcnt vmcnt(6)
	s_ashr_i32 s87, s2, 31
	s_add_i32 s88, s88, 0x20100
	s_add_u32 s30, s2, s33
	v_bitop3_b32 v139, v9, s20, v8 bitop3:0xde
	s_addc_u32 s31, s87, s18
	v_add_u32_e32 v141, 0, v10
	s_barrier
	s_branch .LBB0_403

.LBB0_409:
	s_ashr_i32 s61, s60, 31
	s_lshl_b64 s[18:19], s[60:61], 17
	s_add_u32 s62, s47, s18
	s_addc_u32 s63, s71, s19
	s_and_b64 s[18:19], s[6:7], exec
	s_cselect_b32 s39, s63, s79
	s_cselect_b32 s38, s62, s78
	s_ashr_i32 s59, s58, 31
	s_lshl_b64 s[18:19], s[58:59], 17
	s_add_u32 s64, s14, s18
	s_addc_u32 s65, s16, s19
	s_and_b64 s[18:19], s[6:7], exec
	s_cselect_b32 s69, s65, s77
	s_cselect_b32 s68, s64, s76
	s_add_u32 s18, s78, 0x80
	s_addc_u32 s19, s79, 0
	s_add_u32 s42, s78, 0x100
	s_addc_u32 s43, s79, 0
	s_add_u32 s44, s76, 0x100
	s_addc_u32 s45, s77, 0
	s_add_u32 s78, s78, 0x180
	s_addc_u32 s79, s79, 0
	s_add_u32 s80, s76, 0x180
	s_addc_u32 s81, s77, 0
	s_add_i32 s49, 0, 0x10000
	s_add_i32 s20, 0, 0x14000
	s_mov_b64 s[76:77], s[78:79]
	v_add_u32_e32 v96, s49, v139
	v_add_u32_e32 v138, s20, v139
	ds_read_b128 v[0:3], v96
	ds_read_b128 v[4:7], v96 offset:1024
	ds_read_b128 v[8:11], v96 offset:2048
	ds_read_b128 v[12:15], v96 offset:3072
	ds_read_b128 v[16:19], v138
	ds_read_b128 v[20:23], v138 offset:1024
	ds_read_b128 v[24:27], v138 offset:2048
	ds_read_b128 v[28:31], v138 offset:3072
	s_add_u32 s18, s18, 0x10000
	s_addc_u32 s19, s19, 0
	s_add_i32 s59, s67, 0xc000
	s_mov_b32 m0, s59
	ds_read_b128 v[32:35], v141
	ds_read_b128 v[36:39], v141 offset:1024
	ds_read_b128 v[40:43], v141 offset:2048
	ds_read_b128 v[44:47], v141 offset:3072
	ds_read_b128 v[48:51], v141 offset:4096
	ds_read_b128 v[52:55], v141 offset:5120
	ds_read_b128 v[56:59], v141 offset:6144
	ds_read_b128 v[60:63], v141 offset:7168
	global_load_lds_dwordx4 v130, s[18:19]
	v_lshl_add_u64 v[64:65], s[18:19], 0, v[134:135]
	s_add_i32 s18, s67, 0xe000
	s_mov_b32 m0, s18
	s_nop 0
	global_load_lds_dwordx4 v[64:65], off
	s_waitcnt vmcnt(8)
	s_waitcnt lgkmcnt(0)
	s_barrier
	s_setprio 1
	s_waitcnt lgkmcnt(0)
	v_mfma_f32_16x16x32_bf16 v[64:67], v[0:3], v[32:35], 0
	v_mfma_f32_16x16x32_bf16 v[68:71], v[8:11], v[32:35], 0
	v_mfma_f32_16x16x32_bf16 v[72:75], v[0:3], v[40:43], 0
	v_mfma_f32_16x16x32_bf16 v[76:79], v[8:11], v[40:43], 0
	v_mfma_f32_16x16x32_bf16 v[80:83], v[0:3], v[48:51], 0
	v_mfma_f32_16x16x32_bf16 v[84:87], v[8:11], v[48:51], 0
	v_mfma_f32_16x16x32_bf16 v[88:91], v[0:3], v[56:59], 0
	v_mfma_f32_16x16x32_bf16 v[92:95], v[8:11], v[56:59], 0
	v_mfma_f32_16x16x32_bf16 v[64:67], v[4:7], v[36:39], v[64:67]
	v_mfma_f32_16x16x32_bf16 v[68:71], v[12:15], v[36:39], v[68:71]
	v_mfma_f32_16x16x32_bf16 v[72:75], v[4:7], v[44:47], v[72:75]
	v_mfma_f32_16x16x32_bf16 v[76:79], v[12:15], v[44:47], v[76:79]
	v_mfma_f32_16x16x32_bf16 v[80:83], v[4:7], v[52:55], v[80:83]
	v_mfma_f32_16x16x32_bf16 v[84:87], v[12:15], v[52:55], v[84:87]
	v_mfma_f32_16x16x32_bf16 v[88:91], v[4:7], v[60:63], v[88:91]
	v_mfma_f32_16x16x32_bf16 v[92:95], v[12:15], v[60:63], v[92:95]
	v_mfma_f32_16x16x32_bf16 v[98:101], v[16:19], v[32:35], 0
	v_mfma_f32_16x16x32_bf16 v[32:35], v[24:27], v[32:35], 0
	v_mfma_f32_16x16x32_bf16 v[98:101], v[20:23], v[36:39], v[98:101]
	v_mfma_f32_16x16x32_bf16 v[32:35], v[28:31], v[36:39], v[32:35]
	v_mfma_f32_16x16x32_bf16 v[36:39], v[16:19], v[40:43], 0
	v_mfma_f32_16x16x32_bf16 v[40:43], v[24:27], v[40:43], 0
	v_mfma_f32_16x16x32_bf16 v[36:39], v[20:23], v[44:47], v[36:39]
	v_mfma_f32_16x16x32_bf16 v[40:43], v[28:31], v[44:47], v[40:43]
	v_mfma_f32_16x16x32_bf16 v[44:47], v[16:19], v[48:51], 0
	v_mfma_f32_16x16x32_bf16 v[48:51], v[24:27], v[48:51], 0
	v_mfma_f32_16x16x32_bf16 v[44:47], v[20:23], v[52:55], v[44:47]
	v_mfma_f32_16x16x32_bf16 v[48:51], v[28:31], v[52:55], v[48:51]
	v_mfma_f32_16x16x32_bf16 v[52:55], v[16:19], v[56:59], 0
	v_mfma_f32_16x16x32_bf16 v[56:59], v[24:27], v[56:59], 0
	v_mfma_f32_16x16x32_bf16 v[52:55], v[20:23], v[60:63], v[52:55]
	v_mfma_f32_16x16x32_bf16 v[56:59], v[28:31], v[60:63], v[56:59]
	s_setprio 0
	s_barrier
	s_add_i32 s49, s49, s46
	s_mov_b32 m0, s49
	s_add_i32 s19, s49, 0x2000
	ds_read_b128 v[60:63], v141 offset:16384
	ds_read_b128 v[102:105], v141 offset:17408
	ds_read_b128 v[106:109], v141 offset:18432
	ds_read_b128 v[110:113], v141 offset:19456
	ds_read_b128 v[114:117], v141 offset:20480
	ds_read_b128 v[118:121], v141 offset:21504
	ds_read_b128 v[122:125], v141 offset:22528
	ds_read_b128 v[126:129], v141 offset:23552
	global_load_lds_dwordx4 v132, s[44:45]
	v_lshl_add_u64 v[142:143], s[44:45], 0, v[136:137]
	s_add_u32 s44, s44, 0x10000
	s_mov_b32 m0, s19
	s_addc_u32 s45, s45, 0
	s_add_i32 s20, s20, s46
	global_load_lds_dwordx4 v[142:143], off
	s_mov_b32 m0, s20
	s_add_i32 s33, s20, 0x2000
	global_load_lds_dwordx4 v132, s[44:45]
	s_mov_b32 m0, s33
	s_nop 0
	global_load_lds_dwordx4 v136, s[44:45]
	s_mov_b32 m0, s67
	s_nop 0
	global_load_lds_dwordx4 v130, s[42:43]
	s_mov_b32 m0, s72
	s_nop 0
	global_load_lds_dwordx4 v134, s[42:43]
	s_waitcnt vmcnt(8)
	s_waitcnt lgkmcnt(0)
	s_barrier
	s_setprio 1
	s_waitcnt lgkmcnt(0)
	v_mfma_f32_16x16x32_bf16 v[142:145], v[0:3], v[60:63], 0
	v_mfma_f32_16x16x32_bf16 v[150:153], v[0:3], v[106:109], 0
	v_mfma_f32_16x16x32_bf16 v[158:161], v[0:3], v[114:117], 0
	v_mfma_f32_16x16x32_bf16 v[0:3], v[0:3], v[122:125], 0
	v_mfma_f32_16x16x32_bf16 v[142:145], v[4:7], v[102:105], v[142:145]
	v_mfma_f32_16x16x32_bf16 v[150:153], v[4:7], v[110:113], v[150:153]
	v_mfma_f32_16x16x32_bf16 v[158:161], v[4:7], v[118:121], v[158:161]
	v_mfma_f32_16x16x32_bf16 v[0:3], v[4:7], v[126:129], v[0:3]
	v_mfma_f32_16x16x32_bf16 v[4:7], v[8:11], v[122:125], 0
	v_mfma_f32_16x16x32_bf16 v[146:149], v[8:11], v[60:63], 0
	v_mfma_f32_16x16x32_bf16 v[154:157], v[8:11], v[106:109], 0
	v_mfma_f32_16x16x32_bf16 v[162:165], v[8:11], v[114:117], 0
	v_mfma_f32_16x16x32_bf16 v[4:7], v[12:15], v[126:129], v[4:7]
	v_mfma_f32_16x16x32_bf16 v[146:149], v[12:15], v[102:105], v[146:149]
	v_mfma_f32_16x16x32_bf16 v[154:157], v[12:15], v[110:113], v[154:157]
	v_mfma_f32_16x16x32_bf16 v[162:165], v[12:15], v[118:121], v[162:165]
	v_mfma_f32_16x16x32_bf16 v[8:11], v[16:19], v[60:63], 0
	v_mfma_f32_16x16x32_bf16 v[12:15], v[24:27], v[60:63], 0
	v_mfma_f32_16x16x32_bf16 v[8:11], v[20:23], v[102:105], v[8:11]
	v_mfma_f32_16x16x32_bf16 v[12:15], v[28:31], v[102:105], v[12:15]
	v_mfma_f32_16x16x32_bf16 v[60:63], v[16:19], v[106:109], 0
	v_mfma_f32_16x16x32_bf16 v[102:105], v[24:27], v[106:109], 0
	v_mfma_f32_16x16x32_bf16 v[106:109], v[16:19], v[114:117], 0
	v_mfma_f32_16x16x32_bf16 v[16:19], v[16:19], v[122:125], 0
	v_mfma_f32_16x16x32_bf16 v[60:63], v[20:23], v[110:113], v[60:63]
	v_mfma_f32_16x16x32_bf16 v[102:105], v[28:31], v[110:113], v[102:105]
	v_mfma_f32_16x16x32_bf16 v[106:109], v[20:23], v[118:121], v[106:109]
	v_mfma_f32_16x16x32_bf16 v[110:113], v[24:27], v[114:117], 0
	v_mfma_f32_16x16x32_bf16 v[16:19], v[20:23], v[126:129], v[16:19]
	v_mfma_f32_16x16x32_bf16 v[20:23], v[24:27], v[122:125], 0
	v_mfma_f32_16x16x32_bf16 v[110:113], v[28:31], v[118:121], v[110:113]
	v_mfma_f32_16x16x32_bf16 v[20:23], v[28:31], v[126:129], v[20:23]
	s_setprio 0
	s_barrier
	s_add_i32 s61, 0, 0x18000
	s_add_i32 s44, 0, 0x1c000
	v_add_u32_e32 v140, s61, v139
	v_add_u32_e32 v236, s44, v139
	ds_read_b128 v[24:27], v140
	ds_read_b128 v[28:31], v140 offset:1024
	ds_read_b128 v[114:117], v140 offset:2048
	ds_read_b128 v[118:121], v140 offset:3072
	ds_read_b128 v[122:125], v236
	ds_read_b128 v[126:129], v236 offset:1024
	ds_read_b128 v[166:169], v236 offset:2048
	ds_read_b128 v[170:173], v236 offset:3072
	s_add_u32 s42, s42, 0x10000
	s_addc_u32 s43, s43, 0
	s_mov_b32 m0, s73
	ds_read_b128 v[174:177], v141 offset:32768
	ds_read_b128 v[178:181], v141 offset:33792
	ds_read_b128 v[182:185], v141 offset:34816
	ds_read_b128 v[186:189], v141 offset:35840
	ds_read_b128 v[190:193], v141 offset:36864
	ds_read_b128 v[194:197], v141 offset:37888
	ds_read_b128 v[198:201], v141 offset:38912
	ds_read_b128 v[202:205], v141 offset:39936
	global_load_lds_dwordx4 v130, s[42:43]
	s_mov_b32 m0, s74
	s_nop 0
	global_load_lds_dwordx4 v134, s[42:43]
	s_waitcnt vmcnt(8)
	s_waitcnt lgkmcnt(0)
	s_barrier
	s_setprio 1
	s_waitcnt lgkmcnt(0)
	v_mfma_f32_16x16x32_bf16 v[64:67], v[24:27], v[174:177], v[64:67]
	v_mfma_f32_16x16x32_bf16 v[68:71], v[114:117], v[174:177], v[68:71]
	v_mfma_f32_16x16x32_bf16 v[72:75], v[24:27], v[182:185], v[72:75]
	v_mfma_f32_16x16x32_bf16 v[76:79], v[114:117], v[182:185], v[76:79]
	v_mfma_f32_16x16x32_bf16 v[80:83], v[24:27], v[190:193], v[80:83]
	v_mfma_f32_16x16x32_bf16 v[84:87], v[114:117], v[190:193], v[84:87]
	v_mfma_f32_16x16x32_bf16 v[88:91], v[24:27], v[198:201], v[88:91]
	v_mfma_f32_16x16x32_bf16 v[92:95], v[114:117], v[198:201], v[92:95]
	v_mfma_f32_16x16x32_bf16 v[64:67], v[28:31], v[178:181], v[64:67]
	v_mfma_f32_16x16x32_bf16 v[68:71], v[118:121], v[178:181], v[68:71]
	v_mfma_f32_16x16x32_bf16 v[72:75], v[28:31], v[186:189], v[72:75]
	v_mfma_f32_16x16x32_bf16 v[76:79], v[118:121], v[186:189], v[76:79]
	v_mfma_f32_16x16x32_bf16 v[80:83], v[28:31], v[194:197], v[80:83]
	v_mfma_f32_16x16x32_bf16 v[84:87], v[118:121], v[194:197], v[84:87]
	v_mfma_f32_16x16x32_bf16 v[88:91], v[28:31], v[202:205], v[88:91]
	v_mfma_f32_16x16x32_bf16 v[92:95], v[118:121], v[202:205], v[92:95]
	v_mfma_f32_16x16x32_bf16 v[98:101], v[122:125], v[174:177], v[98:101]
	v_mfma_f32_16x16x32_bf16 v[32:35], v[166:169], v[174:177], v[32:35]
	v_mfma_f32_16x16x32_bf16 v[36:39], v[122:125], v[182:185], v[36:39]
	v_mfma_f32_16x16x32_bf16 v[40:43], v[166:169], v[182:185], v[40:43]
	v_mfma_f32_16x16x32_bf16 v[44:47], v[122:125], v[190:193], v[44:47]
	v_mfma_f32_16x16x32_bf16 v[48:51], v[166:169], v[190:193], v[48:51]
	v_mfma_f32_16x16x32_bf16 v[52:55], v[122:125], v[198:201], v[52:55]
	v_mfma_f32_16x16x32_bf16 v[56:59], v[166:169], v[198:201], v[56:59]
	v_mfma_f32_16x16x32_bf16 v[98:101], v[126:129], v[178:181], v[98:101]
	v_mfma_f32_16x16x32_bf16 v[32:35], v[170:173], v[178:181], v[32:35]
	v_mfma_f32_16x16x32_bf16 v[36:39], v[126:129], v[186:189], v[36:39]
	v_mfma_f32_16x16x32_bf16 v[40:43], v[170:173], v[186:189], v[40:43]
	v_mfma_f32_16x16x32_bf16 v[44:47], v[126:129], v[194:197], v[44:47]
	v_mfma_f32_16x16x32_bf16 v[48:51], v[170:173], v[194:197], v[48:51]
	v_mfma_f32_16x16x32_bf16 v[52:55], v[126:129], v[202:205], v[52:55]
	v_mfma_f32_16x16x32_bf16 v[56:59], v[170:173], v[202:205], v[56:59]
	s_setprio 0
	s_barrier
	s_add_i32 s61, s61, s46
	s_add_i32 s35, s61, 0x2000
	s_mov_b32 m0, s61
	s_add_u32 s42, s80, 0x10000
	ds_read_b128 v[174:177], v141 offset:49152
	ds_read_b128 v[178:181], v141 offset:50176
	ds_read_b128 v[182:185], v141 offset:51200
	ds_read_b128 v[186:189], v141 offset:52224
	ds_read_b128 v[190:193], v141 offset:53248
	ds_read_b128 v[194:197], v141 offset:54272
	ds_read_b128 v[198:201], v141 offset:55296
	ds_read_b128 v[202:205], v141 offset:56320
	global_load_lds_dwordx4 v132, s[80:81]
	s_mov_b32 m0, s35
	s_addc_u32 s43, s81, 0
	s_add_i32 s44, s44, s46
	global_load_lds_dwordx4 v136, s[80:81]
	s_mov_b32 m0, s44
	s_add_i32 s45, s44, 0x2000
	global_load_lds_dwordx4 v132, s[42:43]
	s_mov_b32 m0, s45
	s_nop 0
	global_load_lds_dwordx4 v136, s[42:43]
	s_mov_b32 m0, s85
	s_nop 0
	global_load_lds_dwordx4 v130, s[76:77]
	s_mov_b32 m0, s86
	s_nop 0
	global_load_lds_dwordx4 v134, s[76:77]
	s_waitcnt vmcnt(8)
	s_waitcnt lgkmcnt(0)
	s_barrier
	s_setprio 1
	s_waitcnt lgkmcnt(0)
	v_mfma_f32_16x16x32_bf16 v[0:3], v[24:27], v[198:201], v[0:3]
	v_mfma_f32_16x16x32_bf16 v[4:7], v[114:117], v[198:201], v[4:7]
	v_mfma_f32_16x16x32_bf16 v[142:145], v[24:27], v[174:177], v[142:145]
	v_mfma_f32_16x16x32_bf16 v[146:149], v[114:117], v[174:177], v[146:149]
	v_mfma_f32_16x16x32_bf16 v[150:153], v[24:27], v[182:185], v[150:153]
	v_mfma_f32_16x16x32_bf16 v[154:157], v[114:117], v[182:185], v[154:157]
	v_mfma_f32_16x16x32_bf16 v[158:161], v[24:27], v[190:193], v[158:161]
	v_mfma_f32_16x16x32_bf16 v[162:165], v[114:117], v[190:193], v[162:165]
	v_mfma_f32_16x16x32_bf16 v[0:3], v[28:31], v[202:205], v[0:3]
	v_mfma_f32_16x16x32_bf16 v[4:7], v[118:121], v[202:205], v[4:7]
	v_mfma_f32_16x16x32_bf16 v[142:145], v[28:31], v[178:181], v[142:145]
	v_mfma_f32_16x16x32_bf16 v[146:149], v[118:121], v[178:181], v[146:149]
	v_mfma_f32_16x16x32_bf16 v[150:153], v[28:31], v[186:189], v[150:153]
	v_mfma_f32_16x16x32_bf16 v[154:157], v[118:121], v[186:189], v[154:157]
	v_mfma_f32_16x16x32_bf16 v[158:161], v[28:31], v[194:197], v[158:161]
	v_mfma_f32_16x16x32_bf16 v[162:165], v[118:121], v[194:197], v[162:165]
	v_mfma_f32_16x16x32_bf16 v[8:11], v[122:125], v[174:177], v[8:11]
	v_mfma_f32_16x16x32_bf16 v[12:15], v[166:169], v[174:177], v[12:15]
	v_mfma_f32_16x16x32_bf16 v[24:27], v[122:125], v[182:185], v[60:63]
	v_mfma_f32_16x16x32_bf16 v[28:31], v[166:169], v[182:185], v[102:105]
	v_mfma_f32_16x16x32_bf16 v[60:63], v[122:125], v[190:193], v[106:109]
	v_mfma_f32_16x16x32_bf16 v[102:105], v[166:169], v[190:193], v[110:113]
	v_mfma_f32_16x16x32_bf16 v[16:19], v[122:125], v[198:201], v[16:19]
	v_mfma_f32_16x16x32_bf16 v[20:23], v[166:169], v[198:201], v[20:23]
	v_mfma_f32_16x16x32_bf16 v[8:11], v[126:129], v[178:181], v[8:11]
	v_mfma_f32_16x16x32_bf16 v[12:15], v[170:173], v[178:181], v[12:15]
	v_mfma_f32_16x16x32_bf16 v[24:27], v[126:129], v[186:189], v[24:27]
	v_mfma_f32_16x16x32_bf16 v[28:31], v[170:173], v[186:189], v[28:31]
	v_mfma_f32_16x16x32_bf16 v[60:63], v[126:129], v[194:197], v[60:63]
	v_mfma_f32_16x16x32_bf16 v[102:105], v[170:173], v[194:197], v[102:105]
	v_mfma_f32_16x16x32_bf16 v[16:19], v[126:129], v[202:205], v[16:19]
	v_mfma_f32_16x16x32_bf16 v[20:23], v[170:173], v[202:205], v[20:23]
	s_setprio 0
	s_barrier
	s_add_u32 s76, s38, 0x80
	s_addc_u32 s77, s39, 0
	s_add_u32 s42, s68, 0x80
	s_addc_u32 s43, s69, 0
	ds_read_b128 v[106:109], v96
	ds_read_b128 v[110:113], v96 offset:1024
	ds_read_b128 v[114:117], v96 offset:2048
	ds_read_b128 v[118:121], v96 offset:3072
	ds_read_b128 v[122:125], v138
	ds_read_b128 v[126:129], v138 offset:1024
	ds_read_b128 v[166:169], v138 offset:2048
	ds_read_b128 v[170:173], v138 offset:3072
	s_add_u32 s78, s78, 0x10000
	s_addc_u32 s79, s79, 0
	s_mov_b32 m0, s59
	ds_read_b128 v[174:177], v141
	ds_read_b128 v[178:181], v141 offset:1024
	ds_read_b128 v[182:185], v141 offset:2048
	ds_read_b128 v[186:189], v141 offset:3072
	ds_read_b128 v[190:193], v141 offset:4096
	ds_read_b128 v[194:197], v141 offset:5120
	ds_read_b128 v[198:201], v141 offset:6144
	ds_read_b128 v[202:205], v141 offset:7168
	global_load_lds_dwordx4 v130, s[78:79]
	s_mov_b32 m0, s18
	s_nop 0
	global_load_lds_dwordx4 v134, s[78:79]
	s_waitcnt vmcnt(8)
	s_waitcnt lgkmcnt(0)
	s_barrier
	s_setprio 1
	s_waitcnt lgkmcnt(0)
	v_mfma_f32_16x16x32_bf16 v[88:91], v[106:109], v[198:201], v[88:91]
	v_mfma_f32_16x16x32_bf16 v[64:67], v[106:109], v[174:177], v[64:67]
	v_mfma_f32_16x16x32_bf16 v[68:71], v[114:117], v[174:177], v[68:71]
	v_mfma_f32_16x16x32_bf16 v[72:75], v[106:109], v[182:185], v[72:75]
	v_mfma_f32_16x16x32_bf16 v[76:79], v[114:117], v[182:185], v[76:79]
	v_mfma_f32_16x16x32_bf16 v[80:83], v[106:109], v[190:193], v[80:83]
	v_mfma_f32_16x16x32_bf16 v[84:87], v[114:117], v[190:193], v[84:87]
	v_mfma_f32_16x16x32_bf16 v[206:209], v[110:113], v[202:205], v[88:91]
	v_mfma_f32_16x16x32_bf16 v[88:91], v[114:117], v[198:201], v[92:95]
	v_mfma_f32_16x16x32_bf16 v[64:67], v[110:113], v[178:181], v[64:67]
	v_mfma_f32_16x16x32_bf16 v[68:71], v[118:121], v[178:181], v[68:71]
	v_mfma_f32_16x16x32_bf16 v[72:75], v[110:113], v[186:189], v[72:75]
	v_mfma_f32_16x16x32_bf16 v[76:79], v[118:121], v[186:189], v[76:79]
	v_mfma_f32_16x16x32_bf16 v[80:83], v[110:113], v[194:197], v[80:83]
	v_mfma_f32_16x16x32_bf16 v[84:87], v[118:121], v[194:197], v[84:87]
	v_mfma_f32_16x16x32_bf16 v[92:95], v[118:121], v[202:205], v[88:91]
	v_mfma_f32_16x16x32_bf16 v[44:47], v[122:125], v[190:193], v[44:47]
	v_mfma_f32_16x16x32_bf16 v[88:91], v[122:125], v[174:177], v[98:101]
	v_mfma_f32_16x16x32_bf16 v[32:35], v[166:169], v[174:177], v[32:35]
	v_mfma_f32_16x16x32_bf16 v[174:177], v[126:129], v[194:197], v[44:47]
	v_mfma_f32_16x16x32_bf16 v[44:47], v[166:169], v[190:193], v[48:51]
	v_mfma_f32_16x16x32_bf16 v[36:39], v[122:125], v[182:185], v[36:39]
	v_mfma_f32_16x16x32_bf16 v[40:43], v[166:169], v[182:185], v[40:43]
	v_mfma_f32_16x16x32_bf16 v[48:51], v[170:173], v[194:197], v[44:47]
	v_mfma_f32_16x16x32_bf16 v[44:47], v[122:125], v[198:201], v[52:55]
	v_mfma_f32_16x16x32_bf16 v[210:213], v[126:129], v[178:181], v[88:91]
	v_mfma_f32_16x16x32_bf16 v[32:35], v[170:173], v[178:181], v[32:35]
	v_mfma_f32_16x16x32_bf16 v[36:39], v[126:129], v[186:189], v[36:39]
	v_mfma_f32_16x16x32_bf16 v[40:43], v[170:173], v[186:189], v[40:43]
	v_mfma_f32_16x16x32_bf16 v[178:181], v[126:129], v[202:205], v[44:47]
	v_mfma_f32_16x16x32_bf16 v[44:47], v[166:169], v[198:201], v[56:59]
	v_mfma_f32_16x16x32_bf16 v[182:185], v[170:173], v[202:205], v[44:47]
	s_setprio 0
	s_barrier
	s_mov_b32 m0, s49
	s_add_u32 s18, s68, 0x10000
	s_nop 1
	ds_read_b128 v[44:47], v141 offset:16384
	ds_read_b128 v[52:55], v141 offset:17408
	ds_read_b128 v[56:59], v141 offset:18432
	ds_read_b128 v[88:91], v141 offset:19456
	ds_read_b128 v[98:101], v141 offset:20480
	ds_read_b128 v[186:189], v141 offset:21504
	ds_read_b128 v[190:193], v141 offset:22528
	ds_read_b128 v[194:197], v141 offset:23552
	global_load_lds_dwordx4 v132, s[68:69]
	s_mov_b32 m0, s19
	s_addc_u32 s19, s69, 0
	global_load_lds_dwordx4 v136, s[68:69]
	s_mov_b32 m0, s20
	s_nop 0
	global_load_lds_dwordx4 v132, s[18:19]
	s_mov_b32 m0, s33
	s_nop 0
	global_load_lds_dwordx4 v136, s[18:19]
	s_mov_b32 m0, s67
	s_nop 0
	global_load_lds_dwordx4 v130, s[38:39]
	s_mov_b32 m0, s72
	s_nop 0
	global_load_lds_dwordx4 v134, s[38:39]
	s_waitcnt vmcnt(8)
	s_waitcnt lgkmcnt(0)
	s_barrier
	s_setprio 1
	s_waitcnt lgkmcnt(0)
	v_mfma_f32_16x16x32_bf16 v[0:3], v[106:109], v[190:193], v[0:3]
	v_mfma_f32_16x16x32_bf16 v[4:7], v[114:117], v[190:193], v[4:7]
	v_mfma_f32_16x16x32_bf16 v[142:145], v[106:109], v[44:47], v[142:145]
	v_mfma_f32_16x16x32_bf16 v[146:149], v[114:117], v[44:47], v[146:149]
	v_mfma_f32_16x16x32_bf16 v[150:153], v[106:109], v[56:59], v[150:153]
	v_mfma_f32_16x16x32_bf16 v[154:157], v[114:117], v[56:59], v[154:157]
	v_mfma_f32_16x16x32_bf16 v[158:161], v[106:109], v[98:101], v[158:161]
	v_mfma_f32_16x16x32_bf16 v[162:165], v[114:117], v[98:101], v[162:165]
	v_mfma_f32_16x16x32_bf16 v[0:3], v[110:113], v[194:197], v[0:3]
	v_mfma_f32_16x16x32_bf16 v[4:7], v[118:121], v[194:197], v[4:7]
	v_mfma_f32_16x16x32_bf16 v[142:145], v[110:113], v[52:55], v[142:145]
	v_mfma_f32_16x16x32_bf16 v[146:149], v[118:121], v[52:55], v[146:149]
	v_mfma_f32_16x16x32_bf16 v[150:153], v[110:113], v[88:91], v[150:153]
	v_mfma_f32_16x16x32_bf16 v[154:157], v[118:121], v[88:91], v[154:157]
	v_mfma_f32_16x16x32_bf16 v[158:161], v[110:113], v[186:189], v[158:161]
	v_mfma_f32_16x16x32_bf16 v[162:165], v[118:121], v[186:189], v[162:165]
	v_mfma_f32_16x16x32_bf16 v[28:31], v[166:169], v[56:59], v[28:31]
	v_mfma_f32_16x16x32_bf16 v[8:11], v[122:125], v[44:47], v[8:11]
	v_mfma_f32_16x16x32_bf16 v[12:15], v[166:169], v[44:47], v[12:15]
	v_mfma_f32_16x16x32_bf16 v[24:27], v[122:125], v[56:59], v[24:27]
	v_mfma_f32_16x16x32_bf16 v[198:201], v[170:173], v[88:91], v[28:31]
	v_mfma_f32_16x16x32_bf16 v[28:31], v[122:125], v[98:101], v[60:63]
	v_mfma_f32_16x16x32_bf16 v[16:19], v[122:125], v[190:193], v[16:19]
	v_mfma_f32_16x16x32_bf16 v[8:11], v[126:129], v[52:55], v[8:11]
	v_mfma_f32_16x16x32_bf16 v[12:15], v[170:173], v[52:55], v[12:15]
	v_mfma_f32_16x16x32_bf16 v[24:27], v[126:129], v[88:91], v[24:27]
	v_mfma_f32_16x16x32_bf16 v[202:205], v[126:129], v[186:189], v[28:31]
	v_mfma_f32_16x16x32_bf16 v[28:31], v[166:169], v[98:101], v[102:105]
	v_mfma_f32_16x16x32_bf16 v[16:19], v[126:129], v[194:197], v[16:19]
	v_mfma_f32_16x16x32_bf16 v[20:23], v[166:169], v[190:193], v[20:23]
	v_mfma_f32_16x16x32_bf16 v[186:189], v[170:173], v[186:189], v[28:31]
	v_mfma_f32_16x16x32_bf16 v[166:169], v[170:173], v[194:197], v[20:23]
	s_setprio 0
	s_barrier
	ds_read_b128 v[170:173], v140
	ds_read_b128 v[190:193], v140 offset:1024
	ds_read_b128 v[194:197], v140 offset:2048
	ds_read_b128 v[220:223], v140 offset:3072
	ds_read_b128 v[224:227], v236
	ds_read_b128 v[228:231], v236 offset:1024
	ds_read_b128 v[232:235], v236 offset:2048
	ds_read_b128 v[236:239], v236 offset:3072
	s_add_u32 s18, s38, 0x10000
	s_addc_u32 s19, s39, 0
	s_mov_b32 m0, s73
	ds_read_b128 v[20:23], v141 offset:32768
	ds_read_b128 v[28:31], v141 offset:33792
	ds_read_b128 v[52:55], v141 offset:34816
	ds_read_b128 v[102:105], v141 offset:35840
	ds_read_b128 v[110:113], v141 offset:36864
	ds_read_b128 v[118:121], v141 offset:37888
	ds_read_b128 v[240:243], v141 offset:38912
	ds_read_b128 v[244:247], v141 offset:39936
	global_load_lds_dwordx4 v130, s[18:19]
	s_mov_b32 m0, s74
	s_nop 0
	global_load_lds_dwordx4 v134, s[18:19]
	s_waitcnt vmcnt(8)
	s_waitcnt lgkmcnt(0)
	s_barrier
	s_setprio 1
	s_waitcnt lgkmcnt(0)
	v_mfma_f32_16x16x32_bf16 v[44:47], v[170:173], v[20:23], v[64:67]
	v_mfma_f32_16x16x32_bf16 v[126:129], v[190:193], v[28:31], v[44:47]
	v_mfma_f32_16x16x32_bf16 v[44:47], v[194:197], v[20:23], v[68:71]
	v_mfma_f32_16x16x32_bf16 v[122:125], v[220:223], v[28:31], v[44:47]
	v_mfma_f32_16x16x32_bf16 v[44:47], v[170:173], v[52:55], v[72:75]
	v_mfma_f32_16x16x32_bf16 v[114:117], v[190:193], v[102:105], v[44:47]
	v_mfma_f32_16x16x32_bf16 v[44:47], v[194:197], v[52:55], v[76:79]
	v_mfma_f32_16x16x32_bf16 v[106:109], v[220:223], v[102:105], v[44:47]
	v_mfma_f32_16x16x32_bf16 v[44:47], v[170:173], v[110:113], v[80:83]
	v_mfma_f32_16x16x32_bf16 v[98:101], v[190:193], v[118:121], v[44:47]
	v_mfma_f32_16x16x32_bf16 v[44:47], v[194:197], v[110:113], v[84:87]
	v_mfma_f32_16x16x32_bf16 v[88:91], v[220:223], v[118:121], v[44:47]
	v_mfma_f32_16x16x32_bf16 v[44:47], v[170:173], v[240:243], v[206:209]
	v_mfma_f32_16x16x32_bf16 v[80:83], v[190:193], v[244:247], v[44:47]
	v_mfma_f32_16x16x32_bf16 v[44:47], v[194:197], v[240:243], v[92:95]
	v_mfma_f32_16x16x32_bf16 v[72:75], v[220:223], v[244:247], v[44:47]
	v_mfma_f32_16x16x32_bf16 v[44:47], v[224:227], v[20:23], v[210:213]
	v_mfma_f32_16x16x32_bf16 v[20:23], v[232:235], v[20:23], v[32:35]
	v_mfma_f32_16x16x32_bf16 v[60:63], v[228:231], v[28:31], v[44:47]
	v_mfma_f32_16x16x32_bf16 v[44:47], v[236:239], v[28:31], v[20:23]
	v_mfma_f32_16x16x32_bf16 v[20:23], v[224:227], v[52:55], v[36:39]
	v_mfma_f32_16x16x32_bf16 v[56:59], v[228:231], v[102:105], v[20:23]
	v_mfma_f32_16x16x32_bf16 v[20:23], v[232:235], v[52:55], v[40:43]
	v_mfma_f32_16x16x32_bf16 v[36:39], v[236:239], v[102:105], v[20:23]
	v_mfma_f32_16x16x32_bf16 v[20:23], v[224:227], v[110:113], v[174:177]
	v_mfma_f32_16x16x32_bf16 v[52:55], v[228:231], v[118:121], v[20:23]
	v_mfma_f32_16x16x32_bf16 v[20:23], v[232:235], v[110:113], v[48:51]
	v_mfma_f32_16x16x32_bf16 v[28:31], v[236:239], v[118:121], v[20:23]
	v_mfma_f32_16x16x32_bf16 v[20:23], v[224:227], v[240:243], v[178:181]
	v_mfma_f32_16x16x32_bf16 v[48:51], v[228:231], v[244:247], v[20:23]
	v_mfma_f32_16x16x32_bf16 v[20:23], v[232:235], v[240:243], v[182:185]
	v_mfma_f32_16x16x32_bf16 v[20:23], v[236:239], v[244:247], v[20:23]
	s_setprio 0
	s_barrier
	s_mov_b32 m0, s61
	s_add_u32 s18, s42, 0x10000
	ds_read_b128 v[32:35], v141 offset:49152
	ds_read_b128 v[174:177], v141 offset:50176
	ds_read_b128 v[178:181], v141 offset:51200
	ds_read_b128 v[182:185], v141 offset:52224
	ds_read_b128 v[206:209], v141 offset:53248
	ds_read_b128 v[210:213], v141 offset:54272
	ds_read_b128 v[240:243], v141 offset:55296
	ds_read_b128 v[244:247], v141 offset:56320
	global_load_lds_dwordx4 v132, s[42:43]
	s_mov_b32 m0, s35
	s_addc_u32 s19, s43, 0
	global_load_lds_dwordx4 v136, s[42:43]
	s_mov_b32 m0, s44
	s_nop 0
	global_load_lds_dwordx4 v132, s[18:19]
	s_mov_b32 m0, s45
	s_nop 0
	global_load_lds_dwordx4 v136, s[18:19]
	s_mov_b32 m0, s85
	s_nop 0
	global_load_lds_dwordx4 v130, s[76:77]
	s_mov_b32 m0, s86
	s_nop 0
	global_load_lds_dwordx4 v134, s[76:77]
	s_waitcnt vmcnt(8)
	s_waitcnt lgkmcnt(0)
	s_barrier
	s_setprio 1
	s_waitcnt lgkmcnt(0)
	v_mfma_f32_16x16x32_bf16 v[40:43], v[170:173], v[32:35], v[142:145]
	v_mfma_f32_16x16x32_bf16 v[118:121], v[190:193], v[174:177], v[40:43]
	v_mfma_f32_16x16x32_bf16 v[40:43], v[194:197], v[32:35], v[146:149]
	v_mfma_f32_16x16x32_bf16 v[110:113], v[220:223], v[174:177], v[40:43]
	v_mfma_f32_16x16x32_bf16 v[40:43], v[170:173], v[178:181], v[150:153]
	v_mfma_f32_16x16x32_bf16 v[102:105], v[190:193], v[182:185], v[40:43]
	v_mfma_f32_16x16x32_bf16 v[40:43], v[194:197], v[178:181], v[154:157]
	v_mfma_f32_16x16x32_bf16 v[92:95], v[220:223], v[182:185], v[40:43]
	v_mfma_f32_16x16x32_bf16 v[40:43], v[170:173], v[206:209], v[158:161]
	v_mfma_f32_16x16x32_bf16 v[0:3], v[170:173], v[240:243], v[0:3]
	v_mfma_f32_16x16x32_bf16 v[84:87], v[190:193], v[210:213], v[40:43]
	v_mfma_f32_16x16x32_bf16 v[40:43], v[194:197], v[206:209], v[162:165]
	v_mfma_f32_16x16x32_bf16 v[68:71], v[190:193], v[244:247], v[0:3]
	v_mfma_f32_16x16x32_bf16 v[0:3], v[194:197], v[240:243], v[4:7]
	v_mfma_f32_16x16x32_bf16 v[76:79], v[220:223], v[210:213], v[40:43]
	v_mfma_f32_16x16x32_bf16 v[64:67], v[220:223], v[244:247], v[0:3]
	v_mfma_f32_16x16x32_bf16 v[0:3], v[224:227], v[32:35], v[8:11]
	v_mfma_f32_16x16x32_bf16 v[40:43], v[228:231], v[174:177], v[0:3]
	v_mfma_f32_16x16x32_bf16 v[0:3], v[232:235], v[32:35], v[12:15]
	v_mfma_f32_16x16x32_bf16 v[12:15], v[236:239], v[174:177], v[0:3]
	v_mfma_f32_16x16x32_bf16 v[0:3], v[224:227], v[178:181], v[24:27]
	v_mfma_f32_16x16x32_bf16 v[32:35], v[228:231], v[182:185], v[0:3]
	v_mfma_f32_16x16x32_bf16 v[0:3], v[232:235], v[178:181], v[198:201]
	v_mfma_f32_16x16x32_bf16 v[8:11], v[236:239], v[182:185], v[0:3]
	v_mfma_f32_16x16x32_bf16 v[0:3], v[224:227], v[206:209], v[202:205]
	v_mfma_f32_16x16x32_bf16 v[24:27], v[228:231], v[210:213], v[0:3]
	v_mfma_f32_16x16x32_bf16 v[0:3], v[232:235], v[206:209], v[186:189]
	v_mfma_f32_16x16x32_bf16 v[4:7], v[236:239], v[210:213], v[0:3]
	v_mfma_f32_16x16x32_bf16 v[0:3], v[224:227], v[240:243], v[16:19]
	v_mfma_f32_16x16x32_bf16 v[16:19], v[228:231], v[244:247], v[0:3]
	v_mfma_f32_16x16x32_bf16 v[0:3], v[232:235], v[240:243], v[166:169]
	v_mfma_f32_16x16x32_bf16 v[0:3], v[236:239], v[244:247], v[0:3]
	s_setprio 0
	s_barrier
	s_andn2_b64 vcc, exec, s[10:11]
	s_cbranch_vccnz .LBB0_411
	s_barrier

.LBB0_427:
	s_add_u32 s58, s22, 0x7100000
	s_addc_u32 s59, s23, 0
	s_add_u32 s19, s22, 0x7300000
	s_addc_u32 s93, s23, 0
	s_add_u32 s7, s22, 0x7400000
	v_writelane_b32 v255, s7, 24
	s_addc_u32 s7, s23, 0
	s_add_u32 s60, s22, 0x7500000
	s_addc_u32 s61, s23, 0
	s_add_u32 s62, s22, 0x15d00000
	s_addc_u32 s63, s23, 0
	s_add_u32 s64, s22, 0x18100000
	s_addc_u32 s65, s23, 0
	v_writelane_b32 v255, s7, 26
	s_add_u32 s7, s22, 0x1a100000
	v_writelane_b32 v255, s7, 28
	s_addc_u32 s7, s23, 0
	v_writelane_b32 v255, s7, 30
	s_add_u32 s66, s22, 0x1b100000
	v_and_b32_e32 v9, 48, v8
	v_lshlrev_b32_e32 v10, 6, v8
	s_movk_i32 s7, 0x3c0
	v_lshlrev_b32_e32 v8, 2, v8
	s_addc_u32 s67, s23, 0
	s_and_b32 s9, s2, 3
	s_lshl_b32 s2, s6, 6
	s_lshl_b32 s6, s6, 13
	v_and_or_b32 v9, v10, s7, v9
	v_and_b32_e32 v8, 32, v8
	s_add_i32 m0, s73, 0x18000
	v_lshl_add_u64 v[6:7], v[6:7], 0, s[26:27]
	v_bitop3_b32 v10, v9, s6, v8 bitop3:0xde
	s_lshl_b32 s28, s9, 5
	s_lshl_b32 s6, s9, 12
	s_waitcnt vmcnt(2)
	s_barrier
	global_load_lds_dwordx4 v[6:7], off
	v_lshl_add_u64 v[4:5], v[4:5], 0, s[26:27]
	s_add_i32 m0, s73, 0x1a000
	s_add_i32 s29, s73, 0x8000
	s_add_i32 s16, s73, 0xa000
	v_bitop3_b32 v199, v9, s6, v8 bitop3:0xde
	global_load_lds_dwordx4 v[4:5], off
	v_lshl_add_u64 v[0:1], v[0:1], 0, s[26:27]
	s_mov_b32 m0, s29
	s_add_u32 s6, s38, 0x40080
	global_load_lds_dwordx4 v[0:1], off
	v_lshl_add_u64 v[0:1], v[2:3], 0, s[26:27]
	s_mov_b32 m0, s16
	s_addc_u32 s7, s39, 0
	global_load_lds_dwordx4 v[0:1], off
	s_add_i32 m0, s73, 0x1c000
	s_nop 0
	global_load_lds_dwordx4 v132, s[6:7]
	s_add_i32 m0, s73, 0x1e000
	s_cmpk_lt_u32 s18, 0x100
	global_load_lds_dwordx4 v136, s[6:7]
	s_cselect_b64 s[76:77], -1, 0
	s_cmp_lt_u32 s9, 2
	s_cselect_b64 s[78:79], -1, 0
	s_lshl_b32 s6, s9, 4
	v_writelane_b32 v255, s6, 32
	s_ashr_i32 s95, s20, 31
	s_ashr_i32 s96, s14, 31
	s_lshl_b32 s6, s9, 2
	s_waitcnt vmcnt(6)
	s_add_u32 s80, s19, s6
	s_addc_u32 s81, s93, 0
	s_lshl_b32 s6, s9, 2
	s_mov_b32 s70, s19
	s_mov_b32 s97, 0
	v_add_u32_e32 v200, 0, v10
	v_writelane_b32 v255, s6, 34
	s_barrier
	s_branch .LBB0_430

.LBB0_433:
	s_add_u32 s18, s10, 0x80
	s_addc_u32 s19, s11, 0
	s_add_u32 s10, s10, 0x100
	s_addc_u32 s11, s11, 0
	s_cmp_eq_u32 s92, 12
	s_cselect_b32 s42, s87, s10
	s_cselect_b32 s43, s9, s11
	s_cselect_b32 s45, s85, s94
	s_cselect_b32 s44, vcc_lo, vcc_hi
	s_add_u32 s38, s42, 0x80
	s_addc_u32 s39, s43, 0
	s_add_u32 s68, s44, 0x80
	s_addc_u32 s69, s45, 0
	s_add_i32 s35, 0, 0x10000
	s_add_i32 s49, 0, 0x14000
	v_add_u32_e32 v96, s35, v199
	v_add_u32_e32 v166, s49, v199
	ds_read_b128 v[138:141], v96
	ds_read_b128 v[142:145], v96 offset:1024
	ds_read_b128 v[146:149], v96 offset:2048
	ds_read_b128 v[150:153], v96 offset:3072
	s_waitcnt lgkmcnt(0)
	ds_read_b128 v[154:157], v166
	ds_read_b128 v[158:161], v166 offset:1024
	ds_read_b128 v[162:165], v166 offset:2048
	ds_read_b128 v[166:169], v166 offset:3072
	s_add_u32 s18, s18, 0x40000
	s_addc_u32 s19, s19, 0
	s_add_i32 m0, s73, 0xc000
	ds_read_b128 v[170:173], v200
	ds_read_b128 v[174:177], v200 offset:1024
	ds_read_b128 v[178:181], v200 offset:2048
	ds_read_b128 v[182:185], v200 offset:3072
	ds_read_b128 v[190:193], v200 offset:4096
	ds_read_b128 v[194:197], v200 offset:5120
	ds_read_b128 v[202:205], v200 offset:6144
	ds_read_b128 v[206:209], v200 offset:7168
	global_load_lds_dwordx4 v130, s[18:19]
	s_add_i32 m0, s73, 0xe000
	s_nop 0
	global_load_lds_dwordx4 v134, s[18:19]
	s_waitcnt vmcnt(8)
	s_waitcnt lgkmcnt(0)
	s_barrier
	s_setprio 1
	s_waitcnt lgkmcnt(0)
	v_mfma_f32_16x16x32_bf16 v[126:129], v[138:141], v[170:173], v[126:129]
	v_mfma_f32_16x16x32_bf16 v[122:125], v[146:149], v[170:173], v[122:125]
	v_mfma_f32_16x16x32_bf16 v[118:121], v[138:141], v[178:181], v[118:121]
	v_mfma_f32_16x16x32_bf16 v[110:113], v[146:149], v[178:181], v[110:113]
	v_mfma_f32_16x16x32_bf16 v[102:105], v[138:141], v[190:193], v[102:105]
	v_mfma_f32_16x16x32_bf16 v[92:95], v[146:149], v[190:193], v[92:95]
	v_mfma_f32_16x16x32_bf16 v[84:87], v[138:141], v[202:205], v[84:87]
	v_mfma_f32_16x16x32_bf16 v[76:79], v[146:149], v[202:205], v[76:79]
	v_mfma_f32_16x16x32_bf16 v[126:129], v[142:145], v[174:177], v[126:129]
	v_mfma_f32_16x16x32_bf16 v[122:125], v[150:153], v[174:177], v[122:125]
	v_mfma_f32_16x16x32_bf16 v[118:121], v[142:145], v[182:185], v[118:121]
	v_mfma_f32_16x16x32_bf16 v[110:113], v[150:153], v[182:185], v[110:113]
	v_mfma_f32_16x16x32_bf16 v[102:105], v[142:145], v[194:197], v[102:105]
	v_mfma_f32_16x16x32_bf16 v[92:95], v[150:153], v[194:197], v[92:95]
	v_mfma_f32_16x16x32_bf16 v[84:87], v[142:145], v[206:209], v[84:87]
	v_mfma_f32_16x16x32_bf16 v[76:79], v[150:153], v[206:209], v[76:79]
	v_mfma_f32_16x16x32_bf16 v[114:117], v[154:157], v[170:173], v[114:117]
	v_mfma_f32_16x16x32_bf16 v[106:109], v[162:165], v[170:173], v[106:109]
	v_mfma_f32_16x16x32_bf16 v[98:101], v[154:157], v[178:181], v[98:101]
	v_mfma_f32_16x16x32_bf16 v[88:91], v[162:165], v[178:181], v[88:91]
	v_mfma_f32_16x16x32_bf16 v[80:83], v[154:157], v[190:193], v[80:83]
	v_mfma_f32_16x16x32_bf16 v[72:75], v[162:165], v[190:193], v[72:75]
	v_mfma_f32_16x16x32_bf16 v[68:71], v[154:157], v[202:205], v[68:71]
	v_mfma_f32_16x16x32_bf16 v[64:67], v[162:165], v[202:205], v[64:67]
	v_mfma_f32_16x16x32_bf16 v[114:117], v[158:161], v[174:177], v[114:117]
	v_mfma_f32_16x16x32_bf16 v[106:109], v[166:169], v[174:177], v[106:109]
	v_mfma_f32_16x16x32_bf16 v[98:101], v[158:161], v[182:185], v[98:101]
	v_mfma_f32_16x16x32_bf16 v[88:91], v[166:169], v[182:185], v[88:91]
	v_mfma_f32_16x16x32_bf16 v[80:83], v[158:161], v[194:197], v[80:83]
	v_mfma_f32_16x16x32_bf16 v[72:75], v[166:169], v[194:197], v[72:75]
	v_mfma_f32_16x16x32_bf16 v[68:71], v[158:161], v[206:209], v[68:71]
	v_mfma_f32_16x16x32_bf16 v[64:67], v[166:169], v[206:209], v[64:67]
	s_setprio 0
	s_barrier
	s_add_i32 s18, s35, s72
	s_mov_b32 m0, s18
	ds_read_b128 v[170:173], v200 offset:16384
	ds_read_b128 v[174:177], v200 offset:17408
	ds_read_b128 v[178:181], v200 offset:18432
	ds_read_b128 v[182:185], v200 offset:19456
	ds_read_b128 v[190:193], v200 offset:20480
	ds_read_b128 v[194:197], v200 offset:21504
	ds_read_b128 v[202:205], v200 offset:22528
	ds_read_b128 v[206:209], v200 offset:23552
	global_load_lds_dwordx4 v132, s[44:45]
	s_add_i32 m0, s18, 0x2000
	s_add_u32 s18, s44, 0x40000
	s_addc_u32 s19, s45, 0
	s_add_i32 s35, s49, s72
	global_load_lds_dwordx4 v136, s[44:45]
	s_mov_b32 m0, s35
	s_nop 0
	global_load_lds_dwordx4 v132, s[18:19]
	s_add_i32 m0, s35, 0x2000
	s_nop 0
	global_load_lds_dwordx4 v136, s[18:19]
	s_mov_b32 m0, s73
	s_nop 0
	global_load_lds_dwordx4 v130, s[42:43]
	s_mov_b32 m0, s74
	s_nop 0
	global_load_lds_dwordx4 v134, s[42:43]
	s_waitcnt vmcnt(8)
	s_waitcnt lgkmcnt(0)
	s_barrier
	s_setprio 1
	s_waitcnt lgkmcnt(0)
	v_mfma_f32_16x16x32_bf16 v[60:63], v[138:141], v[170:173], v[60:63]
	v_mfma_f32_16x16x32_bf16 v[56:59], v[146:149], v[170:173], v[56:59]
	v_mfma_f32_16x16x32_bf16 v[52:55], v[138:141], v[178:181], v[52:55]
	v_mfma_f32_16x16x32_bf16 v[44:47], v[146:149], v[178:181], v[44:47]
	v_mfma_f32_16x16x32_bf16 v[36:39], v[138:141], v[190:193], v[36:39]
	v_mfma_f32_16x16x32_bf16 v[28:31], v[146:149], v[190:193], v[28:31]
	v_mfma_f32_16x16x32_bf16 v[20:23], v[138:141], v[202:205], v[20:23]
	v_mfma_f32_16x16x32_bf16 v[12:15], v[146:149], v[202:205], v[12:15]
	v_mfma_f32_16x16x32_bf16 v[60:63], v[142:145], v[174:177], v[60:63]
	v_mfma_f32_16x16x32_bf16 v[56:59], v[150:153], v[174:177], v[56:59]
	v_mfma_f32_16x16x32_bf16 v[52:55], v[142:145], v[182:185], v[52:55]
	v_mfma_f32_16x16x32_bf16 v[44:47], v[150:153], v[182:185], v[44:47]
	v_mfma_f32_16x16x32_bf16 v[36:39], v[142:145], v[194:197], v[36:39]
	v_mfma_f32_16x16x32_bf16 v[28:31], v[150:153], v[194:197], v[28:31]
	v_mfma_f32_16x16x32_bf16 v[20:23], v[142:145], v[206:209], v[20:23]
	v_mfma_f32_16x16x32_bf16 v[12:15], v[150:153], v[206:209], v[12:15]
	v_mfma_f32_16x16x32_bf16 v[48:51], v[154:157], v[170:173], v[48:51]
	v_mfma_f32_16x16x32_bf16 v[40:43], v[162:165], v[170:173], v[40:43]
	v_mfma_f32_16x16x32_bf16 v[32:35], v[154:157], v[178:181], v[32:35]
	v_mfma_f32_16x16x32_bf16 v[24:27], v[162:165], v[178:181], v[24:27]
	v_mfma_f32_16x16x32_bf16 v[16:19], v[154:157], v[190:193], v[16:19]
	v_mfma_f32_16x16x32_bf16 v[8:11], v[162:165], v[190:193], v[8:11]
	v_mfma_f32_16x16x32_bf16 v[4:7], v[154:157], v[202:205], v[4:7]
	v_mfma_f32_16x16x32_bf16 v[0:3], v[162:165], v[202:205], v[0:3]
	v_mfma_f32_16x16x32_bf16 v[48:51], v[158:161], v[174:177], v[48:51]
	v_mfma_f32_16x16x32_bf16 v[40:43], v[166:169], v[174:177], v[40:43]
	v_mfma_f32_16x16x32_bf16 v[32:35], v[158:161], v[182:185], v[32:35]
	v_mfma_f32_16x16x32_bf16 v[24:27], v[166:169], v[182:185], v[24:27]
	v_mfma_f32_16x16x32_bf16 v[16:19], v[158:161], v[194:197], v[16:19]
	v_mfma_f32_16x16x32_bf16 v[8:11], v[166:169], v[194:197], v[8:11]
	v_mfma_f32_16x16x32_bf16 v[4:7], v[158:161], v[206:209], v[4:7]
	v_mfma_f32_16x16x32_bf16 v[0:3], v[166:169], v[206:209], v[0:3]
	s_setprio 0
	s_barrier
	s_add_i32 s35, 0, 0x18000
	v_add_u32_e32 v96, s35, v199
	s_add_i32 s44, 0, 0x1c000
	ds_read_b128 v[138:141], v96
	ds_read_b128 v[142:145], v96 offset:1024
	ds_read_b128 v[146:149], v96 offset:2048
	ds_read_b128 v[150:153], v96 offset:3072
	v_add_u32_e32 v96, s44, v199
	ds_read_b128 v[154:157], v96
	ds_read_b128 v[158:161], v96 offset:1024
	ds_read_b128 v[162:165], v96 offset:2048
	ds_read_b128 v[166:169], v96 offset:3072
	s_add_u32 s18, s42, 0x40000
	s_addc_u32 s19, s43, 0
	s_mov_b32 m0, s75
	ds_read_b128 v[170:173], v200 offset:32768
	ds_read_b128 v[174:177], v200 offset:33792
	ds_read_b128 v[178:181], v200 offset:34816
	ds_read_b128 v[182:185], v200 offset:35840
	ds_read_b128 v[190:193], v200 offset:36864
	ds_read_b128 v[194:197], v200 offset:37888
	ds_read_b128 v[202:205], v200 offset:38912
	ds_read_b128 v[206:209], v200 offset:39936
	global_load_lds_dwordx4 v130, s[18:19]
	s_mov_b32 m0, s83
	s_nop 0
	global_load_lds_dwordx4 v134, s[18:19]
	s_waitcnt vmcnt(8)
	s_waitcnt lgkmcnt(0)
	s_barrier
	s_setprio 1
	s_waitcnt lgkmcnt(0)
	v_mfma_f32_16x16x32_bf16 v[126:129], v[138:141], v[170:173], v[126:129]
	v_mfma_f32_16x16x32_bf16 v[122:125], v[146:149], v[170:173], v[122:125]
	v_mfma_f32_16x16x32_bf16 v[118:121], v[138:141], v[178:181], v[118:121]
	v_mfma_f32_16x16x32_bf16 v[110:113], v[146:149], v[178:181], v[110:113]
	v_mfma_f32_16x16x32_bf16 v[102:105], v[138:141], v[190:193], v[102:105]
	v_mfma_f32_16x16x32_bf16 v[92:95], v[146:149], v[190:193], v[92:95]
	v_mfma_f32_16x16x32_bf16 v[84:87], v[138:141], v[202:205], v[84:87]
	v_mfma_f32_16x16x32_bf16 v[76:79], v[146:149], v[202:205], v[76:79]
	v_mfma_f32_16x16x32_bf16 v[126:129], v[142:145], v[174:177], v[126:129]
	v_mfma_f32_16x16x32_bf16 v[122:125], v[150:153], v[174:177], v[122:125]
	v_mfma_f32_16x16x32_bf16 v[118:121], v[142:145], v[182:185], v[118:121]
	v_mfma_f32_16x16x32_bf16 v[110:113], v[150:153], v[182:185], v[110:113]
	v_mfma_f32_16x16x32_bf16 v[102:105], v[142:145], v[194:197], v[102:105]
	v_mfma_f32_16x16x32_bf16 v[92:95], v[150:153], v[194:197], v[92:95]
	v_mfma_f32_16x16x32_bf16 v[84:87], v[142:145], v[206:209], v[84:87]
	v_mfma_f32_16x16x32_bf16 v[76:79], v[150:153], v[206:209], v[76:79]
	v_mfma_f32_16x16x32_bf16 v[114:117], v[154:157], v[170:173], v[114:117]
	v_mfma_f32_16x16x32_bf16 v[106:109], v[162:165], v[170:173], v[106:109]
	v_mfma_f32_16x16x32_bf16 v[98:101], v[154:157], v[178:181], v[98:101]
	v_mfma_f32_16x16x32_bf16 v[88:91], v[162:165], v[178:181], v[88:91]
	v_mfma_f32_16x16x32_bf16 v[80:83], v[154:157], v[190:193], v[80:83]
	v_mfma_f32_16x16x32_bf16 v[72:75], v[162:165], v[190:193], v[72:75]
	v_mfma_f32_16x16x32_bf16 v[68:71], v[154:157], v[202:205], v[68:71]
	v_mfma_f32_16x16x32_bf16 v[64:67], v[162:165], v[202:205], v[64:67]
	v_mfma_f32_16x16x32_bf16 v[114:117], v[158:161], v[174:177], v[114:117]
	v_mfma_f32_16x16x32_bf16 v[106:109], v[166:169], v[174:177], v[106:109]
	v_mfma_f32_16x16x32_bf16 v[98:101], v[158:161], v[182:185], v[98:101]
	v_mfma_f32_16x16x32_bf16 v[88:91], v[166:169], v[182:185], v[88:91]
	v_mfma_f32_16x16x32_bf16 v[80:83], v[158:161], v[194:197], v[80:83]
	v_mfma_f32_16x16x32_bf16 v[72:75], v[166:169], v[194:197], v[72:75]
	v_mfma_f32_16x16x32_bf16 v[68:71], v[158:161], v[206:209], v[68:71]
	v_mfma_f32_16x16x32_bf16 v[64:67], v[166:169], v[206:209], v[64:67]
	s_setprio 0
	s_barrier
	s_add_i32 s18, s35, s72
	s_mov_b32 m0, s18
	ds_read_b128 v[170:173], v200 offset:49152
	ds_read_b128 v[174:177], v200 offset:50176
	ds_read_b128 v[178:181], v200 offset:51200
	ds_read_b128 v[182:185], v200 offset:52224
	ds_read_b128 v[190:193], v200 offset:53248
	ds_read_b128 v[194:197], v200 offset:54272
	ds_read_b128 v[202:205], v200 offset:55296
	ds_read_b128 v[206:209], v200 offset:56320
	global_load_lds_dwordx4 v132, s[68:69]
	s_add_i32 m0, s18, 0x2000
	s_add_u32 s18, s68, 0x40000
	s_addc_u32 s19, s69, 0
	s_add_i32 s35, s44, s72
	global_load_lds_dwordx4 v136, s[68:69]
	s_mov_b32 m0, s35
	s_nop 0
	global_load_lds_dwordx4 v132, s[18:19]
	s_add_i32 m0, s35, 0x2000
	s_nop 0
	global_load_lds_dwordx4 v136, s[18:19]
	s_mov_b32 m0, s29
	s_nop 0
	global_load_lds_dwordx4 v130, s[38:39]
	s_mov_b32 m0, s16
	s_nop 0
	global_load_lds_dwordx4 v134, s[38:39]
	s_waitcnt vmcnt(8)
	s_waitcnt lgkmcnt(0)
	s_barrier
	s_setprio 1
	s_waitcnt lgkmcnt(0)
	v_mfma_f32_16x16x32_bf16 v[60:63], v[138:141], v[170:173], v[60:63]
	v_mfma_f32_16x16x32_bf16 v[56:59], v[146:149], v[170:173], v[56:59]
	v_mfma_f32_16x16x32_bf16 v[52:55], v[138:141], v[178:181], v[52:55]
	v_mfma_f32_16x16x32_bf16 v[44:47], v[146:149], v[178:181], v[44:47]
	v_mfma_f32_16x16x32_bf16 v[36:39], v[138:141], v[190:193], v[36:39]
	v_mfma_f32_16x16x32_bf16 v[28:31], v[146:149], v[190:193], v[28:31]
	v_mfma_f32_16x16x32_bf16 v[20:23], v[138:141], v[202:205], v[20:23]
	v_mfma_f32_16x16x32_bf16 v[12:15], v[146:149], v[202:205], v[12:15]
	v_mfma_f32_16x16x32_bf16 v[60:63], v[142:145], v[174:177], v[60:63]
	v_mfma_f32_16x16x32_bf16 v[56:59], v[150:153], v[174:177], v[56:59]
	v_mfma_f32_16x16x32_bf16 v[52:55], v[142:145], v[182:185], v[52:55]
	v_mfma_f32_16x16x32_bf16 v[44:47], v[150:153], v[182:185], v[44:47]
	v_mfma_f32_16x16x32_bf16 v[36:39], v[142:145], v[194:197], v[36:39]
	v_mfma_f32_16x16x32_bf16 v[28:31], v[150:153], v[194:197], v[28:31]
	v_mfma_f32_16x16x32_bf16 v[20:23], v[142:145], v[206:209], v[20:23]
	v_mfma_f32_16x16x32_bf16 v[12:15], v[150:153], v[206:209], v[12:15]
	v_mfma_f32_16x16x32_bf16 v[48:51], v[154:157], v[170:173], v[48:51]
	v_mfma_f32_16x16x32_bf16 v[40:43], v[162:165], v[170:173], v[40:43]
	v_mfma_f32_16x16x32_bf16 v[32:35], v[154:157], v[178:181], v[32:35]
	v_mfma_f32_16x16x32_bf16 v[24:27], v[162:165], v[178:181], v[24:27]
	v_mfma_f32_16x16x32_bf16 v[16:19], v[154:157], v[190:193], v[16:19]
	v_mfma_f32_16x16x32_bf16 v[8:11], v[162:165], v[190:193], v[8:11]
	v_mfma_f32_16x16x32_bf16 v[4:7], v[154:157], v[202:205], v[4:7]
	v_mfma_f32_16x16x32_bf16 v[0:3], v[162:165], v[202:205], v[0:3]
	v_mfma_f32_16x16x32_bf16 v[48:51], v[158:161], v[174:177], v[48:51]
	v_mfma_f32_16x16x32_bf16 v[40:43], v[166:169], v[174:177], v[40:43]
	v_mfma_f32_16x16x32_bf16 v[32:35], v[158:161], v[182:185], v[32:35]
	v_mfma_f32_16x16x32_bf16 v[24:27], v[166:169], v[182:185], v[24:27]
	v_mfma_f32_16x16x32_bf16 v[16:19], v[158:161], v[194:197], v[16:19]
	v_mfma_f32_16x16x32_bf16 v[8:11], v[166:169], v[194:197], v[8:11]
	v_mfma_f32_16x16x32_bf16 v[4:7], v[158:161], v[206:209], v[4:7]
	v_mfma_f32_16x16x32_bf16 v[0:3], v[166:169], v[206:209], v[0:3]
	s_setprio 0
	s_barrier
	s_add_i32 s92, s92, 2
	s_add_u32 vcc_hi, vcc_hi, 0x100
	s_addc_u32 s94, s94, 0
	s_cmp_gt_u32 s92, 13
	s_cbranch_scc0 .LBB0_433
	s_and_b64 vcc, exec, s[76:77]
	s_cbranch_vccz .LBB0_436
	s_barrier

.LBB0_689:
	s_add_u32 s22, s6, 0x3100000
	s_addc_u32 s23, s7, 0
	s_add_u32 s28, s6, 0x7100000
	s_addc_u32 s29, s7, 0
	v_and_b32_e32 v9, 48, v8
	v_lshlrev_b32_e32 v10, 6, v8
	s_movk_i32 s7, 0x3c0
	v_lshlrev_b32_e32 v8, 2, v8
	s_and_b32 s71, s9, 3
	s_lshl_b32 s6, s8, 13
	v_and_or_b32 v9, v10, s7, v9
	v_and_b32_e32 v8, 32, v8
	s_add_i32 m0, s66, 0x18000
	v_lshl_add_u64 v[6:7], v[6:7], 0, s[26:27]
	s_lshl_b32 s72, s8, 6
	v_bitop3_b32 v10, v9, s6, v8 bitop3:0xde
	s_lshl_b32 s73, s71, 5
	s_lshl_b32 s6, s71, 12
	s_waitcnt vmcnt(2)
	s_barrier
	global_load_lds_dwordx4 v[6:7], off
	v_lshl_add_u64 v[4:5], v[4:5], 0, s[26:27]
	s_add_i32 m0, s66, 0x1a000
	s_add_i32 s74, s66, 0x8000
	s_add_i32 s75, s66, 0xa000
	v_bitop3_b32 v142, v9, s6, v8 bitop3:0xde
	global_load_lds_dwordx4 v[4:5], off
	v_lshl_add_u64 v[0:1], v[0:1], 0, s[26:27]
	s_mov_b32 m0, s74
	s_add_u32 s6, s38, 0xb0080
	global_load_lds_dwordx4 v[0:1], off
	v_lshl_add_u64 v[0:1], v[2:3], 0, s[26:27]
	s_mov_b32 m0, s75
	s_addc_u32 s7, s39, 0
	global_load_lds_dwordx4 v[0:1], off
	s_add_i32 m0, s66, 0x1c000
	s_nop 0
	global_load_lds_dwordx4 v96, s[6:7]
	s_add_i32 m0, s66, 0x1e000
	s_cmpk_lt_u32 s18, 0x100
	global_load_lds_dwordx4 v134, s[6:7]
	s_waitcnt vmcnt(6)
	s_cselect_b64 s[30:31], -1, 0
	s_ashr_i32 s76, s33, 31
	s_ashr_i32 s77, s2, 31
	s_mov_b32 s78, 0
	v_add_u32_e32 v143, 0, v10
	s_barrier
	s_branch .LBB0_692

.LBB0_703:
	s_cmp_eq_u32 s85, 40
	s_cselect_b32 s42, s8, s81
	s_cselect_b32 s43, s9, s82
	s_cselect_b32 s45, s59, s84
	s_cselect_b32 s44, s58, s83
	s_add_u32 s38, s42, 0x80
	s_addc_u32 s39, s43, 0
	s_add_u32 s62, s44, 0x80
	s_addc_u32 s63, s45, 0
	s_add_i32 s35, 0, 0x10000
	s_mov_b64 s[18:19], s[60:61]
	v_add_u32_e32 v140, s35, v142
	s_add_i32 s49, 0, 0x14000
	ds_read_b128 v[136:139], v140
	ds_read_b128 v[144:147], v140 offset:1024
	ds_read_b128 v[148:151], v140 offset:2048
	ds_read_b128 v[152:155], v140 offset:3072
	v_add_u32_e32 v140, s49, v142
	ds_read_b128 v[156:159], v140
	ds_read_b128 v[160:163], v140 offset:1024
	ds_read_b128 v[164:167], v140 offset:2048
	ds_read_b128 v[168:171], v140 offset:3072
	s_add_u32 s18, s18, 0xb0000
	s_addc_u32 s19, s19, 0
	s_add_i32 m0, s66, 0xc000
	ds_read_b128 v[172:175], v143
	ds_read_b128 v[176:179], v143 offset:1024
	ds_read_b128 v[180:183], v143 offset:2048
	ds_read_b128 v[190:193], v143 offset:3072
	ds_read_b128 v[194:197], v143 offset:4096
	ds_read_b128 v[198:201], v143 offset:5120
	ds_read_b128 v[202:205], v143 offset:6144
	ds_read_b128 v[206:209], v143 offset:7168
	global_load_lds_dwordx4 v130, s[18:19]
	s_add_i32 m0, s66, 0xe000
	s_nop 0
	global_load_lds_dwordx4 v132, s[18:19]
	s_waitcnt vmcnt(8)
	s_waitcnt lgkmcnt(0)
	s_barrier
	s_setprio 1
	s_waitcnt lgkmcnt(0)
	v_mfma_f32_16x16x32_bf16 v[126:129], v[136:139], v[172:175], v[126:129]
	v_mfma_f32_16x16x32_bf16 v[122:125], v[148:151], v[172:175], v[122:125]
	v_mfma_f32_16x16x32_bf16 v[110:113], v[136:139], v[180:183], v[110:113]
	v_mfma_f32_16x16x32_bf16 v[106:109], v[148:151], v[180:183], v[106:109]
	v_mfma_f32_16x16x32_bf16 v[92:95], v[136:139], v[194:197], v[92:95]
	v_mfma_f32_16x16x32_bf16 v[88:91], v[148:151], v[194:197], v[88:91]
	v_mfma_f32_16x16x32_bf16 v[76:79], v[136:139], v[202:205], v[76:79]
	v_mfma_f32_16x16x32_bf16 v[72:75], v[148:151], v[202:205], v[72:75]
	v_mfma_f32_16x16x32_bf16 v[126:129], v[144:147], v[176:179], v[126:129]
	v_mfma_f32_16x16x32_bf16 v[122:125], v[152:155], v[176:179], v[122:125]
	v_mfma_f32_16x16x32_bf16 v[110:113], v[144:147], v[190:193], v[110:113]
	v_mfma_f32_16x16x32_bf16 v[106:109], v[152:155], v[190:193], v[106:109]
	v_mfma_f32_16x16x32_bf16 v[92:95], v[144:147], v[198:201], v[92:95]
	v_mfma_f32_16x16x32_bf16 v[88:91], v[152:155], v[198:201], v[88:91]
	v_mfma_f32_16x16x32_bf16 v[76:79], v[144:147], v[206:209], v[76:79]
	v_mfma_f32_16x16x32_bf16 v[72:75], v[152:155], v[206:209], v[72:75]
	v_mfma_f32_16x16x32_bf16 v[118:121], v[156:159], v[172:175], v[118:121]
	v_mfma_f32_16x16x32_bf16 v[114:117], v[164:167], v[172:175], v[114:117]
	v_mfma_f32_16x16x32_bf16 v[102:105], v[156:159], v[180:183], v[102:105]
	v_mfma_f32_16x16x32_bf16 v[98:101], v[164:167], v[180:183], v[98:101]
	v_mfma_f32_16x16x32_bf16 v[84:87], v[156:159], v[194:197], v[84:87]
	v_mfma_f32_16x16x32_bf16 v[80:83], v[164:167], v[194:197], v[80:83]
	v_mfma_f32_16x16x32_bf16 v[68:71], v[156:159], v[202:205], v[68:71]
	v_mfma_f32_16x16x32_bf16 v[64:67], v[164:167], v[202:205], v[64:67]
	v_mfma_f32_16x16x32_bf16 v[118:121], v[160:163], v[176:179], v[118:121]
	v_mfma_f32_16x16x32_bf16 v[114:117], v[168:171], v[176:179], v[114:117]
	v_mfma_f32_16x16x32_bf16 v[102:105], v[160:163], v[190:193], v[102:105]
	v_mfma_f32_16x16x32_bf16 v[98:101], v[168:171], v[190:193], v[98:101]
	v_mfma_f32_16x16x32_bf16 v[84:87], v[160:163], v[198:201], v[84:87]
	v_mfma_f32_16x16x32_bf16 v[80:83], v[168:171], v[198:201], v[80:83]
	v_mfma_f32_16x16x32_bf16 v[68:71], v[160:163], v[206:209], v[68:71]
	v_mfma_f32_16x16x32_bf16 v[64:67], v[168:171], v[206:209], v[64:67]
	s_setprio 0
	s_barrier
	s_add_i32 s18, s35, s14
	s_mov_b32 m0, s18
	ds_read_b128 v[172:175], v143 offset:16384
	ds_read_b128 v[176:179], v143 offset:17408
	ds_read_b128 v[180:183], v143 offset:18432
	ds_read_b128 v[190:193], v143 offset:19456
	ds_read_b128 v[194:197], v143 offset:20480
	ds_read_b128 v[198:201], v143 offset:21504
	ds_read_b128 v[202:205], v143 offset:22528
	ds_read_b128 v[206:209], v143 offset:23552
	global_load_lds_dwordx4 v96, s[44:45]
	s_add_i32 m0, s18, 0x2000
	s_add_u32 s18, s44, 0xb0000
	s_addc_u32 s19, s45, 0
	s_add_i32 s35, s49, s14
	global_load_lds_dwordx4 v134, s[44:45]
	s_mov_b32 m0, s35
	s_nop 0
	global_load_lds_dwordx4 v96, s[18:19]
	s_add_i32 m0, s35, 0x2000
	s_nop 0
	global_load_lds_dwordx4 v134, s[18:19]
	s_mov_b32 m0, s66
	s_nop 0
	global_load_lds_dwordx4 v130, s[42:43]
	s_mov_b32 m0, s67
	s_nop 0
	global_load_lds_dwordx4 v132, s[42:43]
	s_waitcnt vmcnt(8)
	s_waitcnt lgkmcnt(0)
	s_barrier
	s_setprio 1
	s_waitcnt lgkmcnt(0)
	v_mfma_f32_16x16x32_bf16 v[60:63], v[136:139], v[172:175], v[60:63]
	v_mfma_f32_16x16x32_bf16 v[56:59], v[148:151], v[172:175], v[56:59]
	v_mfma_f32_16x16x32_bf16 v[44:47], v[136:139], v[180:183], v[44:47]
	v_mfma_f32_16x16x32_bf16 v[40:43], v[148:151], v[180:183], v[40:43]
	v_mfma_f32_16x16x32_bf16 v[28:31], v[136:139], v[194:197], v[28:31]
	v_mfma_f32_16x16x32_bf16 v[24:27], v[148:151], v[194:197], v[24:27]
	v_mfma_f32_16x16x32_bf16 v[12:15], v[136:139], v[202:205], v[12:15]
	v_mfma_f32_16x16x32_bf16 v[8:11], v[148:151], v[202:205], v[8:11]
	v_mfma_f32_16x16x32_bf16 v[60:63], v[144:147], v[176:179], v[60:63]
	v_mfma_f32_16x16x32_bf16 v[56:59], v[152:155], v[176:179], v[56:59]
	v_mfma_f32_16x16x32_bf16 v[44:47], v[144:147], v[190:193], v[44:47]
	v_mfma_f32_16x16x32_bf16 v[40:43], v[152:155], v[190:193], v[40:43]
	v_mfma_f32_16x16x32_bf16 v[28:31], v[144:147], v[198:201], v[28:31]
	v_mfma_f32_16x16x32_bf16 v[24:27], v[152:155], v[198:201], v[24:27]
	v_mfma_f32_16x16x32_bf16 v[12:15], v[144:147], v[206:209], v[12:15]
	v_mfma_f32_16x16x32_bf16 v[8:11], v[152:155], v[206:209], v[8:11]
	v_mfma_f32_16x16x32_bf16 v[52:55], v[156:159], v[172:175], v[52:55]
	v_mfma_f32_16x16x32_bf16 v[48:51], v[164:167], v[172:175], v[48:51]
	v_mfma_f32_16x16x32_bf16 v[36:39], v[156:159], v[180:183], v[36:39]
	v_mfma_f32_16x16x32_bf16 v[32:35], v[164:167], v[180:183], v[32:35]
	v_mfma_f32_16x16x32_bf16 v[20:23], v[156:159], v[194:197], v[20:23]
	v_mfma_f32_16x16x32_bf16 v[16:19], v[164:167], v[194:197], v[16:19]
	v_mfma_f32_16x16x32_bf16 v[4:7], v[156:159], v[202:205], v[4:7]
	v_mfma_f32_16x16x32_bf16 v[0:3], v[164:167], v[202:205], v[0:3]
	v_mfma_f32_16x16x32_bf16 v[52:55], v[160:163], v[176:179], v[52:55]
	v_mfma_f32_16x16x32_bf16 v[48:51], v[168:171], v[176:179], v[48:51]
	v_mfma_f32_16x16x32_bf16 v[36:39], v[160:163], v[190:193], v[36:39]
	v_mfma_f32_16x16x32_bf16 v[32:35], v[168:171], v[190:193], v[32:35]
	v_mfma_f32_16x16x32_bf16 v[20:23], v[160:163], v[198:201], v[20:23]
	v_mfma_f32_16x16x32_bf16 v[16:19], v[168:171], v[198:201], v[16:19]
	v_mfma_f32_16x16x32_bf16 v[4:7], v[160:163], v[206:209], v[4:7]
	v_mfma_f32_16x16x32_bf16 v[0:3], v[168:171], v[206:209], v[0:3]
	s_setprio 0
	s_barrier
	s_add_i32 s35, 0, 0x18000
	v_add_u32_e32 v140, s35, v142
	s_add_i32 s44, 0, 0x1c000
	ds_read_b128 v[136:139], v140
	ds_read_b128 v[144:147], v140 offset:1024
	ds_read_b128 v[148:151], v140 offset:2048
	ds_read_b128 v[152:155], v140 offset:3072
	v_add_u32_e32 v140, s44, v142
	ds_read_b128 v[156:159], v140
	ds_read_b128 v[160:163], v140 offset:1024
	ds_read_b128 v[164:167], v140 offset:2048
	ds_read_b128 v[168:171], v140 offset:3072
	s_add_u32 s18, s42, 0xb0000
	s_addc_u32 s19, s43, 0
	s_mov_b32 m0, s68
	ds_read_b128 v[172:175], v143 offset:32768
	ds_read_b128 v[176:179], v143 offset:33792
	ds_read_b128 v[180:183], v143 offset:34816
	ds_read_b128 v[190:193], v143 offset:35840
	ds_read_b128 v[194:197], v143 offset:36864
	ds_read_b128 v[198:201], v143 offset:37888
	ds_read_b128 v[202:205], v143 offset:38912
	ds_read_b128 v[206:209], v143 offset:39936
	global_load_lds_dwordx4 v130, s[18:19]
	s_mov_b32 m0, s69
	s_nop 0
	global_load_lds_dwordx4 v132, s[18:19]
	s_waitcnt vmcnt(8)
	s_waitcnt lgkmcnt(0)
	s_barrier
	s_setprio 1
	s_waitcnt lgkmcnt(0)
	v_mfma_f32_16x16x32_bf16 v[126:129], v[136:139], v[172:175], v[126:129]
	v_mfma_f32_16x16x32_bf16 v[122:125], v[148:151], v[172:175], v[122:125]
	v_mfma_f32_16x16x32_bf16 v[110:113], v[136:139], v[180:183], v[110:113]
	v_mfma_f32_16x16x32_bf16 v[106:109], v[148:151], v[180:183], v[106:109]
	v_mfma_f32_16x16x32_bf16 v[92:95], v[136:139], v[194:197], v[92:95]
	v_mfma_f32_16x16x32_bf16 v[88:91], v[148:151], v[194:197], v[88:91]
	v_mfma_f32_16x16x32_bf16 v[76:79], v[136:139], v[202:205], v[76:79]
	v_mfma_f32_16x16x32_bf16 v[72:75], v[148:151], v[202:205], v[72:75]
	v_mfma_f32_16x16x32_bf16 v[126:129], v[144:147], v[176:179], v[126:129]
	v_mfma_f32_16x16x32_bf16 v[122:125], v[152:155], v[176:179], v[122:125]
	v_mfma_f32_16x16x32_bf16 v[110:113], v[144:147], v[190:193], v[110:113]
	v_mfma_f32_16x16x32_bf16 v[106:109], v[152:155], v[190:193], v[106:109]
	v_mfma_f32_16x16x32_bf16 v[92:95], v[144:147], v[198:201], v[92:95]
	v_mfma_f32_16x16x32_bf16 v[88:91], v[152:155], v[198:201], v[88:91]
	v_mfma_f32_16x16x32_bf16 v[76:79], v[144:147], v[206:209], v[76:79]
	v_mfma_f32_16x16x32_bf16 v[72:75], v[152:155], v[206:209], v[72:75]
	v_mfma_f32_16x16x32_bf16 v[118:121], v[156:159], v[172:175], v[118:121]
	v_mfma_f32_16x16x32_bf16 v[114:117], v[164:167], v[172:175], v[114:117]
	v_mfma_f32_16x16x32_bf16 v[102:105], v[156:159], v[180:183], v[102:105]
	v_mfma_f32_16x16x32_bf16 v[98:101], v[164:167], v[180:183], v[98:101]
	v_mfma_f32_16x16x32_bf16 v[84:87], v[156:159], v[194:197], v[84:87]
	v_mfma_f32_16x16x32_bf16 v[80:83], v[164:167], v[194:197], v[80:83]
	v_mfma_f32_16x16x32_bf16 v[68:71], v[156:159], v[202:205], v[68:71]
	v_mfma_f32_16x16x32_bf16 v[64:67], v[164:167], v[202:205], v[64:67]
	v_mfma_f32_16x16x32_bf16 v[118:121], v[160:163], v[176:179], v[118:121]
	v_mfma_f32_16x16x32_bf16 v[114:117], v[168:171], v[176:179], v[114:117]
	v_mfma_f32_16x16x32_bf16 v[102:105], v[160:163], v[190:193], v[102:105]
	v_mfma_f32_16x16x32_bf16 v[98:101], v[168:171], v[190:193], v[98:101]
	v_mfma_f32_16x16x32_bf16 v[84:87], v[160:163], v[198:201], v[84:87]
	v_mfma_f32_16x16x32_bf16 v[80:83], v[168:171], v[198:201], v[80:83]
	v_mfma_f32_16x16x32_bf16 v[68:71], v[160:163], v[206:209], v[68:71]
	v_mfma_f32_16x16x32_bf16 v[64:67], v[168:171], v[206:209], v[64:67]
	s_setprio 0
	s_barrier
	s_add_i32 s18, s35, s14
	s_mov_b32 m0, s18
	ds_read_b128 v[172:175], v143 offset:49152
	ds_read_b128 v[176:179], v143 offset:50176
	ds_read_b128 v[180:183], v143 offset:51200
	ds_read_b128 v[190:193], v143 offset:52224
	ds_read_b128 v[194:197], v143 offset:53248
	ds_read_b128 v[198:201], v143 offset:54272
	ds_read_b128 v[202:205], v143 offset:55296
	ds_read_b128 v[206:209], v143 offset:56320
	global_load_lds_dwordx4 v96, s[62:63]
	s_add_i32 m0, s18, 0x2000
	s_add_u32 s18, s62, 0xb0000
	s_addc_u32 s19, s63, 0
	s_add_i32 s35, s44, s14
	global_load_lds_dwordx4 v134, s[62:63]
	s_mov_b32 m0, s35
	s_nop 0
	global_load_lds_dwordx4 v96, s[18:19]
	s_add_i32 m0, s35, 0x2000
	s_nop 0
	global_load_lds_dwordx4 v134, s[18:19]
	s_mov_b32 m0, s74
	s_nop 0
	global_load_lds_dwordx4 v130, s[38:39]
	s_mov_b32 m0, s75
	s_nop 0
	global_load_lds_dwordx4 v132, s[38:39]
	s_waitcnt vmcnt(8)
	s_waitcnt lgkmcnt(0)
	s_barrier
	s_setprio 1
	s_waitcnt lgkmcnt(0)
	v_mfma_f32_16x16x32_bf16 v[60:63], v[136:139], v[172:175], v[60:63]
	v_mfma_f32_16x16x32_bf16 v[56:59], v[148:151], v[172:175], v[56:59]
	v_mfma_f32_16x16x32_bf16 v[44:47], v[136:139], v[180:183], v[44:47]
	v_mfma_f32_16x16x32_bf16 v[40:43], v[148:151], v[180:183], v[40:43]
	v_mfma_f32_16x16x32_bf16 v[28:31], v[136:139], v[194:197], v[28:31]
	v_mfma_f32_16x16x32_bf16 v[24:27], v[148:151], v[194:197], v[24:27]
	v_mfma_f32_16x16x32_bf16 v[12:15], v[136:139], v[202:205], v[12:15]
	v_mfma_f32_16x16x32_bf16 v[8:11], v[148:151], v[202:205], v[8:11]
	v_mfma_f32_16x16x32_bf16 v[60:63], v[144:147], v[176:179], v[60:63]
	v_mfma_f32_16x16x32_bf16 v[56:59], v[152:155], v[176:179], v[56:59]
	v_mfma_f32_16x16x32_bf16 v[44:47], v[144:147], v[190:193], v[44:47]
	v_mfma_f32_16x16x32_bf16 v[40:43], v[152:155], v[190:193], v[40:43]
	v_mfma_f32_16x16x32_bf16 v[28:31], v[144:147], v[198:201], v[28:31]
	v_mfma_f32_16x16x32_bf16 v[24:27], v[152:155], v[198:201], v[24:27]
	v_mfma_f32_16x16x32_bf16 v[12:15], v[144:147], v[206:209], v[12:15]
	v_mfma_f32_16x16x32_bf16 v[8:11], v[152:155], v[206:209], v[8:11]
	v_mfma_f32_16x16x32_bf16 v[52:55], v[156:159], v[172:175], v[52:55]
	v_mfma_f32_16x16x32_bf16 v[48:51], v[164:167], v[172:175], v[48:51]
	v_mfma_f32_16x16x32_bf16 v[36:39], v[156:159], v[180:183], v[36:39]
	v_mfma_f32_16x16x32_bf16 v[32:35], v[164:167], v[180:183], v[32:35]
	v_mfma_f32_16x16x32_bf16 v[20:23], v[156:159], v[194:197], v[20:23]
	v_mfma_f32_16x16x32_bf16 v[16:19], v[164:167], v[194:197], v[16:19]
	v_mfma_f32_16x16x32_bf16 v[4:7], v[156:159], v[202:205], v[4:7]
	v_mfma_f32_16x16x32_bf16 v[0:3], v[164:167], v[202:205], v[0:3]
	v_mfma_f32_16x16x32_bf16 v[52:55], v[160:163], v[176:179], v[52:55]
	v_mfma_f32_16x16x32_bf16 v[48:51], v[168:171], v[176:179], v[48:51]
	v_mfma_f32_16x16x32_bf16 v[36:39], v[160:163], v[190:193], v[36:39]
	v_mfma_f32_16x16x32_bf16 v[32:35], v[168:171], v[190:193], v[32:35]
	v_mfma_f32_16x16x32_bf16 v[20:23], v[160:163], v[198:201], v[20:23]
	v_mfma_f32_16x16x32_bf16 v[16:19], v[168:171], v[198:201], v[16:19]
	v_mfma_f32_16x16x32_bf16 v[4:7], v[160:163], v[206:209], v[4:7]
	v_mfma_f32_16x16x32_bf16 v[0:3], v[168:171], v[206:209], v[0:3]
	s_setprio 0
	s_barrier
	s_add_i32 s85, s85, 2
	s_add_u32 s81, s81, 0x100
	s_addc_u32 s82, s82, 0
	s_add_u32 s83, s83, 0x100
	s_addc_u32 s84, s84, 0
	s_add_u32 s60, s60, 0x100
	s_addc_u32 s61, s61, 0
	s_cmp_gt_u32 s85, 41
	s_cbranch_scc0 .LBB0_703
	s_and_b64 vcc, exec, s[30:31]
	s_cbranch_vccz .LBB0_706
	s_barrier

.LBB0_734:
	s_add_u32 s10, s6, 0x7100000
	s_addc_u32 s11, s7, 0
	s_add_u32 s22, s6, 0x7d00000
	s_addc_u32 s23, s7, 0
	s_lshl_b32 s6, s19, 5
	s_and_b32 s76, s6, 0x60
	s_add_i32 m0, s65, 0x18000
	v_lshl_add_u64 v[6:7], v[6:7], 0, s[26:27]
	s_lshl_b32 s75, s28, 6
	s_lshl_b32 s28, s28, 13
	s_lshl_b32 s19, s76, 7
	s_waitcnt vmcnt(2)
	s_barrier
	global_load_lds_dwordx4 v[6:7], off
	v_lshl_add_u64 v[4:5], v[4:5], 0, s[26:27]
	s_add_i32 m0, s65, 0x1a000
	s_add_i32 s77, s65, 0x8000
	s_add_i32 s78, s65, 0xa000
	global_load_lds_dwordx4 v[4:5], off
	v_lshl_add_u64 v[0:1], v[0:1], 0, s[26:27]
	s_mov_b32 m0, s77
	s_add_u32 s6, s38, 0x40080
	global_load_lds_dwordx4 v[0:1], off
	v_lshl_add_u64 v[0:1], v[2:3], 0, s[26:27]
	s_mov_b32 m0, s78
	s_addc_u32 s7, s39, 0
	global_load_lds_dwordx4 v[0:1], off
	s_add_i32 m0, s65, 0x1c000
	s_nop 0
	global_load_lds_dwordx4 v134, s[6:7]
	v_lshl_add_u64 v[0:1], s[6:7], 0, v[130:131]
	s_add_i32 m0, s65, 0x1e000
	s_movk_i32 s6, 0x3c0
	global_load_lds_dwordx4 v[0:1], off
	v_and_b32_e32 v0, 48, v8
	v_lshlrev_b32_e32 v1, 6, v8
	v_and_or_b32 v0, v1, s6, v0
	v_lshlrev_b32_e32 v1, 2, v8
	v_and_b32_e32 v1, 32, v1
	s_waitcnt vmcnt(6)
	v_bitop3_b32 v2, v0, s28, v1 bitop3:0xde
	s_cmpk_lt_u32 s18, 0x100
	s_sext_i32_i16 s80, s20
	v_bitop3_b32 v151, s19, v0, v1 bitop3:0xf6
	s_cselect_b64 s[28:29], -1, 0
	s_ashr_i32 s20, s14, 31
	s_mov_b32 s79, 0
	v_add_u32_e32 v155, 0, v2
	s_barrier
	s_branch .LBB0_737

.LBB0_740:
	s_add_u32 s18, s66, 0x80
	s_addc_u32 s19, s67, 0
	s_add_u32 s66, s66, 0x100
	s_addc_u32 s67, s67, 0
	s_cmp_eq_u32 s85, 12
	s_cselect_b32 s42, s81, s66
	s_cselect_b32 s43, s59, s67
	s_cselect_b32 s45, s31, s84
	s_cselect_b32 s44, s82, s83
	s_add_u32 s38, s42, 0x80
	s_addc_u32 s39, s43, 0
	s_add_u32 s68, s44, 0x80
	s_addc_u32 s69, s45, 0
	s_add_i32 s35, 0, 0x10000
	s_add_i32 s49, 0, 0x14000
	v_add_u32_e32 v96, s35, v151
	v_add_u32_e32 v150, s49, v151
	ds_read_b128 v[138:141], v96
	ds_read_b128 v[142:145], v96 offset:1024
	ds_read_b128 v[146:149], v96 offset:2048
	ds_read_b128 v[156:159], v96 offset:3072
	ds_read_b128 v[160:163], v150
	ds_read_b128 v[164:167], v150 offset:1024
	ds_read_b128 v[168:171], v150 offset:2048
	ds_read_b128 v[172:175], v150 offset:3072
	s_add_u32 s18, s18, 0x40000
	s_addc_u32 s19, s19, 0
	s_add_i32 m0, s65, 0xc000
	ds_read_b128 v[176:179], v155
	ds_read_b128 v[180:183], v155 offset:1024
	ds_read_b128 v[190:193], v155 offset:2048
	ds_read_b128 v[194:197], v155 offset:3072
	ds_read_b128 v[198:201], v155 offset:4096
	ds_read_b128 v[202:205], v155 offset:5120
	ds_read_b128 v[206:209], v155 offset:6144
	ds_read_b128 v[210:213], v155 offset:7168
	global_load_lds_dwordx4 v136, s[18:19]
	s_add_i32 m0, s65, 0xe000
	s_nop 0
	global_load_lds_dwordx4 v132, s[18:19]
	s_waitcnt vmcnt(8)
	s_waitcnt lgkmcnt(0)
	s_barrier
	s_setprio 1
	s_waitcnt lgkmcnt(0)
	v_mfma_f32_16x16x32_bf16 v[126:129], v[138:141], v[176:179], v[126:129]
	v_mfma_f32_16x16x32_bf16 v[118:121], v[146:149], v[176:179], v[118:121]
	v_mfma_f32_16x16x32_bf16 v[110:113], v[138:141], v[190:193], v[110:113]
	v_mfma_f32_16x16x32_bf16 v[102:105], v[146:149], v[190:193], v[102:105]
	v_mfma_f32_16x16x32_bf16 v[92:95], v[138:141], v[198:201], v[92:95]
	v_mfma_f32_16x16x32_bf16 v[84:87], v[146:149], v[198:201], v[84:87]
	v_mfma_f32_16x16x32_bf16 v[76:79], v[138:141], v[206:209], v[76:79]
	v_mfma_f32_16x16x32_bf16 v[68:71], v[146:149], v[206:209], v[68:71]
	v_mfma_f32_16x16x32_bf16 v[126:129], v[142:145], v[180:183], v[126:129]
	v_mfma_f32_16x16x32_bf16 v[118:121], v[156:159], v[180:183], v[118:121]
	v_mfma_f32_16x16x32_bf16 v[110:113], v[142:145], v[194:197], v[110:113]
	v_mfma_f32_16x16x32_bf16 v[102:105], v[156:159], v[194:197], v[102:105]
	v_mfma_f32_16x16x32_bf16 v[92:95], v[142:145], v[202:205], v[92:95]
	v_mfma_f32_16x16x32_bf16 v[84:87], v[156:159], v[202:205], v[84:87]
	v_mfma_f32_16x16x32_bf16 v[76:79], v[142:145], v[210:213], v[76:79]
	v_mfma_f32_16x16x32_bf16 v[68:71], v[156:159], v[210:213], v[68:71]
	v_mfma_f32_16x16x32_bf16 v[122:125], v[160:163], v[176:179], v[122:125]
	v_mfma_f32_16x16x32_bf16 v[114:117], v[168:171], v[176:179], v[114:117]
	v_mfma_f32_16x16x32_bf16 v[106:109], v[160:163], v[190:193], v[106:109]
	v_mfma_f32_16x16x32_bf16 v[98:101], v[168:171], v[190:193], v[98:101]
	v_mfma_f32_16x16x32_bf16 v[88:91], v[160:163], v[198:201], v[88:91]
	v_mfma_f32_16x16x32_bf16 v[80:83], v[168:171], v[198:201], v[80:83]
	v_mfma_f32_16x16x32_bf16 v[72:75], v[160:163], v[206:209], v[72:75]
	v_mfma_f32_16x16x32_bf16 v[64:67], v[168:171], v[206:209], v[64:67]
	v_mfma_f32_16x16x32_bf16 v[122:125], v[164:167], v[180:183], v[122:125]
	v_mfma_f32_16x16x32_bf16 v[114:117], v[172:175], v[180:183], v[114:117]
	v_mfma_f32_16x16x32_bf16 v[106:109], v[164:167], v[194:197], v[106:109]
	v_mfma_f32_16x16x32_bf16 v[98:101], v[172:175], v[194:197], v[98:101]
	v_mfma_f32_16x16x32_bf16 v[88:91], v[164:167], v[202:205], v[88:91]
	v_mfma_f32_16x16x32_bf16 v[80:83], v[172:175], v[202:205], v[80:83]
	v_mfma_f32_16x16x32_bf16 v[72:75], v[164:167], v[210:213], v[72:75]
	v_mfma_f32_16x16x32_bf16 v[64:67], v[172:175], v[210:213], v[64:67]
	s_setprio 0
	s_barrier
	s_add_i32 s18, s35, s47
	s_mov_b32 m0, s18
	ds_read_b128 v[176:179], v155 offset:16384
	ds_read_b128 v[180:183], v155 offset:17408
	ds_read_b128 v[190:193], v155 offset:18432
	ds_read_b128 v[194:197], v155 offset:19456
	ds_read_b128 v[198:201], v155 offset:20480
	ds_read_b128 v[202:205], v155 offset:21504
	ds_read_b128 v[206:209], v155 offset:22528
	ds_read_b128 v[210:213], v155 offset:23552
	global_load_lds_dwordx4 v134, s[44:45]
	s_add_i32 m0, s18, 0x2000
	s_add_u32 s18, s44, 0x40000
	s_addc_u32 s19, s45, 0
	s_add_i32 s35, s49, s47
	global_load_lds_dwordx4 v130, s[44:45]
	s_mov_b32 m0, s35
	s_nop 0
	global_load_lds_dwordx4 v134, s[18:19]
	s_add_i32 m0, s35, 0x2000
	s_nop 0
	global_load_lds_dwordx4 v130, s[18:19]
	s_mov_b32 m0, s65
	s_nop 0
	global_load_lds_dwordx4 v136, s[42:43]
	s_mov_b32 m0, s72
	s_nop 0
	global_load_lds_dwordx4 v132, s[42:43]
	s_waitcnt vmcnt(8)
	s_waitcnt lgkmcnt(0)
	s_barrier
	s_setprio 1
	s_waitcnt lgkmcnt(0)
	v_mfma_f32_16x16x32_bf16 v[60:63], v[138:141], v[176:179], v[60:63]
	v_mfma_f32_16x16x32_bf16 v[52:55], v[146:149], v[176:179], v[52:55]
	v_mfma_f32_16x16x32_bf16 v[44:47], v[138:141], v[190:193], v[44:47]
	v_mfma_f32_16x16x32_bf16 v[36:39], v[146:149], v[190:193], v[36:39]
	v_mfma_f32_16x16x32_bf16 v[28:31], v[138:141], v[198:201], v[28:31]
	v_mfma_f32_16x16x32_bf16 v[20:23], v[146:149], v[198:201], v[20:23]
	v_mfma_f32_16x16x32_bf16 v[12:15], v[138:141], v[206:209], v[12:15]
	v_mfma_f32_16x16x32_bf16 v[4:7], v[146:149], v[206:209], v[4:7]
	v_mfma_f32_16x16x32_bf16 v[60:63], v[142:145], v[180:183], v[60:63]
	v_mfma_f32_16x16x32_bf16 v[52:55], v[156:159], v[180:183], v[52:55]
	v_mfma_f32_16x16x32_bf16 v[44:47], v[142:145], v[194:197], v[44:47]
	v_mfma_f32_16x16x32_bf16 v[36:39], v[156:159], v[194:197], v[36:39]
	v_mfma_f32_16x16x32_bf16 v[28:31], v[142:145], v[202:205], v[28:31]
	v_mfma_f32_16x16x32_bf16 v[20:23], v[156:159], v[202:205], v[20:23]
	v_mfma_f32_16x16x32_bf16 v[12:15], v[142:145], v[210:213], v[12:15]
	v_mfma_f32_16x16x32_bf16 v[4:7], v[156:159], v[210:213], v[4:7]
	v_mfma_f32_16x16x32_bf16 v[56:59], v[160:163], v[176:179], v[56:59]
	v_mfma_f32_16x16x32_bf16 v[48:51], v[168:171], v[176:179], v[48:51]
	v_mfma_f32_16x16x32_bf16 v[40:43], v[160:163], v[190:193], v[40:43]
	v_mfma_f32_16x16x32_bf16 v[32:35], v[168:171], v[190:193], v[32:35]
	v_mfma_f32_16x16x32_bf16 v[24:27], v[160:163], v[198:201], v[24:27]
	v_mfma_f32_16x16x32_bf16 v[16:19], v[168:171], v[198:201], v[16:19]
	v_mfma_f32_16x16x32_bf16 v[8:11], v[160:163], v[206:209], v[8:11]
	v_mfma_f32_16x16x32_bf16 v[0:3], v[168:171], v[206:209], v[0:3]
	v_mfma_f32_16x16x32_bf16 v[56:59], v[164:167], v[180:183], v[56:59]
	v_mfma_f32_16x16x32_bf16 v[48:51], v[172:175], v[180:183], v[48:51]
	v_mfma_f32_16x16x32_bf16 v[40:43], v[164:167], v[194:197], v[40:43]
	v_mfma_f32_16x16x32_bf16 v[32:35], v[172:175], v[194:197], v[32:35]
	v_mfma_f32_16x16x32_bf16 v[24:27], v[164:167], v[202:205], v[24:27]
	v_mfma_f32_16x16x32_bf16 v[16:19], v[172:175], v[202:205], v[16:19]
	v_mfma_f32_16x16x32_bf16 v[8:11], v[164:167], v[210:213], v[8:11]
	v_mfma_f32_16x16x32_bf16 v[0:3], v[172:175], v[210:213], v[0:3]
	s_setprio 0
	s_barrier
	s_add_i32 s35, 0, 0x18000
	v_add_u32_e32 v96, s35, v151
	s_add_i32 s44, 0, 0x1c000
	ds_read_b128 v[138:141], v96
	ds_read_b128 v[142:145], v96 offset:1024
	ds_read_b128 v[146:149], v96 offset:2048
	ds_read_b128 v[156:159], v96 offset:3072
	v_add_u32_e32 v96, s44, v151
	ds_read_b128 v[160:163], v96
	ds_read_b128 v[164:167], v96 offset:1024
	ds_read_b128 v[168:171], v96 offset:2048
	ds_read_b128 v[172:175], v96 offset:3072
	s_add_u32 s18, s42, 0x40000
	s_addc_u32 s19, s43, 0
	s_mov_b32 m0, s73
	ds_read_b128 v[176:179], v155 offset:32768
	ds_read_b128 v[180:183], v155 offset:33792
	ds_read_b128 v[190:193], v155 offset:34816
	ds_read_b128 v[194:197], v155 offset:35840
	ds_read_b128 v[198:201], v155 offset:36864
	ds_read_b128 v[202:205], v155 offset:37888
	ds_read_b128 v[206:209], v155 offset:38912
	ds_read_b128 v[210:213], v155 offset:39936
	global_load_lds_dwordx4 v136, s[18:19]
	s_mov_b32 m0, s74
	s_nop 0
	global_load_lds_dwordx4 v132, s[18:19]
	s_waitcnt vmcnt(8)
	s_waitcnt lgkmcnt(0)
	s_barrier
	s_setprio 1
	s_waitcnt lgkmcnt(0)
	v_mfma_f32_16x16x32_bf16 v[126:129], v[138:141], v[176:179], v[126:129]
	v_mfma_f32_16x16x32_bf16 v[118:121], v[146:149], v[176:179], v[118:121]
	v_mfma_f32_16x16x32_bf16 v[110:113], v[138:141], v[190:193], v[110:113]
	v_mfma_f32_16x16x32_bf16 v[102:105], v[146:149], v[190:193], v[102:105]
	v_mfma_f32_16x16x32_bf16 v[92:95], v[138:141], v[198:201], v[92:95]
	v_mfma_f32_16x16x32_bf16 v[84:87], v[146:149], v[198:201], v[84:87]
	v_mfma_f32_16x16x32_bf16 v[76:79], v[138:141], v[206:209], v[76:79]
	v_mfma_f32_16x16x32_bf16 v[68:71], v[146:149], v[206:209], v[68:71]
	v_mfma_f32_16x16x32_bf16 v[126:129], v[142:145], v[180:183], v[126:129]
	v_mfma_f32_16x16x32_bf16 v[118:121], v[156:159], v[180:183], v[118:121]
	v_mfma_f32_16x16x32_bf16 v[110:113], v[142:145], v[194:197], v[110:113]
	v_mfma_f32_16x16x32_bf16 v[102:105], v[156:159], v[194:197], v[102:105]
	v_mfma_f32_16x16x32_bf16 v[92:95], v[142:145], v[202:205], v[92:95]
	v_mfma_f32_16x16x32_bf16 v[84:87], v[156:159], v[202:205], v[84:87]
	v_mfma_f32_16x16x32_bf16 v[76:79], v[142:145], v[210:213], v[76:79]
	v_mfma_f32_16x16x32_bf16 v[68:71], v[156:159], v[210:213], v[68:71]
	v_mfma_f32_16x16x32_bf16 v[122:125], v[160:163], v[176:179], v[122:125]
	v_mfma_f32_16x16x32_bf16 v[114:117], v[168:171], v[176:179], v[114:117]
	v_mfma_f32_16x16x32_bf16 v[106:109], v[160:163], v[190:193], v[106:109]
	v_mfma_f32_16x16x32_bf16 v[98:101], v[168:171], v[190:193], v[98:101]
	v_mfma_f32_16x16x32_bf16 v[88:91], v[160:163], v[198:201], v[88:91]
	v_mfma_f32_16x16x32_bf16 v[80:83], v[168:171], v[198:201], v[80:83]
	v_mfma_f32_16x16x32_bf16 v[72:75], v[160:163], v[206:209], v[72:75]
	v_mfma_f32_16x16x32_bf16 v[64:67], v[168:171], v[206:209], v[64:67]
	v_mfma_f32_16x16x32_bf16 v[122:125], v[164:167], v[180:183], v[122:125]
	v_mfma_f32_16x16x32_bf16 v[114:117], v[172:175], v[180:183], v[114:117]
	v_mfma_f32_16x16x32_bf16 v[106:109], v[164:167], v[194:197], v[106:109]
	v_mfma_f32_16x16x32_bf16 v[98:101], v[172:175], v[194:197], v[98:101]
	v_mfma_f32_16x16x32_bf16 v[88:91], v[164:167], v[202:205], v[88:91]
	v_mfma_f32_16x16x32_bf16 v[80:83], v[172:175], v[202:205], v[80:83]
	v_mfma_f32_16x16x32_bf16 v[72:75], v[164:167], v[210:213], v[72:75]
	v_mfma_f32_16x16x32_bf16 v[64:67], v[172:175], v[210:213], v[64:67]
	s_setprio 0
	s_barrier
	s_add_i32 s18, s35, s47
	s_mov_b32 m0, s18
	ds_read_b128 v[176:179], v155 offset:49152
	ds_read_b128 v[180:183], v155 offset:50176
	ds_read_b128 v[190:193], v155 offset:51200
	ds_read_b128 v[194:197], v155 offset:52224
	ds_read_b128 v[198:201], v155 offset:53248
	ds_read_b128 v[202:205], v155 offset:54272
	ds_read_b128 v[206:209], v155 offset:55296
	ds_read_b128 v[210:213], v155 offset:56320
	global_load_lds_dwordx4 v134, s[68:69]
	s_add_i32 m0, s18, 0x2000
	s_add_u32 s18, s68, 0x40000
	s_addc_u32 s19, s69, 0
	s_add_i32 s35, s44, s47
	global_load_lds_dwordx4 v130, s[68:69]
	s_mov_b32 m0, s35
	s_nop 0
	global_load_lds_dwordx4 v134, s[18:19]
	s_add_i32 m0, s35, 0x2000
	s_nop 0
	global_load_lds_dwordx4 v130, s[18:19]
	s_mov_b32 m0, s77
	s_nop 0
	global_load_lds_dwordx4 v136, s[38:39]
	s_mov_b32 m0, s78
	s_nop 0
	global_load_lds_dwordx4 v132, s[38:39]
	s_waitcnt vmcnt(8)
	s_cmp_lg_u32 s85, 12
	s_cbranch_scc1 .Lswi_ssq_skip
	global_load_dwordx4 v[220:223], v[252:253], off
	global_load_dwordx4 v[224:227], v[252:253], off offset:1024
	global_load_dwordx4 v[228:231], v[252:253], off offset:2048
	global_load_dwordx4 v[232:235], v[252:253], off offset:3072
	global_load_dwordx4 v[236:239], v[184:185], off
	global_load_dwordx4 v[240:243], v[184:185], off offset:1024
	global_load_dwordx4 v[244:247], v[184:185], off offset:2048
	global_load_dwordx4 v[248:251], v[184:185], off offset:3072
